# K-loops: the s_setprio 0 / s_setprio 1 pair between the two 16-MFMA clusters of each MMA segment removed (priority stays raised for all 32 MFMAs)
# speedup vs baseline: 1.0047x; 1.0009x over previous
.LBB0_219:
	ds_read_b128 v[180:183], v173
	ds_read_b128 v[184:187], v173 offset:1024
	ds_read_b128 v[188:191], v173 offset:2048
	ds_read_b128 v[192:195], v173 offset:3072
	ds_read_b128 v[196:199], v174
	ds_read_b128 v[200:203], v174 offset:1024
	ds_read_b128 v[204:207], v174 offset:2048
	ds_read_b128 v[208:211], v174 offset:3072
	s_add_u32 s36, s34, 0xfffc0080
	s_addc_u32 s37, s35, -1
	s_cmp_eq_u32 s59, 12
	s_cselect_b32 s39, s1, s37
	s_cselect_b32 s38, s9, s36
	s_cselect_b32 s37, s12, s58
	s_cselect_b32 s36, s25, s27
	v_lshl_add_u64 v[156:157], s[34:35], 0, v[142:143]
	s_add_i32 m0, s45, 0xc000
	ds_read_b128 v[212:215], v175
	ds_read_b128 v[216:219], v175 offset:1024
	ds_read_b128 v[220:223], v175 offset:2048
	ds_read_b128 v[224:227], v175 offset:3072
	ds_read_b128 v[228:231], v175 offset:4096
	ds_read_b128 v[232:235], v175 offset:5120
	ds_read_b128 v[236:239], v175 offset:6144
	ds_read_b128 v[240:243], v175 offset:7168
	global_load_lds_dwordx4 v[156:157], off
	v_lshl_add_u64 v[156:157], s[34:35], 0, v[140:141]
	s_add_i32 m0, s45, 0xe000
	s_nop 0
	global_load_lds_dwordx4 v[156:157], off
	s_waitcnt vmcnt(8)
	s_waitcnt lgkmcnt(0)
	s_barrier
	s_setprio 1
	s_waitcnt lgkmcnt(0)
	v_mfma_f32_16x16x32_bf16 v[126:129], v[180:183], v[212:215], v[126:129]
	v_mfma_f32_16x16x32_bf16 v[122:125], v[188:191], v[212:215], v[122:125]
	v_mfma_f32_16x16x32_bf16 v[110:113], v[180:183], v[220:223], v[110:113]
	v_mfma_f32_16x16x32_bf16 v[106:109], v[188:191], v[220:223], v[106:109]
	v_mfma_f32_16x16x32_bf16 v[94:97], v[180:183], v[228:231], v[94:97]
	v_mfma_f32_16x16x32_bf16 v[90:93], v[188:191], v[228:231], v[90:93]
	v_mfma_f32_16x16x32_bf16 v[78:81], v[180:183], v[236:239], v[78:81]
	v_mfma_f32_16x16x32_bf16 v[74:77], v[188:191], v[236:239], v[74:77]
	v_mfma_f32_16x16x32_bf16 v[126:129], v[184:187], v[216:219], v[126:129]
	v_mfma_f32_16x16x32_bf16 v[122:125], v[192:195], v[216:219], v[122:125]
	v_mfma_f32_16x16x32_bf16 v[110:113], v[184:187], v[224:227], v[110:113]
	v_mfma_f32_16x16x32_bf16 v[106:109], v[192:195], v[224:227], v[106:109]
	v_mfma_f32_16x16x32_bf16 v[94:97], v[184:187], v[232:235], v[94:97]
	v_mfma_f32_16x16x32_bf16 v[90:93], v[192:195], v[232:235], v[90:93]
	v_mfma_f32_16x16x32_bf16 v[78:81], v[184:187], v[240:243], v[78:81]
	v_mfma_f32_16x16x32_bf16 v[74:77], v[192:195], v[240:243], v[74:77]
	v_mfma_f32_16x16x32_bf16 v[118:121], v[196:199], v[212:215], v[118:121]
	v_mfma_f32_16x16x32_bf16 v[114:117], v[204:207], v[212:215], v[114:117]
	v_mfma_f32_16x16x32_bf16 v[102:105], v[196:199], v[220:223], v[102:105]
	v_mfma_f32_16x16x32_bf16 v[98:101], v[204:207], v[220:223], v[98:101]
	v_mfma_f32_16x16x32_bf16 v[86:89], v[196:199], v[228:231], v[86:89]
	v_mfma_f32_16x16x32_bf16 v[82:85], v[204:207], v[228:231], v[82:85]
	v_mfma_f32_16x16x32_bf16 v[70:73], v[196:199], v[236:239], v[70:73]
	v_mfma_f32_16x16x32_bf16 v[66:69], v[204:207], v[236:239], v[66:69]
	v_mfma_f32_16x16x32_bf16 v[118:121], v[200:203], v[216:219], v[118:121]
	v_mfma_f32_16x16x32_bf16 v[114:117], v[208:211], v[216:219], v[114:117]
	v_mfma_f32_16x16x32_bf16 v[102:105], v[200:203], v[224:227], v[102:105]
	v_mfma_f32_16x16x32_bf16 v[98:101], v[208:211], v[224:227], v[98:101]
	v_mfma_f32_16x16x32_bf16 v[86:89], v[200:203], v[232:235], v[86:89]
	v_mfma_f32_16x16x32_bf16 v[82:85], v[208:211], v[232:235], v[82:85]
	v_mfma_f32_16x16x32_bf16 v[70:73], v[200:203], v[240:243], v[70:73]
	v_mfma_f32_16x16x32_bf16 v[66:69], v[208:211], v[240:243], v[66:69]
	s_setprio 0
	s_barrier
	s_add_i32 s60, s55, s44
	v_lshl_add_u64 v[156:157], s[36:37], 0, v[132:133]
	s_mov_b32 m0, s60
	ds_read_b128 v[212:215], v175 offset:16384
	ds_read_b128 v[216:219], v175 offset:17408
	ds_read_b128 v[220:223], v175 offset:18432
	ds_read_b128 v[224:227], v175 offset:19456
	ds_read_b128 v[228:231], v175 offset:20480
	ds_read_b128 v[232:235], v175 offset:21504
	ds_read_b128 v[236:239], v175 offset:22528
	ds_read_b128 v[240:243], v175 offset:23552
	global_load_lds_dwordx4 v[156:157], off
	s_add_i32 m0, s60, 0x2000
	s_add_u32 s60, s36, 0x40000
	v_lshl_add_u64 v[160:161], s[36:37], 0, v[136:137]
	s_addc_u32 s61, s37, 0
	s_add_i32 s62, s56, s44
	global_load_lds_dwordx4 v[160:161], off
	v_lshl_add_u64 v[176:177], s[60:61], 0, v[132:133]
	s_mov_b32 m0, s62
	v_lshl_add_u64 v[244:245], s[38:39], 0, v[134:135]
	global_load_lds_dwordx4 v[176:177], off
	v_lshl_add_u64 v[176:177], s[60:61], 0, v[136:137]
	s_add_i32 m0, s62, 0x2000
	s_nop 0
	global_load_lds_dwordx4 v[176:177], off
	v_lshl_add_u64 v[176:177], s[38:39], 0, v[130:131]
	s_mov_b32 m0, s45
	s_nop 0
	global_load_lds_dwordx4 v[176:177], off
	s_mov_b32 m0, s46
	s_nop 0
	global_load_lds_dwordx4 v[244:245], off
	s_waitcnt vmcnt(8)
	s_waitcnt lgkmcnt(0)
	s_barrier
	s_setprio 1
	s_waitcnt lgkmcnt(0)
	v_mfma_f32_16x16x32_bf16 v[62:65], v[180:183], v[212:215], v[62:65]
	v_mfma_f32_16x16x32_bf16 v[58:61], v[188:191], v[212:215], v[58:61]
	v_mfma_f32_16x16x32_bf16 v[46:49], v[180:183], v[220:223], v[46:49]
	v_mfma_f32_16x16x32_bf16 v[42:45], v[188:191], v[220:223], v[42:45]
	v_mfma_f32_16x16x32_bf16 v[30:33], v[180:183], v[228:231], v[30:33]
	v_mfma_f32_16x16x32_bf16 v[26:29], v[188:191], v[228:231], v[26:29]
	v_mfma_f32_16x16x32_bf16 v[14:17], v[180:183], v[236:239], v[14:17]
	v_mfma_f32_16x16x32_bf16 v[10:13], v[188:191], v[236:239], v[10:13]
	v_mfma_f32_16x16x32_bf16 v[62:65], v[184:187], v[216:219], v[62:65]
	v_mfma_f32_16x16x32_bf16 v[58:61], v[192:195], v[216:219], v[58:61]
	v_mfma_f32_16x16x32_bf16 v[46:49], v[184:187], v[224:227], v[46:49]
	v_mfma_f32_16x16x32_bf16 v[42:45], v[192:195], v[224:227], v[42:45]
	v_mfma_f32_16x16x32_bf16 v[30:33], v[184:187], v[232:235], v[30:33]
	v_mfma_f32_16x16x32_bf16 v[26:29], v[192:195], v[232:235], v[26:29]
	v_mfma_f32_16x16x32_bf16 v[14:17], v[184:187], v[240:243], v[14:17]
	v_mfma_f32_16x16x32_bf16 v[10:13], v[192:195], v[240:243], v[10:13]
	v_mfma_f32_16x16x32_bf16 v[54:57], v[196:199], v[212:215], v[54:57]
	v_mfma_f32_16x16x32_bf16 v[50:53], v[204:207], v[212:215], v[50:53]
	v_mfma_f32_16x16x32_bf16 v[38:41], v[196:199], v[220:223], v[38:41]
	v_mfma_f32_16x16x32_bf16 v[34:37], v[204:207], v[220:223], v[34:37]
	v_mfma_f32_16x16x32_bf16 v[22:25], v[196:199], v[228:231], v[22:25]
	v_mfma_f32_16x16x32_bf16 v[18:21], v[204:207], v[228:231], v[18:21]
	v_mfma_f32_16x16x32_bf16 v[6:9], v[196:199], v[236:239], v[6:9]
	v_mfma_f32_16x16x32_bf16 v[2:5], v[204:207], v[236:239], v[2:5]
	v_mfma_f32_16x16x32_bf16 v[54:57], v[200:203], v[216:219], v[54:57]
	v_mfma_f32_16x16x32_bf16 v[50:53], v[208:211], v[216:219], v[50:53]
	v_mfma_f32_16x16x32_bf16 v[38:41], v[200:203], v[224:227], v[38:41]
	v_mfma_f32_16x16x32_bf16 v[34:37], v[208:211], v[224:227], v[34:37]
	v_mfma_f32_16x16x32_bf16 v[22:25], v[200:203], v[232:235], v[22:25]
	v_mfma_f32_16x16x32_bf16 v[18:21], v[208:211], v[232:235], v[18:21]
	v_mfma_f32_16x16x32_bf16 v[6:9], v[200:203], v[240:243], v[6:9]
	v_mfma_f32_16x16x32_bf16 v[2:5], v[208:211], v[240:243], v[2:5]
	s_setprio 0
	s_barrier
	s_add_i32 s60, 0, 0x18000
	v_add_u32_e32 v149, s60, v171
	s_add_i32 s61, 0, 0x1c000
	ds_read_b128 v[180:183], v149
	ds_read_b128 v[184:187], v149 offset:1024
	ds_read_b128 v[188:191], v149 offset:2048
	ds_read_b128 v[192:195], v149 offset:3072
	v_add_u32_e32 v149, s61, v171
	ds_read_b128 v[196:199], v149
	ds_read_b128 v[200:203], v149 offset:1024
	ds_read_b128 v[204:207], v149 offset:2048
	ds_read_b128 v[208:211], v149 offset:3072
	s_add_u32 s38, s38, 0x40000
	s_addc_u32 s39, s39, 0
	s_mov_b32 m0, s47
	v_lshl_add_u64 v[246:247], s[38:39], 0, v[130:131]
	ds_read_b128 v[212:215], v175 offset:32768
	ds_read_b128 v[216:219], v175 offset:33792
	ds_read_b128 v[220:223], v175 offset:34816
	ds_read_b128 v[224:227], v175 offset:35840
	ds_read_b128 v[228:231], v175 offset:36864
	ds_read_b128 v[232:235], v175 offset:37888
	ds_read_b128 v[236:239], v175 offset:38912
	ds_read_b128 v[240:243], v175 offset:39936
	global_load_lds_dwordx4 v[246:247], off
	v_lshl_add_u64 v[246:247], s[38:39], 0, v[134:135]
	s_mov_b32 m0, s48
	s_nop 0
	global_load_lds_dwordx4 v[246:247], off
	s_waitcnt vmcnt(8)
	s_waitcnt lgkmcnt(0)
	s_barrier
	s_setprio 1
	s_waitcnt lgkmcnt(0)
	v_mfma_f32_16x16x32_bf16 v[126:129], v[180:183], v[212:215], v[126:129]
	v_mfma_f32_16x16x32_bf16 v[122:125], v[188:191], v[212:215], v[122:125]
	v_mfma_f32_16x16x32_bf16 v[110:113], v[180:183], v[220:223], v[110:113]
	v_mfma_f32_16x16x32_bf16 v[106:109], v[188:191], v[220:223], v[106:109]
	v_mfma_f32_16x16x32_bf16 v[94:97], v[180:183], v[228:231], v[94:97]
	v_mfma_f32_16x16x32_bf16 v[90:93], v[188:191], v[228:231], v[90:93]
	v_mfma_f32_16x16x32_bf16 v[78:81], v[180:183], v[236:239], v[78:81]
	v_mfma_f32_16x16x32_bf16 v[74:77], v[188:191], v[236:239], v[74:77]
	v_mfma_f32_16x16x32_bf16 v[126:129], v[184:187], v[216:219], v[126:129]
	v_mfma_f32_16x16x32_bf16 v[122:125], v[192:195], v[216:219], v[122:125]
	v_mfma_f32_16x16x32_bf16 v[110:113], v[184:187], v[224:227], v[110:113]
	v_mfma_f32_16x16x32_bf16 v[106:109], v[192:195], v[224:227], v[106:109]
	v_mfma_f32_16x16x32_bf16 v[94:97], v[184:187], v[232:235], v[94:97]
	v_mfma_f32_16x16x32_bf16 v[90:93], v[192:195], v[232:235], v[90:93]
	v_mfma_f32_16x16x32_bf16 v[78:81], v[184:187], v[240:243], v[78:81]
	v_mfma_f32_16x16x32_bf16 v[74:77], v[192:195], v[240:243], v[74:77]
	v_mfma_f32_16x16x32_bf16 v[118:121], v[196:199], v[212:215], v[118:121]
	v_mfma_f32_16x16x32_bf16 v[114:117], v[204:207], v[212:215], v[114:117]
	v_mfma_f32_16x16x32_bf16 v[102:105], v[196:199], v[220:223], v[102:105]
	v_mfma_f32_16x16x32_bf16 v[98:101], v[204:207], v[220:223], v[98:101]
	v_mfma_f32_16x16x32_bf16 v[86:89], v[196:199], v[228:231], v[86:89]
	v_mfma_f32_16x16x32_bf16 v[82:85], v[204:207], v[228:231], v[82:85]
	v_mfma_f32_16x16x32_bf16 v[70:73], v[196:199], v[236:239], v[70:73]
	v_mfma_f32_16x16x32_bf16 v[66:69], v[204:207], v[236:239], v[66:69]
	v_mfma_f32_16x16x32_bf16 v[118:121], v[200:203], v[216:219], v[118:121]
	v_mfma_f32_16x16x32_bf16 v[114:117], v[208:211], v[216:219], v[114:117]
	v_mfma_f32_16x16x32_bf16 v[102:105], v[200:203], v[224:227], v[102:105]
	v_mfma_f32_16x16x32_bf16 v[98:101], v[208:211], v[224:227], v[98:101]
	v_mfma_f32_16x16x32_bf16 v[86:89], v[200:203], v[232:235], v[86:89]
	v_mfma_f32_16x16x32_bf16 v[82:85], v[208:211], v[232:235], v[82:85]
	v_mfma_f32_16x16x32_bf16 v[70:73], v[200:203], v[240:243], v[70:73]
	v_mfma_f32_16x16x32_bf16 v[66:69], v[208:211], v[240:243], v[66:69]
	s_setprio 0
	s_barrier
	s_add_i32 s38, s60, s44
	v_lshl_add_u64 v[156:157], v[156:157], 0, s[18:19]
	s_mov_b32 m0, s38
	ds_read_b128 v[212:215], v175 offset:49152
	ds_read_b128 v[216:219], v175 offset:50176
	ds_read_b128 v[220:223], v175 offset:51200
	ds_read_b128 v[224:227], v175 offset:52224
	ds_read_b128 v[228:231], v175 offset:53248
	ds_read_b128 v[232:235], v175 offset:54272
	ds_read_b128 v[236:239], v175 offset:55296
	ds_read_b128 v[240:243], v175 offset:56320
	global_load_lds_dwordx4 v[156:157], off
	s_add_i32 m0, s38, 0x2000
	s_add_u32 s36, s36, 0x40080
	v_lshl_add_u64 v[156:157], v[160:161], 0, s[18:19]
	s_addc_u32 s37, s37, 0
	s_add_i32 s38, s61, s44
	global_load_lds_dwordx4 v[156:157], off
	v_lshl_add_u64 v[156:157], s[36:37], 0, v[132:133]
	s_mov_b32 m0, s38
	s_nop 0
	global_load_lds_dwordx4 v[156:157], off
	v_lshl_add_u64 v[156:157], s[36:37], 0, v[136:137]
	s_add_i32 m0, s38, 0x2000
	s_nop 0
	global_load_lds_dwordx4 v[156:157], off
	v_lshl_add_u64 v[156:157], v[176:177], 0, s[18:19]
	s_mov_b32 m0, s51
	s_nop 0
	global_load_lds_dwordx4 v[156:157], off
	v_lshl_add_u64 v[156:157], v[244:245], 0, s[18:19]
	s_mov_b32 m0, s52
	s_nop 0
	global_load_lds_dwordx4 v[156:157], off
	s_waitcnt vmcnt(8)
	s_waitcnt lgkmcnt(0)
	s_barrier
	s_setprio 1
	s_waitcnt lgkmcnt(0)
	v_mfma_f32_16x16x32_bf16 v[62:65], v[180:183], v[212:215], v[62:65]
	v_mfma_f32_16x16x32_bf16 v[58:61], v[188:191], v[212:215], v[58:61]
	v_mfma_f32_16x16x32_bf16 v[46:49], v[180:183], v[220:223], v[46:49]
	v_mfma_f32_16x16x32_bf16 v[42:45], v[188:191], v[220:223], v[42:45]
	v_mfma_f32_16x16x32_bf16 v[30:33], v[180:183], v[228:231], v[30:33]
	v_mfma_f32_16x16x32_bf16 v[26:29], v[188:191], v[228:231], v[26:29]
	v_mfma_f32_16x16x32_bf16 v[14:17], v[180:183], v[236:239], v[14:17]
	v_mfma_f32_16x16x32_bf16 v[10:13], v[188:191], v[236:239], v[10:13]
	v_mfma_f32_16x16x32_bf16 v[62:65], v[184:187], v[216:219], v[62:65]
	v_mfma_f32_16x16x32_bf16 v[58:61], v[192:195], v[216:219], v[58:61]
	v_mfma_f32_16x16x32_bf16 v[46:49], v[184:187], v[224:227], v[46:49]
	v_mfma_f32_16x16x32_bf16 v[42:45], v[192:195], v[224:227], v[42:45]
	v_mfma_f32_16x16x32_bf16 v[30:33], v[184:187], v[232:235], v[30:33]
	v_mfma_f32_16x16x32_bf16 v[26:29], v[192:195], v[232:235], v[26:29]
	v_mfma_f32_16x16x32_bf16 v[14:17], v[184:187], v[240:243], v[14:17]
	v_mfma_f32_16x16x32_bf16 v[10:13], v[192:195], v[240:243], v[10:13]
	v_mfma_f32_16x16x32_bf16 v[54:57], v[196:199], v[212:215], v[54:57]
	v_mfma_f32_16x16x32_bf16 v[50:53], v[204:207], v[212:215], v[50:53]
	v_mfma_f32_16x16x32_bf16 v[38:41], v[196:199], v[220:223], v[38:41]
	v_mfma_f32_16x16x32_bf16 v[34:37], v[204:207], v[220:223], v[34:37]
	v_mfma_f32_16x16x32_bf16 v[22:25], v[196:199], v[228:231], v[22:25]
	v_mfma_f32_16x16x32_bf16 v[18:21], v[204:207], v[228:231], v[18:21]
	v_mfma_f32_16x16x32_bf16 v[6:9], v[196:199], v[236:239], v[6:9]
	v_mfma_f32_16x16x32_bf16 v[2:5], v[204:207], v[236:239], v[2:5]
	v_mfma_f32_16x16x32_bf16 v[54:57], v[200:203], v[216:219], v[54:57]
	v_mfma_f32_16x16x32_bf16 v[50:53], v[208:211], v[216:219], v[50:53]
	v_mfma_f32_16x16x32_bf16 v[38:41], v[200:203], v[224:227], v[38:41]
	v_mfma_f32_16x16x32_bf16 v[34:37], v[208:211], v[224:227], v[34:37]
	v_mfma_f32_16x16x32_bf16 v[22:25], v[200:203], v[232:235], v[22:25]
	v_mfma_f32_16x16x32_bf16 v[18:21], v[208:211], v[232:235], v[18:21]
	v_mfma_f32_16x16x32_bf16 v[6:9], v[200:203], v[240:243], v[6:9]
	v_mfma_f32_16x16x32_bf16 v[2:5], v[208:211], v[240:243], v[2:5]
	s_setprio 0
	s_barrier
	s_add_i32 s59, s59, 2
	s_add_u32 s27, s27, 0x100
	s_addc_u32 s58, s58, 0
	s_add_u32 s34, s34, 0x100
	s_addc_u32 s35, s35, 0
	s_cmp_gt_u32 s59, 13
	s_cbranch_scc0 .LBB0_219
	s_and_b64 vcc, exec, s[20:21]
	s_cbranch_vccz .LBB0_222
	s_barrier

.LBB0_681:
	v_add_u32_e32 v154, s62, v156
	ds_read_b128 v[130:133], v154
	ds_read_b128 v[150:153], v154 offset:1024
	ds_read_b128 v[160:163], v154 offset:2048
	ds_read_b128 v[164:167], v154 offset:3072
	v_add_u32_e32 v154, s63, v156
	ds_read_b128 v[168:171], v154
	ds_read_b128 v[172:175], v154 offset:1024
	ds_read_b128 v[180:183], v154 offset:2048
	ds_read_b128 v[184:187], v154 offset:3072
	s_add_u32 s42, s40, 0xfffc0080
	s_addc_u32 s43, s41, -1
	s_cmp_eq_u32 s68, 12
	s_cselect_b32 s45, s31, s43
	s_cselect_b32 s44, s39, s42
	s_cselect_b32 s43, s29, s67
	s_cselect_b32 s42, s65, s66
	v_lshl_add_u64 v[154:155], s[40:41], 0, v[144:145]
	s_add_i32 m0, s51, 0xc000
	ds_read_b128 v[188:191], v158
	ds_read_b128 v[192:195], v158 offset:1024
	ds_read_b128 v[196:199], v158 offset:2048
	ds_read_b128 v[200:203], v158 offset:3072
	ds_read_b128 v[204:207], v158 offset:4096
	ds_read_b128 v[208:211], v158 offset:5120
	ds_read_b128 v[212:215], v158 offset:6144
	ds_read_b128 v[216:219], v158 offset:7168
	global_load_lds_dwordx4 v[154:155], off
	v_lshl_add_u64 v[154:155], s[40:41], 0, v[142:143]
	s_add_i32 m0, s51, 0xe000
	s_nop 0
	global_load_lds_dwordx4 v[154:155], off
	s_waitcnt vmcnt(8)
	s_waitcnt lgkmcnt(0)
	s_barrier
	s_setprio 1
	s_waitcnt lgkmcnt(0)
	v_mfma_f32_16x16x32_bf16 v[114:117], v[130:133], v[188:191], v[114:117]
	v_mfma_f32_16x16x32_bf16 v[118:121], v[160:163], v[188:191], v[118:121]
	v_mfma_f32_16x16x32_bf16 v[98:101], v[130:133], v[196:199], v[98:101]
	v_mfma_f32_16x16x32_bf16 v[102:105], v[160:163], v[196:199], v[102:105]
	v_mfma_f32_16x16x32_bf16 v[82:85], v[130:133], v[204:207], v[82:85]
	v_mfma_f32_16x16x32_bf16 v[86:89], v[160:163], v[204:207], v[86:89]
	v_mfma_f32_16x16x32_bf16 v[66:69], v[130:133], v[212:215], v[66:69]
	v_mfma_f32_16x16x32_bf16 v[70:73], v[160:163], v[212:215], v[70:73]
	v_mfma_f32_16x16x32_bf16 v[114:117], v[150:153], v[192:195], v[114:117]
	v_mfma_f32_16x16x32_bf16 v[118:121], v[164:167], v[192:195], v[118:121]
	v_mfma_f32_16x16x32_bf16 v[98:101], v[150:153], v[200:203], v[98:101]
	v_mfma_f32_16x16x32_bf16 v[102:105], v[164:167], v[200:203], v[102:105]
	v_mfma_f32_16x16x32_bf16 v[82:85], v[150:153], v[208:211], v[82:85]
	v_mfma_f32_16x16x32_bf16 v[86:89], v[164:167], v[208:211], v[86:89]
	v_mfma_f32_16x16x32_bf16 v[66:69], v[150:153], v[216:219], v[66:69]
	v_mfma_f32_16x16x32_bf16 v[70:73], v[164:167], v[216:219], v[70:73]
	v_mfma_f32_16x16x32_bf16 v[122:125], v[168:171], v[188:191], v[122:125]
	v_mfma_f32_16x16x32_bf16 v[126:129], v[180:183], v[188:191], v[126:129]
	v_mfma_f32_16x16x32_bf16 v[106:109], v[168:171], v[196:199], v[106:109]
	v_mfma_f32_16x16x32_bf16 v[110:113], v[180:183], v[196:199], v[110:113]
	v_mfma_f32_16x16x32_bf16 v[90:93], v[168:171], v[204:207], v[90:93]
	v_mfma_f32_16x16x32_bf16 v[94:97], v[180:183], v[204:207], v[94:97]
	v_mfma_f32_16x16x32_bf16 v[74:77], v[168:171], v[212:215], v[74:77]
	v_mfma_f32_16x16x32_bf16 v[78:81], v[180:183], v[212:215], v[78:81]
	v_mfma_f32_16x16x32_bf16 v[122:125], v[172:175], v[192:195], v[122:125]
	v_mfma_f32_16x16x32_bf16 v[126:129], v[184:187], v[192:195], v[126:129]
	v_mfma_f32_16x16x32_bf16 v[106:109], v[172:175], v[200:203], v[106:109]
	v_mfma_f32_16x16x32_bf16 v[110:113], v[184:187], v[200:203], v[110:113]
	v_mfma_f32_16x16x32_bf16 v[90:93], v[172:175], v[208:211], v[90:93]
	v_mfma_f32_16x16x32_bf16 v[94:97], v[184:187], v[208:211], v[94:97]
	v_mfma_f32_16x16x32_bf16 v[74:77], v[172:175], v[216:219], v[74:77]
	v_mfma_f32_16x16x32_bf16 v[78:81], v[184:187], v[216:219], v[78:81]
	s_setprio 0
	s_barrier
	s_add_i32 s69, s62, s50
	v_lshl_add_u64 v[154:155], s[42:43], 0, v[136:137]
	s_mov_b32 m0, s69
	ds_read_b128 v[188:191], v158 offset:16384
	ds_read_b128 v[192:195], v158 offset:17408
	ds_read_b128 v[196:199], v158 offset:18432
	ds_read_b128 v[200:203], v158 offset:19456
	ds_read_b128 v[204:207], v158 offset:20480
	ds_read_b128 v[208:211], v158 offset:21504
	ds_read_b128 v[212:215], v158 offset:22528
	ds_read_b128 v[216:219], v158 offset:23552
	global_load_lds_dwordx4 v[154:155], off
	s_add_i32 m0, s69, 0x2000
	s_add_u32 s70, s42, 0x40000
	v_lshl_add_u64 v[176:177], s[42:43], 0, v[140:141]
	s_addc_u32 s71, s43, 0
	s_add_i32 s69, s63, s50
	global_load_lds_dwordx4 v[176:177], off
	v_lshl_add_u64 v[220:221], s[70:71], 0, v[136:137]
	s_mov_b32 m0, s69
	v_lshl_add_u64 v[222:223], s[44:45], 0, v[138:139]
	global_load_lds_dwordx4 v[220:221], off
	v_lshl_add_u64 v[220:221], s[70:71], 0, v[140:141]
	s_add_i32 m0, s69, 0x2000
	s_nop 0
	global_load_lds_dwordx4 v[220:221], off
	v_lshl_add_u64 v[220:221], s[44:45], 0, v[134:135]
	s_mov_b32 m0, s51
	s_nop 0
	global_load_lds_dwordx4 v[220:221], off
	s_mov_b32 m0, s52
	s_nop 0
	global_load_lds_dwordx4 v[222:223], off
	s_waitcnt vmcnt(8)
	s_waitcnt lgkmcnt(0)
	s_barrier
	s_setprio 1
	s_waitcnt lgkmcnt(0)
	v_mfma_f32_16x16x32_bf16 v[50:53], v[130:133], v[188:191], v[50:53]
	v_mfma_f32_16x16x32_bf16 v[54:57], v[160:163], v[188:191], v[54:57]
	v_mfma_f32_16x16x32_bf16 v[26:29], v[130:133], v[196:199], v[26:29]
	v_mfma_f32_16x16x32_bf16 v[30:33], v[160:163], v[196:199], v[30:33]
	v_mfma_f32_16x16x32_bf16 v[18:21], v[130:133], v[204:207], v[18:21]
	v_mfma_f32_16x16x32_bf16 v[22:25], v[160:163], v[204:207], v[22:25]
	v_mfma_f32_16x16x32_bf16 v[2:5], v[130:133], v[212:215], v[2:5]
	v_mfma_f32_16x16x32_bf16 v[6:9], v[160:163], v[212:215], v[6:9]
	v_mfma_f32_16x16x32_bf16 v[50:53], v[150:153], v[192:195], v[50:53]
	v_mfma_f32_16x16x32_bf16 v[54:57], v[164:167], v[192:195], v[54:57]
	v_mfma_f32_16x16x32_bf16 v[26:29], v[150:153], v[200:203], v[26:29]
	v_mfma_f32_16x16x32_bf16 v[30:33], v[164:167], v[200:203], v[30:33]
	v_mfma_f32_16x16x32_bf16 v[18:21], v[150:153], v[208:211], v[18:21]
	v_mfma_f32_16x16x32_bf16 v[22:25], v[164:167], v[208:211], v[22:25]
	v_mfma_f32_16x16x32_bf16 v[2:5], v[150:153], v[216:219], v[2:5]
	v_mfma_f32_16x16x32_bf16 v[6:9], v[164:167], v[216:219], v[6:9]
	v_mfma_f32_16x16x32_bf16 v[58:61], v[168:171], v[188:191], v[58:61]
	v_mfma_f32_16x16x32_bf16 v[62:65], v[180:183], v[188:191], v[62:65]
	v_mfma_f32_16x16x32_bf16 v[42:45], v[168:171], v[196:199], v[42:45]
	v_mfma_f32_16x16x32_bf16 v[46:49], v[180:183], v[196:199], v[46:49]
	v_mfma_f32_16x16x32_bf16 v[34:37], v[168:171], v[204:207], v[34:37]
	v_mfma_f32_16x16x32_bf16 v[38:41], v[180:183], v[204:207], v[38:41]
	v_mfma_f32_16x16x32_bf16 v[10:13], v[168:171], v[212:215], v[10:13]
	v_mfma_f32_16x16x32_bf16 v[14:17], v[180:183], v[212:215], v[14:17]
	v_mfma_f32_16x16x32_bf16 v[58:61], v[172:175], v[192:195], v[58:61]
	v_mfma_f32_16x16x32_bf16 v[62:65], v[184:187], v[192:195], v[62:65]
	v_mfma_f32_16x16x32_bf16 v[42:45], v[172:175], v[200:203], v[42:45]
	v_mfma_f32_16x16x32_bf16 v[46:49], v[184:187], v[200:203], v[46:49]
	v_mfma_f32_16x16x32_bf16 v[34:37], v[172:175], v[208:211], v[34:37]
	v_mfma_f32_16x16x32_bf16 v[38:41], v[184:187], v[208:211], v[38:41]
	v_mfma_f32_16x16x32_bf16 v[10:13], v[172:175], v[216:219], v[10:13]
	v_mfma_f32_16x16x32_bf16 v[14:17], v[184:187], v[216:219], v[14:17]
	s_setprio 0
	s_barrier
	s_add_i32 s69, 0, 0x18000
	s_add_i32 s70, 0, 0x1c000
	v_add_u32_e32 v164, s69, v156
	v_add_u32_e32 v179, s70, v156
	ds_read_b128 v[130:133], v164
	ds_read_b128 v[150:153], v164 offset:1024
	ds_read_b128 v[160:163], v164 offset:2048
	ds_read_b128 v[164:167], v164 offset:3072
	ds_read_b128 v[168:171], v179
	ds_read_b128 v[172:175], v179 offset:1024
	ds_read_b128 v[180:183], v179 offset:2048
	ds_read_b128 v[184:187], v179 offset:3072
	s_add_u32 s44, s44, 0x40000
	s_addc_u32 s45, s45, 0
	s_mov_b32 m0, s53
	v_lshl_add_u64 v[224:225], s[44:45], 0, v[134:135]
	ds_read_b128 v[188:191], v158 offset:32768
	ds_read_b128 v[192:195], v158 offset:33792
	ds_read_b128 v[196:199], v158 offset:34816
	ds_read_b128 v[200:203], v158 offset:35840
	ds_read_b128 v[204:207], v158 offset:36864
	ds_read_b128 v[208:211], v158 offset:37888
	ds_read_b128 v[212:215], v158 offset:38912
	ds_read_b128 v[216:219], v158 offset:39936
	global_load_lds_dwordx4 v[224:225], off
	v_lshl_add_u64 v[224:225], s[44:45], 0, v[138:139]
	s_mov_b32 m0, s54
	s_nop 0
	global_load_lds_dwordx4 v[224:225], off
	s_waitcnt vmcnt(8)
	s_waitcnt lgkmcnt(0)
	s_barrier
	s_setprio 1
	s_waitcnt lgkmcnt(0)
	v_mfma_f32_16x16x32_bf16 v[114:117], v[130:133], v[188:191], v[114:117]
	v_mfma_f32_16x16x32_bf16 v[118:121], v[160:163], v[188:191], v[118:121]
	v_mfma_f32_16x16x32_bf16 v[98:101], v[130:133], v[196:199], v[98:101]
	v_mfma_f32_16x16x32_bf16 v[102:105], v[160:163], v[196:199], v[102:105]
	v_mfma_f32_16x16x32_bf16 v[82:85], v[130:133], v[204:207], v[82:85]
	v_mfma_f32_16x16x32_bf16 v[86:89], v[160:163], v[204:207], v[86:89]
	v_mfma_f32_16x16x32_bf16 v[66:69], v[130:133], v[212:215], v[66:69]
	v_mfma_f32_16x16x32_bf16 v[70:73], v[160:163], v[212:215], v[70:73]
	v_mfma_f32_16x16x32_bf16 v[114:117], v[150:153], v[192:195], v[114:117]
	v_mfma_f32_16x16x32_bf16 v[118:121], v[164:167], v[192:195], v[118:121]
	v_mfma_f32_16x16x32_bf16 v[98:101], v[150:153], v[200:203], v[98:101]
	v_mfma_f32_16x16x32_bf16 v[102:105], v[164:167], v[200:203], v[102:105]
	v_mfma_f32_16x16x32_bf16 v[82:85], v[150:153], v[208:211], v[82:85]
	v_mfma_f32_16x16x32_bf16 v[86:89], v[164:167], v[208:211], v[86:89]
	v_mfma_f32_16x16x32_bf16 v[66:69], v[150:153], v[216:219], v[66:69]
	v_mfma_f32_16x16x32_bf16 v[70:73], v[164:167], v[216:219], v[70:73]
	v_mfma_f32_16x16x32_bf16 v[122:125], v[168:171], v[188:191], v[122:125]
	v_mfma_f32_16x16x32_bf16 v[126:129], v[180:183], v[188:191], v[126:129]
	v_mfma_f32_16x16x32_bf16 v[106:109], v[168:171], v[196:199], v[106:109]
	v_mfma_f32_16x16x32_bf16 v[110:113], v[180:183], v[196:199], v[110:113]
	v_mfma_f32_16x16x32_bf16 v[90:93], v[168:171], v[204:207], v[90:93]
	v_mfma_f32_16x16x32_bf16 v[94:97], v[180:183], v[204:207], v[94:97]
	v_mfma_f32_16x16x32_bf16 v[74:77], v[168:171], v[212:215], v[74:77]
	v_mfma_f32_16x16x32_bf16 v[78:81], v[180:183], v[212:215], v[78:81]
	v_mfma_f32_16x16x32_bf16 v[122:125], v[172:175], v[192:195], v[122:125]
	v_mfma_f32_16x16x32_bf16 v[126:129], v[184:187], v[192:195], v[126:129]
	v_mfma_f32_16x16x32_bf16 v[106:109], v[172:175], v[200:203], v[106:109]
	v_mfma_f32_16x16x32_bf16 v[110:113], v[184:187], v[200:203], v[110:113]
	v_mfma_f32_16x16x32_bf16 v[90:93], v[172:175], v[208:211], v[90:93]
	v_mfma_f32_16x16x32_bf16 v[94:97], v[184:187], v[208:211], v[94:97]
	v_mfma_f32_16x16x32_bf16 v[74:77], v[172:175], v[216:219], v[74:77]
	v_mfma_f32_16x16x32_bf16 v[78:81], v[184:187], v[216:219], v[78:81]
	s_setprio 0
	s_barrier
	s_add_i32 s44, s69, s50
	v_lshl_add_u64 v[154:155], v[154:155], 0, s[22:23]
	s_mov_b32 m0, s44
	ds_read_b128 v[188:191], v158 offset:49152
	ds_read_b128 v[192:195], v158 offset:50176
	ds_read_b128 v[196:199], v158 offset:51200
	ds_read_b128 v[200:203], v158 offset:52224
	ds_read_b128 v[204:207], v158 offset:53248
	ds_read_b128 v[208:211], v158 offset:54272
	ds_read_b128 v[212:215], v158 offset:55296
	ds_read_b128 v[216:219], v158 offset:56320
	global_load_lds_dwordx4 v[154:155], off
	s_add_i32 m0, s44, 0x2000
	s_add_u32 s42, s42, 0x40080
	v_lshl_add_u64 v[154:155], v[176:177], 0, s[22:23]
	s_addc_u32 s43, s43, 0
	s_add_i32 s44, s70, s50
	global_load_lds_dwordx4 v[154:155], off
	v_lshl_add_u64 v[154:155], s[42:43], 0, v[136:137]
	s_mov_b32 m0, s44
	s_nop 0
	global_load_lds_dwordx4 v[154:155], off
	v_lshl_add_u64 v[154:155], s[42:43], 0, v[140:141]
	s_add_i32 m0, s44, 0x2000
	s_nop 0
	global_load_lds_dwordx4 v[154:155], off
	v_lshl_add_u64 v[154:155], v[220:221], 0, s[22:23]
	s_mov_b32 m0, s57
	s_nop 0
	global_load_lds_dwordx4 v[154:155], off
	v_lshl_add_u64 v[154:155], v[222:223], 0, s[22:23]
	s_mov_b32 m0, s58
	s_nop 0
	global_load_lds_dwordx4 v[154:155], off
	s_waitcnt vmcnt(8)
	s_waitcnt lgkmcnt(0)
	s_barrier
	s_setprio 1
	s_waitcnt lgkmcnt(0)
	v_mfma_f32_16x16x32_bf16 v[50:53], v[130:133], v[188:191], v[50:53]
	v_mfma_f32_16x16x32_bf16 v[54:57], v[160:163], v[188:191], v[54:57]
	v_mfma_f32_16x16x32_bf16 v[26:29], v[130:133], v[196:199], v[26:29]
	v_mfma_f32_16x16x32_bf16 v[30:33], v[160:163], v[196:199], v[30:33]
	v_mfma_f32_16x16x32_bf16 v[18:21], v[130:133], v[204:207], v[18:21]
	v_mfma_f32_16x16x32_bf16 v[22:25], v[160:163], v[204:207], v[22:25]
	v_mfma_f32_16x16x32_bf16 v[2:5], v[130:133], v[212:215], v[2:5]
	v_mfma_f32_16x16x32_bf16 v[6:9], v[160:163], v[212:215], v[6:9]
	v_mfma_f32_16x16x32_bf16 v[50:53], v[150:153], v[192:195], v[50:53]
	v_mfma_f32_16x16x32_bf16 v[54:57], v[164:167], v[192:195], v[54:57]
	v_mfma_f32_16x16x32_bf16 v[26:29], v[150:153], v[200:203], v[26:29]
	v_mfma_f32_16x16x32_bf16 v[30:33], v[164:167], v[200:203], v[30:33]
	v_mfma_f32_16x16x32_bf16 v[18:21], v[150:153], v[208:211], v[18:21]
	v_mfma_f32_16x16x32_bf16 v[22:25], v[164:167], v[208:211], v[22:25]
	v_mfma_f32_16x16x32_bf16 v[2:5], v[150:153], v[216:219], v[2:5]
	v_mfma_f32_16x16x32_bf16 v[6:9], v[164:167], v[216:219], v[6:9]
	v_mfma_f32_16x16x32_bf16 v[58:61], v[168:171], v[188:191], v[58:61]
	v_mfma_f32_16x16x32_bf16 v[62:65], v[180:183], v[188:191], v[62:65]
	v_mfma_f32_16x16x32_bf16 v[42:45], v[168:171], v[196:199], v[42:45]
	v_mfma_f32_16x16x32_bf16 v[46:49], v[180:183], v[196:199], v[46:49]
	v_mfma_f32_16x16x32_bf16 v[34:37], v[168:171], v[204:207], v[34:37]
	v_mfma_f32_16x16x32_bf16 v[38:41], v[180:183], v[204:207], v[38:41]
	v_mfma_f32_16x16x32_bf16 v[10:13], v[168:171], v[212:215], v[10:13]
	v_mfma_f32_16x16x32_bf16 v[14:17], v[180:183], v[212:215], v[14:17]
	v_mfma_f32_16x16x32_bf16 v[58:61], v[172:175], v[192:195], v[58:61]
	v_mfma_f32_16x16x32_bf16 v[62:65], v[184:187], v[192:195], v[62:65]
	v_mfma_f32_16x16x32_bf16 v[42:45], v[172:175], v[200:203], v[42:45]
	v_mfma_f32_16x16x32_bf16 v[46:49], v[184:187], v[200:203], v[46:49]
	v_mfma_f32_16x16x32_bf16 v[34:37], v[172:175], v[208:211], v[34:37]
	v_mfma_f32_16x16x32_bf16 v[38:41], v[184:187], v[208:211], v[38:41]
	v_mfma_f32_16x16x32_bf16 v[10:13], v[172:175], v[216:219], v[10:13]
	v_mfma_f32_16x16x32_bf16 v[14:17], v[184:187], v[216:219], v[14:17]
	s_setprio 0
	s_barrier
	s_add_i32 s68, s68, 2
	s_add_u32 s66, s66, 0x100
	s_addc_u32 s67, s67, 0
	s_add_u32 s40, s40, 0x100
	s_addc_u32 s41, s41, 0
	s_cmp_gt_u32 s68, 13
	s_cbranch_scc0 .LBB0_681
	s_and_b64 vcc, exec, s[24:25]
	s_cbranch_vccz .LBB0_684
	s_barrier

.LBB0_858:
	ds_read_b128 v[164:167], v173
	ds_read_b128 v[180:183], v173 offset:1024
	ds_read_b128 v[184:187], v173 offset:2048
	ds_read_b128 v[188:191], v173 offset:3072
	ds_read_b128 v[192:195], v174
	ds_read_b128 v[196:199], v174 offset:1024
	ds_read_b128 v[200:203], v174 offset:2048
	ds_read_b128 v[204:207], v174 offset:3072
	s_add_u32 s38, s36, 0xfffc0080
	s_addc_u32 s39, s37, -1
	s_cmp_eq_u32 s61, 12
	s_cselect_b32 s41, s25, s39
	s_cselect_b32 s40, s31, s38
	s_cselect_b32 s39, s23, s60
	s_cselect_b32 s38, s58, s59
	v_lshl_add_u64 v[176:177], s[36:37], 0, v[142:143]
	s_add_i32 m0, s35, 0xc000
	ds_read_b128 v[208:211], v175
	ds_read_b128 v[212:215], v175 offset:1024
	ds_read_b128 v[216:219], v175 offset:2048
	ds_read_b128 v[220:223], v175 offset:3072
	ds_read_b128 v[224:227], v175 offset:4096
	ds_read_b128 v[228:231], v175 offset:5120
	ds_read_b128 v[232:235], v175 offset:6144
	ds_read_b128 v[236:239], v175 offset:7168
	global_load_lds_dwordx4 v[176:177], off
	v_lshl_add_u64 v[176:177], s[36:37], 0, v[140:141]
	s_add_i32 m0, s35, 0xe000
	s_nop 0
	global_load_lds_dwordx4 v[176:177], off
	s_waitcnt vmcnt(8)
	s_waitcnt lgkmcnt(0)
	s_barrier
	s_setprio 1
	s_waitcnt lgkmcnt(0)
	v_mfma_f32_16x16x32_bf16 v[126:129], v[164:167], v[208:211], v[126:129]
	v_mfma_f32_16x16x32_bf16 v[122:125], v[184:187], v[208:211], v[122:125]
	v_mfma_f32_16x16x32_bf16 v[110:113], v[164:167], v[216:219], v[110:113]
	v_mfma_f32_16x16x32_bf16 v[106:109], v[184:187], v[216:219], v[106:109]
	v_mfma_f32_16x16x32_bf16 v[94:97], v[164:167], v[224:227], v[94:97]
	v_mfma_f32_16x16x32_bf16 v[90:93], v[184:187], v[224:227], v[90:93]
	v_mfma_f32_16x16x32_bf16 v[78:81], v[164:167], v[232:235], v[78:81]
	v_mfma_f32_16x16x32_bf16 v[74:77], v[184:187], v[232:235], v[74:77]
	v_mfma_f32_16x16x32_bf16 v[126:129], v[180:183], v[212:215], v[126:129]
	v_mfma_f32_16x16x32_bf16 v[122:125], v[188:191], v[212:215], v[122:125]
	v_mfma_f32_16x16x32_bf16 v[110:113], v[180:183], v[220:223], v[110:113]
	v_mfma_f32_16x16x32_bf16 v[106:109], v[188:191], v[220:223], v[106:109]
	v_mfma_f32_16x16x32_bf16 v[94:97], v[180:183], v[228:231], v[94:97]
	v_mfma_f32_16x16x32_bf16 v[90:93], v[188:191], v[228:231], v[90:93]
	v_mfma_f32_16x16x32_bf16 v[78:81], v[180:183], v[236:239], v[78:81]
	v_mfma_f32_16x16x32_bf16 v[74:77], v[188:191], v[236:239], v[74:77]
	v_mfma_f32_16x16x32_bf16 v[118:121], v[192:195], v[208:211], v[118:121]
	v_mfma_f32_16x16x32_bf16 v[114:117], v[200:203], v[208:211], v[114:117]
	v_mfma_f32_16x16x32_bf16 v[102:105], v[192:195], v[216:219], v[102:105]
	v_mfma_f32_16x16x32_bf16 v[98:101], v[200:203], v[216:219], v[98:101]
	v_mfma_f32_16x16x32_bf16 v[86:89], v[192:195], v[224:227], v[86:89]
	v_mfma_f32_16x16x32_bf16 v[82:85], v[200:203], v[224:227], v[82:85]
	v_mfma_f32_16x16x32_bf16 v[70:73], v[192:195], v[232:235], v[70:73]
	v_mfma_f32_16x16x32_bf16 v[66:69], v[200:203], v[232:235], v[66:69]
	v_mfma_f32_16x16x32_bf16 v[118:121], v[196:199], v[212:215], v[118:121]
	v_mfma_f32_16x16x32_bf16 v[114:117], v[204:207], v[212:215], v[114:117]
	v_mfma_f32_16x16x32_bf16 v[102:105], v[196:199], v[220:223], v[102:105]
	v_mfma_f32_16x16x32_bf16 v[98:101], v[204:207], v[220:223], v[98:101]
	v_mfma_f32_16x16x32_bf16 v[86:89], v[196:199], v[228:231], v[86:89]
	v_mfma_f32_16x16x32_bf16 v[82:85], v[204:207], v[228:231], v[82:85]
	v_mfma_f32_16x16x32_bf16 v[70:73], v[196:199], v[236:239], v[70:73]
	v_mfma_f32_16x16x32_bf16 v[66:69], v[204:207], v[236:239], v[66:69]
	s_setprio 0
	s_barrier
	s_add_i32 s62, s56, s45
	v_lshl_add_u64 v[176:177], s[38:39], 0, v[132:133]
	s_mov_b32 m0, s62
	ds_read_b128 v[208:211], v175 offset:16384
	ds_read_b128 v[212:215], v175 offset:17408
	ds_read_b128 v[216:219], v175 offset:18432
	ds_read_b128 v[220:223], v175 offset:19456
	ds_read_b128 v[224:227], v175 offset:20480
	ds_read_b128 v[228:231], v175 offset:21504
	ds_read_b128 v[232:235], v175 offset:22528
	ds_read_b128 v[236:239], v175 offset:23552
	global_load_lds_dwordx4 v[176:177], off
	s_add_i32 m0, s62, 0x2000
	s_add_u32 s62, s38, 0x40000
	v_lshl_add_u64 v[240:241], s[38:39], 0, v[136:137]
	s_addc_u32 s63, s39, 0
	s_add_i32 s64, s57, s45
	global_load_lds_dwordx4 v[240:241], off
	v_lshl_add_u64 v[242:243], s[62:63], 0, v[132:133]
	s_mov_b32 m0, s64
	v_lshl_add_u64 v[244:245], s[40:41], 0, v[134:135]
	global_load_lds_dwordx4 v[242:243], off
	v_lshl_add_u64 v[242:243], s[62:63], 0, v[136:137]
	s_add_i32 m0, s64, 0x2000
	s_nop 0
	global_load_lds_dwordx4 v[242:243], off
	v_lshl_add_u64 v[242:243], s[40:41], 0, v[130:131]
	s_mov_b32 m0, s35
	s_nop 0
	global_load_lds_dwordx4 v[242:243], off
	s_mov_b32 m0, s46
	s_nop 0
	global_load_lds_dwordx4 v[244:245], off
	s_waitcnt vmcnt(8)
	s_waitcnt lgkmcnt(0)
	s_barrier
	s_setprio 1
	s_waitcnt lgkmcnt(0)
	v_mfma_f32_16x16x32_bf16 v[62:65], v[164:167], v[208:211], v[62:65]
	v_mfma_f32_16x16x32_bf16 v[58:61], v[184:187], v[208:211], v[58:61]
	v_mfma_f32_16x16x32_bf16 v[46:49], v[164:167], v[216:219], v[46:49]
	v_mfma_f32_16x16x32_bf16 v[42:45], v[184:187], v[216:219], v[42:45]
	v_mfma_f32_16x16x32_bf16 v[30:33], v[164:167], v[224:227], v[30:33]
	v_mfma_f32_16x16x32_bf16 v[26:29], v[184:187], v[224:227], v[26:29]
	v_mfma_f32_16x16x32_bf16 v[14:17], v[164:167], v[232:235], v[14:17]
	v_mfma_f32_16x16x32_bf16 v[10:13], v[184:187], v[232:235], v[10:13]
	v_mfma_f32_16x16x32_bf16 v[62:65], v[180:183], v[212:215], v[62:65]
	v_mfma_f32_16x16x32_bf16 v[58:61], v[188:191], v[212:215], v[58:61]
	v_mfma_f32_16x16x32_bf16 v[46:49], v[180:183], v[220:223], v[46:49]
	v_mfma_f32_16x16x32_bf16 v[42:45], v[188:191], v[220:223], v[42:45]
	v_mfma_f32_16x16x32_bf16 v[30:33], v[180:183], v[228:231], v[30:33]
	v_mfma_f32_16x16x32_bf16 v[26:29], v[188:191], v[228:231], v[26:29]
	v_mfma_f32_16x16x32_bf16 v[14:17], v[180:183], v[236:239], v[14:17]
	v_mfma_f32_16x16x32_bf16 v[10:13], v[188:191], v[236:239], v[10:13]
	v_mfma_f32_16x16x32_bf16 v[54:57], v[192:195], v[208:211], v[54:57]
	v_mfma_f32_16x16x32_bf16 v[50:53], v[200:203], v[208:211], v[50:53]
	v_mfma_f32_16x16x32_bf16 v[38:41], v[192:195], v[216:219], v[38:41]
	v_mfma_f32_16x16x32_bf16 v[34:37], v[200:203], v[216:219], v[34:37]
	v_mfma_f32_16x16x32_bf16 v[22:25], v[192:195], v[224:227], v[22:25]
	v_mfma_f32_16x16x32_bf16 v[18:21], v[200:203], v[224:227], v[18:21]
	v_mfma_f32_16x16x32_bf16 v[6:9], v[192:195], v[232:235], v[6:9]
	v_mfma_f32_16x16x32_bf16 v[2:5], v[200:203], v[232:235], v[2:5]
	v_mfma_f32_16x16x32_bf16 v[54:57], v[196:199], v[212:215], v[54:57]
	v_mfma_f32_16x16x32_bf16 v[50:53], v[204:207], v[212:215], v[50:53]
	v_mfma_f32_16x16x32_bf16 v[38:41], v[196:199], v[220:223], v[38:41]
	v_mfma_f32_16x16x32_bf16 v[34:37], v[204:207], v[220:223], v[34:37]
	v_mfma_f32_16x16x32_bf16 v[22:25], v[196:199], v[228:231], v[22:25]
	v_mfma_f32_16x16x32_bf16 v[18:21], v[204:207], v[228:231], v[18:21]
	v_mfma_f32_16x16x32_bf16 v[6:9], v[196:199], v[236:239], v[6:9]
	v_mfma_f32_16x16x32_bf16 v[2:5], v[204:207], v[236:239], v[2:5]
	s_setprio 0
	s_barrier
	s_add_i32 s62, 0, 0x18000
	v_add_u32_e32 v149, s62, v171
	s_add_i32 s63, 0, 0x1c000
	ds_read_b128 v[164:167], v149
	ds_read_b128 v[180:183], v149 offset:1024
	ds_read_b128 v[184:187], v149 offset:2048
	ds_read_b128 v[188:191], v149 offset:3072
	v_add_u32_e32 v149, s63, v171
	ds_read_b128 v[192:195], v149
	ds_read_b128 v[196:199], v149 offset:1024
	ds_read_b128 v[200:203], v149 offset:2048
	ds_read_b128 v[204:207], v149 offset:3072
	s_add_u32 s40, s40, 0x40000
	s_addc_u32 s41, s41, 0
	s_mov_b32 m0, s47
	v_lshl_add_u64 v[246:247], s[40:41], 0, v[130:131]
	ds_read_b128 v[208:211], v175 offset:32768
	ds_read_b128 v[212:215], v175 offset:33792
	ds_read_b128 v[216:219], v175 offset:34816
	ds_read_b128 v[220:223], v175 offset:35840
	ds_read_b128 v[224:227], v175 offset:36864
	ds_read_b128 v[228:231], v175 offset:37888
	ds_read_b128 v[232:235], v175 offset:38912
	ds_read_b128 v[236:239], v175 offset:39936
	global_load_lds_dwordx4 v[246:247], off
	v_lshl_add_u64 v[246:247], s[40:41], 0, v[134:135]
	s_mov_b32 m0, s48
	s_nop 0
	global_load_lds_dwordx4 v[246:247], off
	s_waitcnt vmcnt(8)
	s_waitcnt lgkmcnt(0)
	s_barrier
	s_setprio 1
	s_waitcnt lgkmcnt(0)
	v_mfma_f32_16x16x32_bf16 v[126:129], v[164:167], v[208:211], v[126:129]
	v_mfma_f32_16x16x32_bf16 v[122:125], v[184:187], v[208:211], v[122:125]
	v_mfma_f32_16x16x32_bf16 v[110:113], v[164:167], v[216:219], v[110:113]
	v_mfma_f32_16x16x32_bf16 v[106:109], v[184:187], v[216:219], v[106:109]
	v_mfma_f32_16x16x32_bf16 v[94:97], v[164:167], v[224:227], v[94:97]
	v_mfma_f32_16x16x32_bf16 v[90:93], v[184:187], v[224:227], v[90:93]
	v_mfma_f32_16x16x32_bf16 v[78:81], v[164:167], v[232:235], v[78:81]
	v_mfma_f32_16x16x32_bf16 v[74:77], v[184:187], v[232:235], v[74:77]
	v_mfma_f32_16x16x32_bf16 v[126:129], v[180:183], v[212:215], v[126:129]
	v_mfma_f32_16x16x32_bf16 v[122:125], v[188:191], v[212:215], v[122:125]
	v_mfma_f32_16x16x32_bf16 v[110:113], v[180:183], v[220:223], v[110:113]
	v_mfma_f32_16x16x32_bf16 v[106:109], v[188:191], v[220:223], v[106:109]
	v_mfma_f32_16x16x32_bf16 v[94:97], v[180:183], v[228:231], v[94:97]
	v_mfma_f32_16x16x32_bf16 v[90:93], v[188:191], v[228:231], v[90:93]
	v_mfma_f32_16x16x32_bf16 v[78:81], v[180:183], v[236:239], v[78:81]
	v_mfma_f32_16x16x32_bf16 v[74:77], v[188:191], v[236:239], v[74:77]
	v_mfma_f32_16x16x32_bf16 v[118:121], v[192:195], v[208:211], v[118:121]
	v_mfma_f32_16x16x32_bf16 v[114:117], v[200:203], v[208:211], v[114:117]
	v_mfma_f32_16x16x32_bf16 v[102:105], v[192:195], v[216:219], v[102:105]
	v_mfma_f32_16x16x32_bf16 v[98:101], v[200:203], v[216:219], v[98:101]
	v_mfma_f32_16x16x32_bf16 v[86:89], v[192:195], v[224:227], v[86:89]
	v_mfma_f32_16x16x32_bf16 v[82:85], v[200:203], v[224:227], v[82:85]
	v_mfma_f32_16x16x32_bf16 v[70:73], v[192:195], v[232:235], v[70:73]
	v_mfma_f32_16x16x32_bf16 v[66:69], v[200:203], v[232:235], v[66:69]
	v_mfma_f32_16x16x32_bf16 v[118:121], v[196:199], v[212:215], v[118:121]
	v_mfma_f32_16x16x32_bf16 v[114:117], v[204:207], v[212:215], v[114:117]
	v_mfma_f32_16x16x32_bf16 v[102:105], v[196:199], v[220:223], v[102:105]
	v_mfma_f32_16x16x32_bf16 v[98:101], v[204:207], v[220:223], v[98:101]
	v_mfma_f32_16x16x32_bf16 v[86:89], v[196:199], v[228:231], v[86:89]
	v_mfma_f32_16x16x32_bf16 v[82:85], v[204:207], v[228:231], v[82:85]
	v_mfma_f32_16x16x32_bf16 v[70:73], v[196:199], v[236:239], v[70:73]
	v_mfma_f32_16x16x32_bf16 v[66:69], v[204:207], v[236:239], v[66:69]
	s_setprio 0
	s_barrier
	s_add_i32 s40, s62, s45
	v_lshl_add_u64 v[176:177], v[176:177], 0, s[8:9]
	s_mov_b32 m0, s40
	ds_read_b128 v[208:211], v175 offset:49152
	ds_read_b128 v[212:215], v175 offset:50176
	ds_read_b128 v[216:219], v175 offset:51200
	ds_read_b128 v[220:223], v175 offset:52224
	ds_read_b128 v[224:227], v175 offset:53248
	ds_read_b128 v[228:231], v175 offset:54272
	ds_read_b128 v[232:235], v175 offset:55296
	ds_read_b128 v[236:239], v175 offset:56320
	global_load_lds_dwordx4 v[176:177], off
	s_add_i32 m0, s40, 0x2000
	s_add_u32 s38, s38, 0x40080
	v_lshl_add_u64 v[176:177], v[240:241], 0, s[8:9]
	s_addc_u32 s39, s39, 0
	s_add_i32 s40, s63, s45
	global_load_lds_dwordx4 v[176:177], off
	v_lshl_add_u64 v[176:177], s[38:39], 0, v[132:133]
	s_mov_b32 m0, s40
	s_nop 0
	global_load_lds_dwordx4 v[176:177], off
	v_lshl_add_u64 v[176:177], s[38:39], 0, v[136:137]
	s_add_i32 m0, s40, 0x2000
	s_nop 0
	global_load_lds_dwordx4 v[176:177], off
	v_lshl_add_u64 v[176:177], v[242:243], 0, s[8:9]
	s_mov_b32 m0, s51
	s_nop 0
	global_load_lds_dwordx4 v[176:177], off
	v_lshl_add_u64 v[176:177], v[244:245], 0, s[8:9]
	s_mov_b32 m0, s52
	s_nop 0
	global_load_lds_dwordx4 v[176:177], off
	s_waitcnt vmcnt(8)
	s_waitcnt lgkmcnt(0)
	s_barrier
	s_setprio 1
	s_waitcnt lgkmcnt(0)
	v_mfma_f32_16x16x32_bf16 v[62:65], v[164:167], v[208:211], v[62:65]
	v_mfma_f32_16x16x32_bf16 v[58:61], v[184:187], v[208:211], v[58:61]
	v_mfma_f32_16x16x32_bf16 v[46:49], v[164:167], v[216:219], v[46:49]
	v_mfma_f32_16x16x32_bf16 v[42:45], v[184:187], v[216:219], v[42:45]
	v_mfma_f32_16x16x32_bf16 v[30:33], v[164:167], v[224:227], v[30:33]
	v_mfma_f32_16x16x32_bf16 v[26:29], v[184:187], v[224:227], v[26:29]
	v_mfma_f32_16x16x32_bf16 v[14:17], v[164:167], v[232:235], v[14:17]
	v_mfma_f32_16x16x32_bf16 v[10:13], v[184:187], v[232:235], v[10:13]
	v_mfma_f32_16x16x32_bf16 v[62:65], v[180:183], v[212:215], v[62:65]
	v_mfma_f32_16x16x32_bf16 v[58:61], v[188:191], v[212:215], v[58:61]
	v_mfma_f32_16x16x32_bf16 v[46:49], v[180:183], v[220:223], v[46:49]
	v_mfma_f32_16x16x32_bf16 v[42:45], v[188:191], v[220:223], v[42:45]
	v_mfma_f32_16x16x32_bf16 v[30:33], v[180:183], v[228:231], v[30:33]
	v_mfma_f32_16x16x32_bf16 v[26:29], v[188:191], v[228:231], v[26:29]
	v_mfma_f32_16x16x32_bf16 v[14:17], v[180:183], v[236:239], v[14:17]
	v_mfma_f32_16x16x32_bf16 v[10:13], v[188:191], v[236:239], v[10:13]
	v_mfma_f32_16x16x32_bf16 v[54:57], v[192:195], v[208:211], v[54:57]
	v_mfma_f32_16x16x32_bf16 v[50:53], v[200:203], v[208:211], v[50:53]
	v_mfma_f32_16x16x32_bf16 v[38:41], v[192:195], v[216:219], v[38:41]
	v_mfma_f32_16x16x32_bf16 v[34:37], v[200:203], v[216:219], v[34:37]
	v_mfma_f32_16x16x32_bf16 v[22:25], v[192:195], v[224:227], v[22:25]
	v_mfma_f32_16x16x32_bf16 v[18:21], v[200:203], v[224:227], v[18:21]
	v_mfma_f32_16x16x32_bf16 v[6:9], v[192:195], v[232:235], v[6:9]
	v_mfma_f32_16x16x32_bf16 v[2:5], v[200:203], v[232:235], v[2:5]
	v_mfma_f32_16x16x32_bf16 v[54:57], v[196:199], v[212:215], v[54:57]
	v_mfma_f32_16x16x32_bf16 v[50:53], v[204:207], v[212:215], v[50:53]
	v_mfma_f32_16x16x32_bf16 v[38:41], v[196:199], v[220:223], v[38:41]
	v_mfma_f32_16x16x32_bf16 v[34:37], v[204:207], v[220:223], v[34:37]
	v_mfma_f32_16x16x32_bf16 v[22:25], v[196:199], v[228:231], v[22:25]
	v_mfma_f32_16x16x32_bf16 v[18:21], v[204:207], v[228:231], v[18:21]
	v_mfma_f32_16x16x32_bf16 v[6:9], v[196:199], v[236:239], v[6:9]
	v_mfma_f32_16x16x32_bf16 v[2:5], v[204:207], v[236:239], v[2:5]
	s_setprio 0
	s_barrier
	s_add_i32 s61, s61, 2
	s_add_u32 s59, s59, 0x100
	s_addc_u32 s60, s60, 0
	s_add_u32 s36, s36, 0x100
	s_addc_u32 s37, s37, 0
	s_cmp_gt_u32 s61, 13
	s_cbranch_scc0 .LBB0_858
	s_andn2_b64 vcc, exec, s[2:3]
	s_cbranch_vccnz .Lrs8h_skip1
	v_lshl_add_u32 v188, s24, 8, v170
	v_ashrrev_i32_e32 v189, 31, v188
	v_lshlrev_b64 v[180:181], 6, v[188:189]
	v_lshl_add_u64 v[196:197], v[138:139], 0, v[180:181]
	v_or_b32_e32 v180, 16, v188
	v_or_b32_e32 v190, 32, v188
	v_or_b32_e32 v188, 48, v188
	v_ashrrev_i32_e32 v181, 31, v180
	v_ashrrev_i32_e32 v191, 31, v190
	v_ashrrev_i32_e32 v189, 31, v188
	v_lshlrev_b64 v[180:181], 6, v[180:181]
	v_lshlrev_b64 v[190:191], 6, v[190:191]
	v_lshlrev_b64 v[188:189], 6, v[188:189]
	v_add_co_u32_e32 v208, vcc, s49, v196
	v_lshl_add_u64 v[184:185], v[138:139], 0, v[180:181]
	v_lshl_add_u64 v[190:191], v[138:139], 0, v[190:191]
	v_lshl_add_u64 v[192:193], v[138:139], 0, v[188:189]
	v_addc_co_u32_e32 v209, vcc, 0, v197, vcc
	flat_load_dwordx4 v[180:183], v[196:197]
	s_nop 0
	flat_load_dwordx4 v[184:187], v[184:185]
	s_nop 0
	flat_load_dwordx4 v[188:191], v[190:191]
	s_nop 0
	flat_load_dwordx4 v[192:195], v[192:193]
	s_nop 0
	flat_load_dwordx4 v[196:199], v[208:209]
	flat_load_dwordx4 v[200:203], v[208:209] offset:1024
	flat_load_dwordx4 v[204:207], v[208:209] offset:2048
	s_nop 0
	flat_load_dwordx4 v[208:211], v[208:209] offset:3072

.LBB0_1039:
	v_add_u32_e32 v154, s62, v156
	ds_read_b128 v[130:133], v154
	ds_read_b128 v[150:153], v154 offset:1024
	ds_read_b128 v[160:163], v154 offset:2048
	ds_read_b128 v[164:167], v154 offset:3072
	v_add_u32_e32 v154, s63, v156
	ds_read_b128 v[168:171], v154
	ds_read_b128 v[172:175], v154 offset:1024
	ds_read_b128 v[180:183], v154 offset:2048
	ds_read_b128 v[184:187], v154 offset:3072
	s_add_u32 s42, s40, 0xfff00080
	s_addc_u32 s43, s41, -1
	s_cmp_eq_u32 s68, 60
	s_cselect_b32 s45, s31, s43
	s_cselect_b32 s44, s39, s42
	s_cselect_b32 s43, s29, s67
	s_cselect_b32 s42, s65, s66
	v_lshl_add_u64 v[154:155], s[40:41], 0, v[144:145]
	s_add_i32 m0, s51, 0xc000
	ds_read_b128 v[188:191], v158
	ds_read_b128 v[192:195], v158 offset:1024
	ds_read_b128 v[196:199], v158 offset:2048
	ds_read_b128 v[200:203], v158 offset:3072
	ds_read_b128 v[204:207], v158 offset:4096
	ds_read_b128 v[208:211], v158 offset:5120
	ds_read_b128 v[212:215], v158 offset:6144
	ds_read_b128 v[216:219], v158 offset:7168
	global_load_lds_dwordx4 v[154:155], off
	v_lshl_add_u64 v[154:155], s[40:41], 0, v[142:143]
	s_add_i32 m0, s51, 0xe000
	s_nop 0
	global_load_lds_dwordx4 v[154:155], off
	s_waitcnt vmcnt(8)
	s_waitcnt lgkmcnt(0)
	s_barrier
	s_setprio 1
	s_waitcnt lgkmcnt(0)
	v_mfma_f32_16x16x32_bf16 v[114:117], v[130:133], v[188:191], v[114:117]
	v_mfma_f32_16x16x32_bf16 v[118:121], v[160:163], v[188:191], v[118:121]
	v_mfma_f32_16x16x32_bf16 v[98:101], v[130:133], v[196:199], v[98:101]
	v_mfma_f32_16x16x32_bf16 v[102:105], v[160:163], v[196:199], v[102:105]
	v_mfma_f32_16x16x32_bf16 v[82:85], v[130:133], v[204:207], v[82:85]
	v_mfma_f32_16x16x32_bf16 v[86:89], v[160:163], v[204:207], v[86:89]
	v_mfma_f32_16x16x32_bf16 v[66:69], v[130:133], v[212:215], v[66:69]
	v_mfma_f32_16x16x32_bf16 v[70:73], v[160:163], v[212:215], v[70:73]
	v_mfma_f32_16x16x32_bf16 v[114:117], v[150:153], v[192:195], v[114:117]
	v_mfma_f32_16x16x32_bf16 v[118:121], v[164:167], v[192:195], v[118:121]
	v_mfma_f32_16x16x32_bf16 v[98:101], v[150:153], v[200:203], v[98:101]
	v_mfma_f32_16x16x32_bf16 v[102:105], v[164:167], v[200:203], v[102:105]
	v_mfma_f32_16x16x32_bf16 v[82:85], v[150:153], v[208:211], v[82:85]
	v_mfma_f32_16x16x32_bf16 v[86:89], v[164:167], v[208:211], v[86:89]
	v_mfma_f32_16x16x32_bf16 v[66:69], v[150:153], v[216:219], v[66:69]
	v_mfma_f32_16x16x32_bf16 v[70:73], v[164:167], v[216:219], v[70:73]
	v_mfma_f32_16x16x32_bf16 v[122:125], v[168:171], v[188:191], v[122:125]
	v_mfma_f32_16x16x32_bf16 v[126:129], v[180:183], v[188:191], v[126:129]
	v_mfma_f32_16x16x32_bf16 v[106:109], v[168:171], v[196:199], v[106:109]
	v_mfma_f32_16x16x32_bf16 v[110:113], v[180:183], v[196:199], v[110:113]
	v_mfma_f32_16x16x32_bf16 v[90:93], v[168:171], v[204:207], v[90:93]
	v_mfma_f32_16x16x32_bf16 v[94:97], v[180:183], v[204:207], v[94:97]
	v_mfma_f32_16x16x32_bf16 v[74:77], v[168:171], v[212:215], v[74:77]
	v_mfma_f32_16x16x32_bf16 v[78:81], v[180:183], v[212:215], v[78:81]
	v_mfma_f32_16x16x32_bf16 v[122:125], v[172:175], v[192:195], v[122:125]
	v_mfma_f32_16x16x32_bf16 v[126:129], v[184:187], v[192:195], v[126:129]
	v_mfma_f32_16x16x32_bf16 v[106:109], v[172:175], v[200:203], v[106:109]
	v_mfma_f32_16x16x32_bf16 v[110:113], v[184:187], v[200:203], v[110:113]
	v_mfma_f32_16x16x32_bf16 v[90:93], v[172:175], v[208:211], v[90:93]
	v_mfma_f32_16x16x32_bf16 v[94:97], v[184:187], v[208:211], v[94:97]
	v_mfma_f32_16x16x32_bf16 v[74:77], v[172:175], v[216:219], v[74:77]
	v_mfma_f32_16x16x32_bf16 v[78:81], v[184:187], v[216:219], v[78:81]
	s_setprio 0
	s_barrier
	s_add_i32 s69, s62, s50
	v_lshl_add_u64 v[154:155], s[42:43], 0, v[136:137]
	s_mov_b32 m0, s69
	ds_read_b128 v[188:191], v158 offset:16384
	ds_read_b128 v[192:195], v158 offset:17408
	ds_read_b128 v[196:199], v158 offset:18432
	ds_read_b128 v[200:203], v158 offset:19456
	ds_read_b128 v[204:207], v158 offset:20480
	ds_read_b128 v[208:211], v158 offset:21504
	ds_read_b128 v[212:215], v158 offset:22528
	ds_read_b128 v[216:219], v158 offset:23552
	global_load_lds_dwordx4 v[154:155], off
	s_add_i32 m0, s69, 0x2000
	s_add_u32 s70, s42, 0x100000
	v_lshl_add_u64 v[176:177], s[42:43], 0, v[140:141]
	s_addc_u32 s71, s43, 0
	s_add_i32 s69, s63, s50
	global_load_lds_dwordx4 v[176:177], off
	v_lshl_add_u64 v[220:221], s[70:71], 0, v[136:137]
	s_mov_b32 m0, s69
	v_lshl_add_u64 v[222:223], s[44:45], 0, v[138:139]
	global_load_lds_dwordx4 v[220:221], off
	v_lshl_add_u64 v[220:221], s[70:71], 0, v[140:141]
	s_add_i32 m0, s69, 0x2000
	s_nop 0
	global_load_lds_dwordx4 v[220:221], off
	v_lshl_add_u64 v[220:221], s[44:45], 0, v[134:135]
	s_mov_b32 m0, s51
	s_nop 0
	global_load_lds_dwordx4 v[220:221], off
	s_mov_b32 m0, s52
	s_nop 0
	global_load_lds_dwordx4 v[222:223], off
	s_waitcnt vmcnt(8)
	s_waitcnt lgkmcnt(0)
	s_barrier
	s_setprio 1
	s_waitcnt lgkmcnt(0)
	v_mfma_f32_16x16x32_bf16 v[50:53], v[130:133], v[188:191], v[50:53]
	v_mfma_f32_16x16x32_bf16 v[54:57], v[160:163], v[188:191], v[54:57]
	v_mfma_f32_16x16x32_bf16 v[26:29], v[130:133], v[196:199], v[26:29]
	v_mfma_f32_16x16x32_bf16 v[30:33], v[160:163], v[196:199], v[30:33]
	v_mfma_f32_16x16x32_bf16 v[18:21], v[130:133], v[204:207], v[18:21]
	v_mfma_f32_16x16x32_bf16 v[22:25], v[160:163], v[204:207], v[22:25]
	v_mfma_f32_16x16x32_bf16 v[2:5], v[130:133], v[212:215], v[2:5]
	v_mfma_f32_16x16x32_bf16 v[6:9], v[160:163], v[212:215], v[6:9]
	v_mfma_f32_16x16x32_bf16 v[50:53], v[150:153], v[192:195], v[50:53]
	v_mfma_f32_16x16x32_bf16 v[54:57], v[164:167], v[192:195], v[54:57]
	v_mfma_f32_16x16x32_bf16 v[26:29], v[150:153], v[200:203], v[26:29]
	v_mfma_f32_16x16x32_bf16 v[30:33], v[164:167], v[200:203], v[30:33]
	v_mfma_f32_16x16x32_bf16 v[18:21], v[150:153], v[208:211], v[18:21]
	v_mfma_f32_16x16x32_bf16 v[22:25], v[164:167], v[208:211], v[22:25]
	v_mfma_f32_16x16x32_bf16 v[2:5], v[150:153], v[216:219], v[2:5]
	v_mfma_f32_16x16x32_bf16 v[6:9], v[164:167], v[216:219], v[6:9]
	v_mfma_f32_16x16x32_bf16 v[58:61], v[168:171], v[188:191], v[58:61]
	v_mfma_f32_16x16x32_bf16 v[62:65], v[180:183], v[188:191], v[62:65]
	v_mfma_f32_16x16x32_bf16 v[42:45], v[168:171], v[196:199], v[42:45]
	v_mfma_f32_16x16x32_bf16 v[46:49], v[180:183], v[196:199], v[46:49]
	v_mfma_f32_16x16x32_bf16 v[34:37], v[168:171], v[204:207], v[34:37]
	v_mfma_f32_16x16x32_bf16 v[38:41], v[180:183], v[204:207], v[38:41]
	v_mfma_f32_16x16x32_bf16 v[10:13], v[168:171], v[212:215], v[10:13]
	v_mfma_f32_16x16x32_bf16 v[14:17], v[180:183], v[212:215], v[14:17]
	v_mfma_f32_16x16x32_bf16 v[58:61], v[172:175], v[192:195], v[58:61]
	v_mfma_f32_16x16x32_bf16 v[62:65], v[184:187], v[192:195], v[62:65]
	v_mfma_f32_16x16x32_bf16 v[42:45], v[172:175], v[200:203], v[42:45]
	v_mfma_f32_16x16x32_bf16 v[46:49], v[184:187], v[200:203], v[46:49]
	v_mfma_f32_16x16x32_bf16 v[34:37], v[172:175], v[208:211], v[34:37]
	v_mfma_f32_16x16x32_bf16 v[38:41], v[184:187], v[208:211], v[38:41]
	v_mfma_f32_16x16x32_bf16 v[10:13], v[172:175], v[216:219], v[10:13]
	v_mfma_f32_16x16x32_bf16 v[14:17], v[184:187], v[216:219], v[14:17]
	s_setprio 0
	s_barrier
	s_add_i32 s69, 0, 0x18000
	s_add_i32 s70, 0, 0x1c000
	v_add_u32_e32 v164, s69, v156
	v_add_u32_e32 v179, s70, v156
	ds_read_b128 v[130:133], v164
	ds_read_b128 v[150:153], v164 offset:1024
	ds_read_b128 v[160:163], v164 offset:2048
	ds_read_b128 v[164:167], v164 offset:3072
	ds_read_b128 v[168:171], v179
	ds_read_b128 v[172:175], v179 offset:1024
	ds_read_b128 v[180:183], v179 offset:2048
	ds_read_b128 v[184:187], v179 offset:3072
	s_add_u32 s44, s44, 0x100000
	s_addc_u32 s45, s45, 0
	s_mov_b32 m0, s53
	v_lshl_add_u64 v[224:225], s[44:45], 0, v[134:135]
	ds_read_b128 v[188:191], v158 offset:32768
	ds_read_b128 v[192:195], v158 offset:33792
	ds_read_b128 v[196:199], v158 offset:34816
	ds_read_b128 v[200:203], v158 offset:35840
	ds_read_b128 v[204:207], v158 offset:36864
	ds_read_b128 v[208:211], v158 offset:37888
	ds_read_b128 v[212:215], v158 offset:38912
	ds_read_b128 v[216:219], v158 offset:39936
	global_load_lds_dwordx4 v[224:225], off
	v_lshl_add_u64 v[224:225], s[44:45], 0, v[138:139]
	s_mov_b32 m0, s54
	s_nop 0
	global_load_lds_dwordx4 v[224:225], off
	s_waitcnt vmcnt(8)
	s_waitcnt lgkmcnt(0)
	s_barrier
	s_setprio 1
	s_waitcnt lgkmcnt(0)
	v_mfma_f32_16x16x32_bf16 v[114:117], v[130:133], v[188:191], v[114:117]
	v_mfma_f32_16x16x32_bf16 v[118:121], v[160:163], v[188:191], v[118:121]
	v_mfma_f32_16x16x32_bf16 v[98:101], v[130:133], v[196:199], v[98:101]
	v_mfma_f32_16x16x32_bf16 v[102:105], v[160:163], v[196:199], v[102:105]
	v_mfma_f32_16x16x32_bf16 v[82:85], v[130:133], v[204:207], v[82:85]
	v_mfma_f32_16x16x32_bf16 v[86:89], v[160:163], v[204:207], v[86:89]
	v_mfma_f32_16x16x32_bf16 v[66:69], v[130:133], v[212:215], v[66:69]
	v_mfma_f32_16x16x32_bf16 v[70:73], v[160:163], v[212:215], v[70:73]
	v_mfma_f32_16x16x32_bf16 v[114:117], v[150:153], v[192:195], v[114:117]
	v_mfma_f32_16x16x32_bf16 v[118:121], v[164:167], v[192:195], v[118:121]
	v_mfma_f32_16x16x32_bf16 v[98:101], v[150:153], v[200:203], v[98:101]
	v_mfma_f32_16x16x32_bf16 v[102:105], v[164:167], v[200:203], v[102:105]
	v_mfma_f32_16x16x32_bf16 v[82:85], v[150:153], v[208:211], v[82:85]
	v_mfma_f32_16x16x32_bf16 v[86:89], v[164:167], v[208:211], v[86:89]
	v_mfma_f32_16x16x32_bf16 v[66:69], v[150:153], v[216:219], v[66:69]
	v_mfma_f32_16x16x32_bf16 v[70:73], v[164:167], v[216:219], v[70:73]
	v_mfma_f32_16x16x32_bf16 v[122:125], v[168:171], v[188:191], v[122:125]
	v_mfma_f32_16x16x32_bf16 v[126:129], v[180:183], v[188:191], v[126:129]
	v_mfma_f32_16x16x32_bf16 v[106:109], v[168:171], v[196:199], v[106:109]
	v_mfma_f32_16x16x32_bf16 v[110:113], v[180:183], v[196:199], v[110:113]
	v_mfma_f32_16x16x32_bf16 v[90:93], v[168:171], v[204:207], v[90:93]
	v_mfma_f32_16x16x32_bf16 v[94:97], v[180:183], v[204:207], v[94:97]
	v_mfma_f32_16x16x32_bf16 v[74:77], v[168:171], v[212:215], v[74:77]
	v_mfma_f32_16x16x32_bf16 v[78:81], v[180:183], v[212:215], v[78:81]
	v_mfma_f32_16x16x32_bf16 v[122:125], v[172:175], v[192:195], v[122:125]
	v_mfma_f32_16x16x32_bf16 v[126:129], v[184:187], v[192:195], v[126:129]
	v_mfma_f32_16x16x32_bf16 v[106:109], v[172:175], v[200:203], v[106:109]
	v_mfma_f32_16x16x32_bf16 v[110:113], v[184:187], v[200:203], v[110:113]
	v_mfma_f32_16x16x32_bf16 v[90:93], v[172:175], v[208:211], v[90:93]
	v_mfma_f32_16x16x32_bf16 v[94:97], v[184:187], v[208:211], v[94:97]
	v_mfma_f32_16x16x32_bf16 v[74:77], v[172:175], v[216:219], v[74:77]
	v_mfma_f32_16x16x32_bf16 v[78:81], v[184:187], v[216:219], v[78:81]
	s_setprio 0
	s_barrier
	s_add_i32 s44, s69, s50
	v_lshl_add_u64 v[154:155], v[154:155], 0, s[22:23]
	s_mov_b32 m0, s44
	ds_read_b128 v[188:191], v158 offset:49152
	ds_read_b128 v[192:195], v158 offset:50176
	ds_read_b128 v[196:199], v158 offset:51200
	ds_read_b128 v[200:203], v158 offset:52224
	ds_read_b128 v[204:207], v158 offset:53248
	ds_read_b128 v[208:211], v158 offset:54272
	ds_read_b128 v[212:215], v158 offset:55296
	ds_read_b128 v[216:219], v158 offset:56320
	global_load_lds_dwordx4 v[154:155], off
	s_add_i32 m0, s44, 0x2000
	s_add_u32 s42, s42, 0x100080
	v_lshl_add_u64 v[154:155], v[176:177], 0, s[22:23]
	s_addc_u32 s43, s43, 0
	s_add_i32 s44, s70, s50
	global_load_lds_dwordx4 v[154:155], off
	v_lshl_add_u64 v[154:155], s[42:43], 0, v[136:137]
	s_mov_b32 m0, s44
	s_nop 0
	global_load_lds_dwordx4 v[154:155], off
	v_lshl_add_u64 v[154:155], s[42:43], 0, v[140:141]
	s_add_i32 m0, s44, 0x2000
	s_nop 0
	global_load_lds_dwordx4 v[154:155], off
	v_lshl_add_u64 v[154:155], v[220:221], 0, s[22:23]
	s_mov_b32 m0, s57
	s_nop 0
	global_load_lds_dwordx4 v[154:155], off
	v_lshl_add_u64 v[154:155], v[222:223], 0, s[22:23]
	s_mov_b32 m0, s58
	s_nop 0
	global_load_lds_dwordx4 v[154:155], off
	s_waitcnt vmcnt(8)
	s_waitcnt lgkmcnt(0)
	s_barrier
	s_setprio 1
	s_waitcnt lgkmcnt(0)
	v_mfma_f32_16x16x32_bf16 v[50:53], v[130:133], v[188:191], v[50:53]
	v_mfma_f32_16x16x32_bf16 v[54:57], v[160:163], v[188:191], v[54:57]
	v_mfma_f32_16x16x32_bf16 v[26:29], v[130:133], v[196:199], v[26:29]
	v_mfma_f32_16x16x32_bf16 v[30:33], v[160:163], v[196:199], v[30:33]
	v_mfma_f32_16x16x32_bf16 v[18:21], v[130:133], v[204:207], v[18:21]
	v_mfma_f32_16x16x32_bf16 v[22:25], v[160:163], v[204:207], v[22:25]
	v_mfma_f32_16x16x32_bf16 v[2:5], v[130:133], v[212:215], v[2:5]
	v_mfma_f32_16x16x32_bf16 v[6:9], v[160:163], v[212:215], v[6:9]
	v_mfma_f32_16x16x32_bf16 v[50:53], v[150:153], v[192:195], v[50:53]
	v_mfma_f32_16x16x32_bf16 v[54:57], v[164:167], v[192:195], v[54:57]
	v_mfma_f32_16x16x32_bf16 v[26:29], v[150:153], v[200:203], v[26:29]
	v_mfma_f32_16x16x32_bf16 v[30:33], v[164:167], v[200:203], v[30:33]
	v_mfma_f32_16x16x32_bf16 v[18:21], v[150:153], v[208:211], v[18:21]
	v_mfma_f32_16x16x32_bf16 v[22:25], v[164:167], v[208:211], v[22:25]
	v_mfma_f32_16x16x32_bf16 v[2:5], v[150:153], v[216:219], v[2:5]
	v_mfma_f32_16x16x32_bf16 v[6:9], v[164:167], v[216:219], v[6:9]
	v_mfma_f32_16x16x32_bf16 v[58:61], v[168:171], v[188:191], v[58:61]
	v_mfma_f32_16x16x32_bf16 v[62:65], v[180:183], v[188:191], v[62:65]
	v_mfma_f32_16x16x32_bf16 v[42:45], v[168:171], v[196:199], v[42:45]
	v_mfma_f32_16x16x32_bf16 v[46:49], v[180:183], v[196:199], v[46:49]
	v_mfma_f32_16x16x32_bf16 v[34:37], v[168:171], v[204:207], v[34:37]
	v_mfma_f32_16x16x32_bf16 v[38:41], v[180:183], v[204:207], v[38:41]
	v_mfma_f32_16x16x32_bf16 v[10:13], v[168:171], v[212:215], v[10:13]
	v_mfma_f32_16x16x32_bf16 v[14:17], v[180:183], v[212:215], v[14:17]
	v_mfma_f32_16x16x32_bf16 v[58:61], v[172:175], v[192:195], v[58:61]
	v_mfma_f32_16x16x32_bf16 v[62:65], v[184:187], v[192:195], v[62:65]
	v_mfma_f32_16x16x32_bf16 v[42:45], v[172:175], v[200:203], v[42:45]
	v_mfma_f32_16x16x32_bf16 v[46:49], v[184:187], v[200:203], v[46:49]
	v_mfma_f32_16x16x32_bf16 v[34:37], v[172:175], v[208:211], v[34:37]
	v_mfma_f32_16x16x32_bf16 v[38:41], v[184:187], v[208:211], v[38:41]
	v_mfma_f32_16x16x32_bf16 v[10:13], v[172:175], v[216:219], v[10:13]
	v_mfma_f32_16x16x32_bf16 v[14:17], v[184:187], v[216:219], v[14:17]
	s_setprio 0
	s_barrier
	s_add_i32 s68, s68, 2
	s_add_u32 s66, s66, 0x100
	s_addc_u32 s67, s67, 0
	s_add_u32 s40, s40, 0x100
	s_addc_u32 s41, s41, 0
	s_cmp_gt_u32 s68, 61
	s_cbranch_scc0 .LBB0_1039
	s_and_b64 vcc, exec, s[24:25]
	s_cbranch_vccz .LBB0_1042
	s_barrier

.LBB0_1216:
	s_add_u32 s45, s38, s44
	s_addc_u32 s50, s39, 0
	s_add_u32 s48, s45, 0x100
	s_addc_u32 s49, s50, 0
	s_and_b64 s[46:47], s[42:43], exec
	s_cselect_b32 s47, s25, s49
	s_cselect_b32 s46, s31, s48
	s_add_u32 s44, s36, s44
	s_addc_u32 s48, s37, 0
	s_add_u32 s44, s44, 0x100
	s_addc_u32 s48, s48, 0
	s_and_b64 s[42:43], s[42:43], exec
	s_cselect_b32 s49, s23, s48
	s_cselect_b32 s48, s69, s44
	s_add_u32 s52, s45, 0x10080
	ds_read_b128 v[142:145], v148
	ds_read_b128 v[152:155], v148 offset:1024
	ds_read_b128 v[156:159], v148 offset:2048
	ds_read_b128 v[160:163], v148 offset:3072
	ds_read_b128 v[164:167], v149
	ds_read_b128 v[168:171], v149 offset:1024
	ds_read_b128 v[172:175], v149 offset:2048
	ds_read_b128 v[180:183], v149 offset:3072
	s_addc_u32 s53, s50, 0
	s_add_i32 s77, s67, s57
	s_add_i32 m0, s35, 0xc000
	s_add_i32 s80, s35, 0xe000
	s_add_i32 s74, s77, 0x2000
	s_add_u32 s50, s48, 0x10000
	s_addc_u32 s51, s49, 0
	s_add_i32 s76, s68, s57
	s_add_i32 s75, s76, 0x2000
	s_add_i32 s73, 0, 0x18000
	s_add_i32 s72, 0, 0x1c000
	s_add_u32 s44, s46, 0x10000
	s_addc_u32 s45, s47, 0
	s_add_i32 s71, s73, s57
	s_add_i32 s70, s71, 0x2000
	s_add_u32 s42, s48, 0x10080
	s_addc_u32 s43, s49, 0
	s_add_i32 s79, s72, s57
	s_add_i32 s78, s79, 0x2000
	v_lshl_add_u64 v[176:177], s[52:53], 0, v[130:131]
	ds_read_b128 v[184:187], v150
	ds_read_b128 v[188:191], v150 offset:1024
	ds_read_b128 v[192:195], v150 offset:2048
	ds_read_b128 v[196:199], v150 offset:3072
	ds_read_b128 v[200:203], v150 offset:4096
	ds_read_b128 v[204:207], v150 offset:5120
	ds_read_b128 v[208:211], v150 offset:6144
	ds_read_b128 v[212:215], v150 offset:7168
	global_load_lds_dwordx4 v[176:177], off
	v_lshl_add_u64 v[176:177], s[52:53], 0, v[134:135]
	s_mov_b32 m0, s80
	s_nop 0
	global_load_lds_dwordx4 v[176:177], off
	s_waitcnt vmcnt(8)
	s_waitcnt lgkmcnt(0)
	s_barrier
	s_setprio 1
	s_waitcnt lgkmcnt(0)
	v_mfma_f32_16x16x32_bf16 v[126:129], v[142:145], v[184:187], v[126:129]
	v_mfma_f32_16x16x32_bf16 v[122:125], v[156:159], v[184:187], v[122:125]
	v_mfma_f32_16x16x32_bf16 v[110:113], v[142:145], v[192:195], v[110:113]
	v_mfma_f32_16x16x32_bf16 v[106:109], v[156:159], v[192:195], v[106:109]
	v_mfma_f32_16x16x32_bf16 v[94:97], v[142:145], v[200:203], v[94:97]
	v_mfma_f32_16x16x32_bf16 v[90:93], v[156:159], v[200:203], v[90:93]
	v_mfma_f32_16x16x32_bf16 v[78:81], v[142:145], v[208:211], v[78:81]
	v_mfma_f32_16x16x32_bf16 v[74:77], v[156:159], v[208:211], v[74:77]
	v_mfma_f32_16x16x32_bf16 v[126:129], v[152:155], v[188:191], v[126:129]
	v_mfma_f32_16x16x32_bf16 v[122:125], v[160:163], v[188:191], v[122:125]
	v_mfma_f32_16x16x32_bf16 v[110:113], v[152:155], v[196:199], v[110:113]
	v_mfma_f32_16x16x32_bf16 v[106:109], v[160:163], v[196:199], v[106:109]
	v_mfma_f32_16x16x32_bf16 v[94:97], v[152:155], v[204:207], v[94:97]
	v_mfma_f32_16x16x32_bf16 v[90:93], v[160:163], v[204:207], v[90:93]
	v_mfma_f32_16x16x32_bf16 v[78:81], v[152:155], v[212:215], v[78:81]
	v_mfma_f32_16x16x32_bf16 v[74:77], v[160:163], v[212:215], v[74:77]
	v_mfma_f32_16x16x32_bf16 v[118:121], v[164:167], v[184:187], v[118:121]
	v_mfma_f32_16x16x32_bf16 v[114:117], v[172:175], v[184:187], v[114:117]
	v_mfma_f32_16x16x32_bf16 v[102:105], v[164:167], v[192:195], v[102:105]
	v_mfma_f32_16x16x32_bf16 v[98:101], v[172:175], v[192:195], v[98:101]
	v_mfma_f32_16x16x32_bf16 v[86:89], v[164:167], v[200:203], v[86:89]
	v_mfma_f32_16x16x32_bf16 v[82:85], v[172:175], v[200:203], v[82:85]
	v_mfma_f32_16x16x32_bf16 v[70:73], v[164:167], v[208:211], v[70:73]
	v_mfma_f32_16x16x32_bf16 v[66:69], v[172:175], v[208:211], v[66:69]
	v_mfma_f32_16x16x32_bf16 v[118:121], v[168:171], v[188:191], v[118:121]
	v_mfma_f32_16x16x32_bf16 v[114:117], v[180:183], v[188:191], v[114:117]
	v_mfma_f32_16x16x32_bf16 v[102:105], v[168:171], v[196:199], v[102:105]
	v_mfma_f32_16x16x32_bf16 v[98:101], v[180:183], v[196:199], v[98:101]
	v_mfma_f32_16x16x32_bf16 v[86:89], v[168:171], v[204:207], v[86:89]
	v_mfma_f32_16x16x32_bf16 v[82:85], v[180:183], v[204:207], v[82:85]
	v_mfma_f32_16x16x32_bf16 v[70:73], v[168:171], v[212:215], v[70:73]
	v_mfma_f32_16x16x32_bf16 v[66:69], v[180:183], v[212:215], v[66:69]
	s_setprio 0
	s_barrier
	s_mov_b32 m0, s77
	v_lshl_add_u64 v[176:177], s[48:49], 0, v[132:133]
	ds_read_b128 v[184:187], v150 offset:16384
	ds_read_b128 v[188:191], v150 offset:17408
	ds_read_b128 v[192:195], v150 offset:18432
	ds_read_b128 v[196:199], v150 offset:19456
	ds_read_b128 v[200:203], v150 offset:20480
	ds_read_b128 v[204:207], v150 offset:21504
	ds_read_b128 v[208:211], v150 offset:22528
	ds_read_b128 v[212:215], v150 offset:23552
	global_load_lds_dwordx4 v[176:177], off
	v_lshl_add_u64 v[216:217], s[48:49], 0, v[136:137]
	s_mov_b32 m0, s74
	v_lshl_add_u64 v[218:219], s[50:51], 0, v[132:133]
	global_load_lds_dwordx4 v[216:217], off
	s_mov_b32 m0, s76
	v_lshl_add_u64 v[220:221], s[46:47], 0, v[134:135]
	global_load_lds_dwordx4 v[218:219], off
	v_lshl_add_u64 v[218:219], s[50:51], 0, v[136:137]
	s_mov_b32 m0, s75
	s_nop 0
	global_load_lds_dwordx4 v[218:219], off
	v_lshl_add_u64 v[218:219], s[46:47], 0, v[130:131]
	s_mov_b32 m0, s35
	s_nop 0
	global_load_lds_dwordx4 v[218:219], off
	s_mov_b32 m0, s58
	s_nop 0
	global_load_lds_dwordx4 v[220:221], off
	s_waitcnt vmcnt(8)
	s_waitcnt lgkmcnt(0)
	s_barrier
	s_setprio 1
	s_waitcnt lgkmcnt(0)
	v_mfma_f32_16x16x32_bf16 v[62:65], v[142:145], v[184:187], v[62:65]
	v_mfma_f32_16x16x32_bf16 v[58:61], v[156:159], v[184:187], v[58:61]
	v_mfma_f32_16x16x32_bf16 v[46:49], v[142:145], v[192:195], v[46:49]
	v_mfma_f32_16x16x32_bf16 v[42:45], v[156:159], v[192:195], v[42:45]
	v_mfma_f32_16x16x32_bf16 v[30:33], v[142:145], v[200:203], v[30:33]
	v_mfma_f32_16x16x32_bf16 v[26:29], v[156:159], v[200:203], v[26:29]
	v_mfma_f32_16x16x32_bf16 v[14:17], v[142:145], v[208:211], v[14:17]
	v_mfma_f32_16x16x32_bf16 v[10:13], v[156:159], v[208:211], v[10:13]
	v_mfma_f32_16x16x32_bf16 v[62:65], v[152:155], v[188:191], v[62:65]
	v_mfma_f32_16x16x32_bf16 v[58:61], v[160:163], v[188:191], v[58:61]
	v_mfma_f32_16x16x32_bf16 v[46:49], v[152:155], v[196:199], v[46:49]
	v_mfma_f32_16x16x32_bf16 v[42:45], v[160:163], v[196:199], v[42:45]
	v_mfma_f32_16x16x32_bf16 v[30:33], v[152:155], v[204:207], v[30:33]
	v_mfma_f32_16x16x32_bf16 v[26:29], v[160:163], v[204:207], v[26:29]
	v_mfma_f32_16x16x32_bf16 v[14:17], v[152:155], v[212:215], v[14:17]
	v_mfma_f32_16x16x32_bf16 v[10:13], v[160:163], v[212:215], v[10:13]
	v_mfma_f32_16x16x32_bf16 v[54:57], v[164:167], v[184:187], v[54:57]
	v_mfma_f32_16x16x32_bf16 v[50:53], v[172:175], v[184:187], v[50:53]
	v_mfma_f32_16x16x32_bf16 v[38:41], v[164:167], v[192:195], v[38:41]
	v_mfma_f32_16x16x32_bf16 v[34:37], v[172:175], v[192:195], v[34:37]
	v_mfma_f32_16x16x32_bf16 v[22:25], v[164:167], v[200:203], v[22:25]
	v_mfma_f32_16x16x32_bf16 v[18:21], v[172:175], v[200:203], v[18:21]
	v_mfma_f32_16x16x32_bf16 v[6:9], v[164:167], v[208:211], v[6:9]
	v_mfma_f32_16x16x32_bf16 v[2:5], v[172:175], v[208:211], v[2:5]
	v_mfma_f32_16x16x32_bf16 v[54:57], v[168:171], v[188:191], v[54:57]
	v_mfma_f32_16x16x32_bf16 v[50:53], v[180:183], v[188:191], v[50:53]
	v_mfma_f32_16x16x32_bf16 v[38:41], v[168:171], v[196:199], v[38:41]
	v_mfma_f32_16x16x32_bf16 v[34:37], v[180:183], v[196:199], v[34:37]
	v_mfma_f32_16x16x32_bf16 v[22:25], v[168:171], v[204:207], v[22:25]
	v_mfma_f32_16x16x32_bf16 v[18:21], v[180:183], v[204:207], v[18:21]
	v_mfma_f32_16x16x32_bf16 v[6:9], v[168:171], v[212:215], v[6:9]
	v_mfma_f32_16x16x32_bf16 v[2:5], v[180:183], v[212:215], v[2:5]
	s_setprio 0
	s_barrier
	v_add_u32_e32 v151, s73, v146
	ds_read_b128 v[142:145], v151
	ds_read_b128 v[152:155], v151 offset:1024
	ds_read_b128 v[156:159], v151 offset:2048
	ds_read_b128 v[160:163], v151 offset:3072
	v_add_u32_e32 v151, s72, v146
	ds_read_b128 v[164:167], v151
	ds_read_b128 v[168:171], v151 offset:1024
	ds_read_b128 v[172:175], v151 offset:2048
	ds_read_b128 v[180:183], v151 offset:3072
	s_mov_b32 m0, s59
	v_lshl_add_u64 v[222:223], s[44:45], 0, v[130:131]
	ds_read_b128 v[184:187], v150 offset:32768
	ds_read_b128 v[188:191], v150 offset:33792
	ds_read_b128 v[192:195], v150 offset:34816
	ds_read_b128 v[196:199], v150 offset:35840
	ds_read_b128 v[200:203], v150 offset:36864
	ds_read_b128 v[204:207], v150 offset:37888
	ds_read_b128 v[208:211], v150 offset:38912
	ds_read_b128 v[212:215], v150 offset:39936
	global_load_lds_dwordx4 v[222:223], off
	v_lshl_add_u64 v[222:223], s[44:45], 0, v[134:135]
	s_mov_b32 m0, s60
	s_nop 0
	global_load_lds_dwordx4 v[222:223], off
	s_waitcnt vmcnt(8)
	s_waitcnt lgkmcnt(0)
	s_barrier
	s_setprio 1
	s_waitcnt lgkmcnt(0)
	v_mfma_f32_16x16x32_bf16 v[126:129], v[142:145], v[184:187], v[126:129]
	v_mfma_f32_16x16x32_bf16 v[122:125], v[156:159], v[184:187], v[122:125]
	v_mfma_f32_16x16x32_bf16 v[110:113], v[142:145], v[192:195], v[110:113]
	v_mfma_f32_16x16x32_bf16 v[106:109], v[156:159], v[192:195], v[106:109]
	v_mfma_f32_16x16x32_bf16 v[94:97], v[142:145], v[200:203], v[94:97]
	v_mfma_f32_16x16x32_bf16 v[90:93], v[156:159], v[200:203], v[90:93]
	v_mfma_f32_16x16x32_bf16 v[78:81], v[142:145], v[208:211], v[78:81]
	v_mfma_f32_16x16x32_bf16 v[74:77], v[156:159], v[208:211], v[74:77]
	v_mfma_f32_16x16x32_bf16 v[126:129], v[152:155], v[188:191], v[126:129]
	v_mfma_f32_16x16x32_bf16 v[122:125], v[160:163], v[188:191], v[122:125]
	v_mfma_f32_16x16x32_bf16 v[110:113], v[152:155], v[196:199], v[110:113]
	v_mfma_f32_16x16x32_bf16 v[106:109], v[160:163], v[196:199], v[106:109]
	v_mfma_f32_16x16x32_bf16 v[94:97], v[152:155], v[204:207], v[94:97]
	v_mfma_f32_16x16x32_bf16 v[90:93], v[160:163], v[204:207], v[90:93]
	v_mfma_f32_16x16x32_bf16 v[78:81], v[152:155], v[212:215], v[78:81]
	v_mfma_f32_16x16x32_bf16 v[74:77], v[160:163], v[212:215], v[74:77]
	v_mfma_f32_16x16x32_bf16 v[118:121], v[164:167], v[184:187], v[118:121]
	v_mfma_f32_16x16x32_bf16 v[114:117], v[172:175], v[184:187], v[114:117]
	v_mfma_f32_16x16x32_bf16 v[102:105], v[164:167], v[192:195], v[102:105]
	v_mfma_f32_16x16x32_bf16 v[98:101], v[172:175], v[192:195], v[98:101]
	v_mfma_f32_16x16x32_bf16 v[86:89], v[164:167], v[200:203], v[86:89]
	v_mfma_f32_16x16x32_bf16 v[82:85], v[172:175], v[200:203], v[82:85]
	v_mfma_f32_16x16x32_bf16 v[70:73], v[164:167], v[208:211], v[70:73]
	v_mfma_f32_16x16x32_bf16 v[66:69], v[172:175], v[208:211], v[66:69]
	v_mfma_f32_16x16x32_bf16 v[118:121], v[168:171], v[188:191], v[118:121]
	v_mfma_f32_16x16x32_bf16 v[114:117], v[180:183], v[188:191], v[114:117]
	v_mfma_f32_16x16x32_bf16 v[102:105], v[168:171], v[196:199], v[102:105]
	v_mfma_f32_16x16x32_bf16 v[98:101], v[180:183], v[196:199], v[98:101]
	v_mfma_f32_16x16x32_bf16 v[86:89], v[168:171], v[204:207], v[86:89]
	v_mfma_f32_16x16x32_bf16 v[82:85], v[180:183], v[204:207], v[82:85]
	v_mfma_f32_16x16x32_bf16 v[70:73], v[168:171], v[212:215], v[70:73]
	v_mfma_f32_16x16x32_bf16 v[66:69], v[180:183], v[212:215], v[66:69]
	s_setprio 0
	s_barrier
	s_mov_b32 m0, s71
	v_lshl_add_u64 v[176:177], v[176:177], 0, s[8:9]
	ds_read_b128 v[184:187], v150 offset:49152
	ds_read_b128 v[188:191], v150 offset:50176
	ds_read_b128 v[192:195], v150 offset:51200
	ds_read_b128 v[196:199], v150 offset:52224
	ds_read_b128 v[200:203], v150 offset:53248
	ds_read_b128 v[204:207], v150 offset:54272
	ds_read_b128 v[208:211], v150 offset:55296
	ds_read_b128 v[212:215], v150 offset:56320
	global_load_lds_dwordx4 v[176:177], off
	v_lshl_add_u64 v[176:177], v[216:217], 0, s[8:9]
	s_mov_b32 m0, s70
	s_nop 0
	global_load_lds_dwordx4 v[176:177], off
	v_lshl_add_u64 v[176:177], s[42:43], 0, v[132:133]
	s_mov_b32 m0, s79
	s_nop 0
	global_load_lds_dwordx4 v[176:177], off
	v_lshl_add_u64 v[176:177], s[42:43], 0, v[136:137]
	s_mov_b32 m0, s78
	s_nop 0
	global_load_lds_dwordx4 v[176:177], off
	v_lshl_add_u64 v[176:177], v[218:219], 0, s[8:9]
	s_mov_b32 m0, s62
	s_nop 0
	global_load_lds_dwordx4 v[176:177], off
	v_lshl_add_u64 v[176:177], v[220:221], 0, s[8:9]
	s_mov_b32 m0, s63
	s_nop 0
	global_load_lds_dwordx4 v[176:177], off
	s_waitcnt vmcnt(8)
	s_waitcnt lgkmcnt(0)
	s_barrier
	s_setprio 1
	s_waitcnt lgkmcnt(0)
	v_mfma_f32_16x16x32_bf16 v[62:65], v[142:145], v[184:187], v[62:65]
	v_mfma_f32_16x16x32_bf16 v[58:61], v[156:159], v[184:187], v[58:61]
	v_mfma_f32_16x16x32_bf16 v[46:49], v[142:145], v[192:195], v[46:49]
	v_mfma_f32_16x16x32_bf16 v[42:45], v[156:159], v[192:195], v[42:45]
	v_mfma_f32_16x16x32_bf16 v[30:33], v[142:145], v[200:203], v[30:33]
	v_mfma_f32_16x16x32_bf16 v[26:29], v[156:159], v[200:203], v[26:29]
	v_mfma_f32_16x16x32_bf16 v[14:17], v[142:145], v[208:211], v[14:17]
	v_mfma_f32_16x16x32_bf16 v[10:13], v[156:159], v[208:211], v[10:13]
	v_mfma_f32_16x16x32_bf16 v[62:65], v[152:155], v[188:191], v[62:65]
	v_mfma_f32_16x16x32_bf16 v[58:61], v[160:163], v[188:191], v[58:61]
	v_mfma_f32_16x16x32_bf16 v[46:49], v[152:155], v[196:199], v[46:49]
	v_mfma_f32_16x16x32_bf16 v[42:45], v[160:163], v[196:199], v[42:45]
	v_mfma_f32_16x16x32_bf16 v[30:33], v[152:155], v[204:207], v[30:33]
	v_mfma_f32_16x16x32_bf16 v[26:29], v[160:163], v[204:207], v[26:29]
	v_mfma_f32_16x16x32_bf16 v[14:17], v[152:155], v[212:215], v[14:17]
	v_mfma_f32_16x16x32_bf16 v[10:13], v[160:163], v[212:215], v[10:13]
	v_mfma_f32_16x16x32_bf16 v[54:57], v[164:167], v[184:187], v[54:57]
	v_mfma_f32_16x16x32_bf16 v[50:53], v[172:175], v[184:187], v[50:53]
	v_mfma_f32_16x16x32_bf16 v[38:41], v[164:167], v[192:195], v[38:41]
	v_mfma_f32_16x16x32_bf16 v[34:37], v[172:175], v[192:195], v[34:37]
	v_mfma_f32_16x16x32_bf16 v[22:25], v[164:167], v[200:203], v[22:25]
	v_mfma_f32_16x16x32_bf16 v[18:21], v[172:175], v[200:203], v[18:21]
	v_mfma_f32_16x16x32_bf16 v[6:9], v[164:167], v[208:211], v[6:9]
	v_mfma_f32_16x16x32_bf16 v[2:5], v[172:175], v[208:211], v[2:5]
	v_mfma_f32_16x16x32_bf16 v[54:57], v[168:171], v[188:191], v[54:57]
	v_mfma_f32_16x16x32_bf16 v[50:53], v[180:183], v[188:191], v[50:53]
	v_mfma_f32_16x16x32_bf16 v[38:41], v[168:171], v[196:199], v[38:41]
	v_mfma_f32_16x16x32_bf16 v[34:37], v[180:183], v[196:199], v[34:37]
	v_mfma_f32_16x16x32_bf16 v[22:25], v[168:171], v[204:207], v[22:25]
	v_mfma_f32_16x16x32_bf16 v[18:21], v[180:183], v[204:207], v[18:21]
	v_mfma_f32_16x16x32_bf16 v[6:9], v[168:171], v[212:215], v[6:9]
	v_mfma_f32_16x16x32_bf16 v[2:5], v[180:183], v[212:215], v[2:5]
	s_setprio 0
	s_barrier
	s_movk_i32 s44, 0x100
	s_andn2_b64 vcc, exec, s[40:41]
	s_mov_b64 s[42:43], -1
	s_mov_b64 s[40:41], 0
	s_cbranch_vccz .LBB0_1216
	s_and_b64 vcc, exec, s[10:11]
	s_cbranch_vccz .LBB0_1219
	s_barrier

.LBB0_1308:
	ds_read_b128 v[130:133], v184
	ds_read_b128 v[134:137], v184 offset:1024
	ds_read_b128 v[138:141], v184 offset:2048
	ds_read_b128 v[142:145], v184 offset:3072
	ds_read_b128 v[146:149], v185
	ds_read_b128 v[150:153], v185 offset:1024
	ds_read_b128 v[172:175], v185 offset:2048
	ds_read_b128 v[196:199], v185 offset:3072
	s_add_u32 s38, s36, 0xfffc0080
	s_addc_u32 s39, s37, -1
	s_cmp_eq_u32 s61, 12
	s_cselect_b32 s41, s27, s39
	s_cselect_b32 s40, s35, s38
	s_cselect_b32 s39, s25, s60
	s_cselect_b32 s38, s58, s59
	v_lshl_add_u64 v[176:177], s[36:37], 0, v[166:167]
	s_add_i32 m0, s45, 0xc000
	ds_read_b128 v[200:203], v186
	ds_read_b128 v[204:207], v186 offset:1024
	ds_read_b128 v[208:211], v186 offset:2048
	ds_read_b128 v[212:215], v186 offset:3072
	ds_read_b128 v[216:219], v186 offset:4096
	ds_read_b128 v[220:223], v186 offset:5120
	ds_read_b128 v[224:227], v186 offset:6144
	ds_read_b128 v[228:231], v186 offset:7168
	global_load_lds_dwordx4 v[176:177], off
	v_lshl_add_u64 v[176:177], s[36:37], 0, v[164:165]
	s_add_i32 m0, s45, 0xe000
	s_nop 0
	global_load_lds_dwordx4 v[176:177], off
	s_waitcnt vmcnt(8)
	s_waitcnt lgkmcnt(0)
	s_barrier
	s_setprio 1
	s_waitcnt lgkmcnt(0)
	v_mfma_f32_16x16x32_bf16 v[126:129], v[130:133], v[200:203], v[126:129]
	v_mfma_f32_16x16x32_bf16 v[122:125], v[138:141], v[200:203], v[122:125]
	v_mfma_f32_16x16x32_bf16 v[110:113], v[130:133], v[208:211], v[110:113]
	v_mfma_f32_16x16x32_bf16 v[106:109], v[138:141], v[208:211], v[106:109]
	v_mfma_f32_16x16x32_bf16 v[94:97], v[130:133], v[216:219], v[94:97]
	v_mfma_f32_16x16x32_bf16 v[90:93], v[138:141], v[216:219], v[90:93]
	v_mfma_f32_16x16x32_bf16 v[78:81], v[130:133], v[224:227], v[78:81]
	v_mfma_f32_16x16x32_bf16 v[74:77], v[138:141], v[224:227], v[74:77]
	v_mfma_f32_16x16x32_bf16 v[126:129], v[134:137], v[204:207], v[126:129]
	v_mfma_f32_16x16x32_bf16 v[122:125], v[142:145], v[204:207], v[122:125]
	v_mfma_f32_16x16x32_bf16 v[110:113], v[134:137], v[212:215], v[110:113]
	v_mfma_f32_16x16x32_bf16 v[106:109], v[142:145], v[212:215], v[106:109]
	v_mfma_f32_16x16x32_bf16 v[94:97], v[134:137], v[220:223], v[94:97]
	v_mfma_f32_16x16x32_bf16 v[90:93], v[142:145], v[220:223], v[90:93]
	v_mfma_f32_16x16x32_bf16 v[78:81], v[134:137], v[228:231], v[78:81]
	v_mfma_f32_16x16x32_bf16 v[74:77], v[142:145], v[228:231], v[74:77]
	v_mfma_f32_16x16x32_bf16 v[118:121], v[146:149], v[200:203], v[118:121]
	v_mfma_f32_16x16x32_bf16 v[114:117], v[172:175], v[200:203], v[114:117]
	v_mfma_f32_16x16x32_bf16 v[102:105], v[146:149], v[208:211], v[102:105]
	v_mfma_f32_16x16x32_bf16 v[98:101], v[172:175], v[208:211], v[98:101]
	v_mfma_f32_16x16x32_bf16 v[86:89], v[146:149], v[216:219], v[86:89]
	v_mfma_f32_16x16x32_bf16 v[82:85], v[172:175], v[216:219], v[82:85]
	v_mfma_f32_16x16x32_bf16 v[70:73], v[146:149], v[224:227], v[70:73]
	v_mfma_f32_16x16x32_bf16 v[66:69], v[172:175], v[224:227], v[66:69]
	v_mfma_f32_16x16x32_bf16 v[118:121], v[150:153], v[204:207], v[118:121]
	v_mfma_f32_16x16x32_bf16 v[114:117], v[196:199], v[204:207], v[114:117]
	v_mfma_f32_16x16x32_bf16 v[102:105], v[150:153], v[212:215], v[102:105]
	v_mfma_f32_16x16x32_bf16 v[98:101], v[196:199], v[212:215], v[98:101]
	v_mfma_f32_16x16x32_bf16 v[86:89], v[150:153], v[220:223], v[86:89]
	v_mfma_f32_16x16x32_bf16 v[82:85], v[196:199], v[220:223], v[82:85]
	v_mfma_f32_16x16x32_bf16 v[70:73], v[150:153], v[228:231], v[70:73]
	v_mfma_f32_16x16x32_bf16 v[66:69], v[196:199], v[228:231], v[66:69]
	s_setprio 0
	s_barrier
	s_add_i32 s62, s55, s44
	v_lshl_add_u64 v[176:177], s[38:39], 0, v[156:157]
	s_mov_b32 m0, s62
	ds_read_b128 v[200:203], v186 offset:16384
	ds_read_b128 v[204:207], v186 offset:17408
	ds_read_b128 v[208:211], v186 offset:18432
	ds_read_b128 v[212:215], v186 offset:19456
	ds_read_b128 v[216:219], v186 offset:20480
	ds_read_b128 v[220:223], v186 offset:21504
	ds_read_b128 v[224:227], v186 offset:22528
	ds_read_b128 v[228:231], v186 offset:23552
	global_load_lds_dwordx4 v[176:177], off
	s_add_i32 m0, s62, 0x2000
	s_add_u32 s62, s38, 0x40000
	v_lshl_add_u64 v[232:233], s[38:39], 0, v[160:161]
	s_addc_u32 s63, s39, 0
	s_add_i32 s64, s56, s44
	global_load_lds_dwordx4 v[232:233], off
	v_lshl_add_u64 v[234:235], s[62:63], 0, v[156:157]
	s_mov_b32 m0, s64
	v_lshl_add_u64 v[236:237], s[40:41], 0, v[158:159]
	global_load_lds_dwordx4 v[234:235], off
	v_lshl_add_u64 v[234:235], s[62:63], 0, v[160:161]
	s_add_i32 m0, s64, 0x2000
	s_nop 0
	global_load_lds_dwordx4 v[234:235], off
	v_lshl_add_u64 v[234:235], s[40:41], 0, v[154:155]
	s_mov_b32 m0, s45
	s_nop 0
	global_load_lds_dwordx4 v[234:235], off
	s_mov_b32 m0, s46
	s_nop 0
	global_load_lds_dwordx4 v[236:237], off
	s_waitcnt vmcnt(8)
	s_waitcnt lgkmcnt(0)
	s_barrier
	s_setprio 1
	s_waitcnt lgkmcnt(0)
	v_mfma_f32_16x16x32_bf16 v[62:65], v[130:133], v[200:203], v[62:65]
	v_mfma_f32_16x16x32_bf16 v[58:61], v[138:141], v[200:203], v[58:61]
	v_mfma_f32_16x16x32_bf16 v[46:49], v[130:133], v[208:211], v[46:49]
	v_mfma_f32_16x16x32_bf16 v[42:45], v[138:141], v[208:211], v[42:45]
	v_mfma_f32_16x16x32_bf16 v[30:33], v[130:133], v[216:219], v[30:33]
	v_mfma_f32_16x16x32_bf16 v[26:29], v[138:141], v[216:219], v[26:29]
	v_mfma_f32_16x16x32_bf16 v[14:17], v[130:133], v[224:227], v[14:17]
	v_mfma_f32_16x16x32_bf16 v[10:13], v[138:141], v[224:227], v[10:13]
	v_mfma_f32_16x16x32_bf16 v[62:65], v[134:137], v[204:207], v[62:65]
	v_mfma_f32_16x16x32_bf16 v[58:61], v[142:145], v[204:207], v[58:61]
	v_mfma_f32_16x16x32_bf16 v[46:49], v[134:137], v[212:215], v[46:49]
	v_mfma_f32_16x16x32_bf16 v[42:45], v[142:145], v[212:215], v[42:45]
	v_mfma_f32_16x16x32_bf16 v[30:33], v[134:137], v[220:223], v[30:33]
	v_mfma_f32_16x16x32_bf16 v[26:29], v[142:145], v[220:223], v[26:29]
	v_mfma_f32_16x16x32_bf16 v[14:17], v[134:137], v[228:231], v[14:17]
	v_mfma_f32_16x16x32_bf16 v[10:13], v[142:145], v[228:231], v[10:13]
	v_mfma_f32_16x16x32_bf16 v[54:57], v[146:149], v[200:203], v[54:57]
	v_mfma_f32_16x16x32_bf16 v[50:53], v[172:175], v[200:203], v[50:53]
	v_mfma_f32_16x16x32_bf16 v[38:41], v[146:149], v[208:211], v[38:41]
	v_mfma_f32_16x16x32_bf16 v[34:37], v[172:175], v[208:211], v[34:37]
	v_mfma_f32_16x16x32_bf16 v[22:25], v[146:149], v[216:219], v[22:25]
	v_mfma_f32_16x16x32_bf16 v[18:21], v[172:175], v[216:219], v[18:21]
	v_mfma_f32_16x16x32_bf16 v[6:9], v[146:149], v[224:227], v[6:9]
	v_mfma_f32_16x16x32_bf16 v[2:5], v[172:175], v[224:227], v[2:5]
	v_mfma_f32_16x16x32_bf16 v[54:57], v[150:153], v[204:207], v[54:57]
	v_mfma_f32_16x16x32_bf16 v[50:53], v[196:199], v[204:207], v[50:53]
	v_mfma_f32_16x16x32_bf16 v[38:41], v[150:153], v[212:215], v[38:41]
	v_mfma_f32_16x16x32_bf16 v[34:37], v[196:199], v[212:215], v[34:37]
	v_mfma_f32_16x16x32_bf16 v[22:25], v[150:153], v[220:223], v[22:25]
	v_mfma_f32_16x16x32_bf16 v[18:21], v[196:199], v[220:223], v[18:21]
	v_mfma_f32_16x16x32_bf16 v[6:9], v[150:153], v[228:231], v[6:9]
	v_mfma_f32_16x16x32_bf16 v[2:5], v[196:199], v[228:231], v[2:5]
	s_setprio 0
	s_barrier
	s_add_i32 s62, 0, 0x18000
	s_add_i32 s63, 0, 0x1c000
	v_add_u32_e32 v142, s62, v182
	v_add_u32_e32 v195, s63, v182
	ds_read_b128 v[130:133], v142
	ds_read_b128 v[134:137], v142 offset:1024
	ds_read_b128 v[138:141], v142 offset:2048
	ds_read_b128 v[142:145], v142 offset:3072
	ds_read_b128 v[146:149], v195
	ds_read_b128 v[150:153], v195 offset:1024
	ds_read_b128 v[172:175], v195 offset:2048
	ds_read_b128 v[196:199], v195 offset:3072
	s_add_u32 s40, s40, 0x40000
	s_addc_u32 s41, s41, 0
	s_mov_b32 m0, s47
	v_lshl_add_u64 v[238:239], s[40:41], 0, v[154:155]
	ds_read_b128 v[200:203], v186 offset:32768
	ds_read_b128 v[204:207], v186 offset:33792
	ds_read_b128 v[208:211], v186 offset:34816
	ds_read_b128 v[212:215], v186 offset:35840
	ds_read_b128 v[216:219], v186 offset:36864
	ds_read_b128 v[220:223], v186 offset:37888
	ds_read_b128 v[224:227], v186 offset:38912
	ds_read_b128 v[228:231], v186 offset:39936
	global_load_lds_dwordx4 v[238:239], off
	v_lshl_add_u64 v[238:239], s[40:41], 0, v[158:159]
	s_mov_b32 m0, s48
	s_nop 0
	global_load_lds_dwordx4 v[238:239], off
	s_waitcnt vmcnt(8)
	s_waitcnt lgkmcnt(0)
	s_barrier
	s_setprio 1
	s_waitcnt lgkmcnt(0)
	v_mfma_f32_16x16x32_bf16 v[126:129], v[130:133], v[200:203], v[126:129]
	v_mfma_f32_16x16x32_bf16 v[122:125], v[138:141], v[200:203], v[122:125]
	v_mfma_f32_16x16x32_bf16 v[110:113], v[130:133], v[208:211], v[110:113]
	v_mfma_f32_16x16x32_bf16 v[106:109], v[138:141], v[208:211], v[106:109]
	v_mfma_f32_16x16x32_bf16 v[94:97], v[130:133], v[216:219], v[94:97]
	v_mfma_f32_16x16x32_bf16 v[90:93], v[138:141], v[216:219], v[90:93]
	v_mfma_f32_16x16x32_bf16 v[78:81], v[130:133], v[224:227], v[78:81]
	v_mfma_f32_16x16x32_bf16 v[74:77], v[138:141], v[224:227], v[74:77]
	v_mfma_f32_16x16x32_bf16 v[126:129], v[134:137], v[204:207], v[126:129]
	v_mfma_f32_16x16x32_bf16 v[122:125], v[142:145], v[204:207], v[122:125]
	v_mfma_f32_16x16x32_bf16 v[110:113], v[134:137], v[212:215], v[110:113]
	v_mfma_f32_16x16x32_bf16 v[106:109], v[142:145], v[212:215], v[106:109]
	v_mfma_f32_16x16x32_bf16 v[94:97], v[134:137], v[220:223], v[94:97]
	v_mfma_f32_16x16x32_bf16 v[90:93], v[142:145], v[220:223], v[90:93]
	v_mfma_f32_16x16x32_bf16 v[78:81], v[134:137], v[228:231], v[78:81]
	v_mfma_f32_16x16x32_bf16 v[74:77], v[142:145], v[228:231], v[74:77]
	v_mfma_f32_16x16x32_bf16 v[118:121], v[146:149], v[200:203], v[118:121]
	v_mfma_f32_16x16x32_bf16 v[114:117], v[172:175], v[200:203], v[114:117]
	v_mfma_f32_16x16x32_bf16 v[102:105], v[146:149], v[208:211], v[102:105]
	v_mfma_f32_16x16x32_bf16 v[98:101], v[172:175], v[208:211], v[98:101]
	v_mfma_f32_16x16x32_bf16 v[86:89], v[146:149], v[216:219], v[86:89]
	v_mfma_f32_16x16x32_bf16 v[82:85], v[172:175], v[216:219], v[82:85]
	v_mfma_f32_16x16x32_bf16 v[70:73], v[146:149], v[224:227], v[70:73]
	v_mfma_f32_16x16x32_bf16 v[66:69], v[172:175], v[224:227], v[66:69]
	v_mfma_f32_16x16x32_bf16 v[118:121], v[150:153], v[204:207], v[118:121]
	v_mfma_f32_16x16x32_bf16 v[114:117], v[196:199], v[204:207], v[114:117]
	v_mfma_f32_16x16x32_bf16 v[102:105], v[150:153], v[212:215], v[102:105]
	v_mfma_f32_16x16x32_bf16 v[98:101], v[196:199], v[212:215], v[98:101]
	v_mfma_f32_16x16x32_bf16 v[86:89], v[150:153], v[220:223], v[86:89]
	v_mfma_f32_16x16x32_bf16 v[82:85], v[196:199], v[220:223], v[82:85]
	v_mfma_f32_16x16x32_bf16 v[70:73], v[150:153], v[228:231], v[70:73]
	v_mfma_f32_16x16x32_bf16 v[66:69], v[196:199], v[228:231], v[66:69]
	s_setprio 0
	s_barrier
	s_add_i32 s40, s62, s44
	v_lshl_add_u64 v[176:177], v[176:177], 0, s[18:19]
	s_mov_b32 m0, s40
	ds_read_b128 v[200:203], v186 offset:49152
	ds_read_b128 v[204:207], v186 offset:50176
	ds_read_b128 v[208:211], v186 offset:51200
	ds_read_b128 v[212:215], v186 offset:52224
	ds_read_b128 v[216:219], v186 offset:53248
	ds_read_b128 v[220:223], v186 offset:54272
	ds_read_b128 v[224:227], v186 offset:55296
	ds_read_b128 v[228:231], v186 offset:56320
	global_load_lds_dwordx4 v[176:177], off
	s_add_i32 m0, s40, 0x2000
	s_add_u32 s38, s38, 0x40080
	v_lshl_add_u64 v[176:177], v[232:233], 0, s[18:19]
	s_addc_u32 s39, s39, 0
	s_add_i32 s40, s63, s44
	global_load_lds_dwordx4 v[176:177], off
	v_lshl_add_u64 v[176:177], s[38:39], 0, v[156:157]
	s_mov_b32 m0, s40
	s_nop 0
	global_load_lds_dwordx4 v[176:177], off
	v_lshl_add_u64 v[176:177], s[38:39], 0, v[160:161]
	s_add_i32 m0, s40, 0x2000
	s_nop 0
	global_load_lds_dwordx4 v[176:177], off
	v_lshl_add_u64 v[176:177], v[234:235], 0, s[18:19]
	s_mov_b32 m0, s33
	s_nop 0
	global_load_lds_dwordx4 v[176:177], off
	v_lshl_add_u64 v[176:177], v[236:237], 0, s[18:19]
	s_mov_b32 m0, s51
	s_nop 0
	global_load_lds_dwordx4 v[176:177], off
	s_waitcnt vmcnt(8)
	s_waitcnt lgkmcnt(0)
	s_barrier
	s_setprio 1
	s_waitcnt lgkmcnt(0)
	v_mfma_f32_16x16x32_bf16 v[62:65], v[130:133], v[200:203], v[62:65]
	v_mfma_f32_16x16x32_bf16 v[58:61], v[138:141], v[200:203], v[58:61]
	v_mfma_f32_16x16x32_bf16 v[46:49], v[130:133], v[208:211], v[46:49]
	v_mfma_f32_16x16x32_bf16 v[42:45], v[138:141], v[208:211], v[42:45]
	v_mfma_f32_16x16x32_bf16 v[30:33], v[130:133], v[216:219], v[30:33]
	v_mfma_f32_16x16x32_bf16 v[26:29], v[138:141], v[216:219], v[26:29]
	v_mfma_f32_16x16x32_bf16 v[14:17], v[130:133], v[224:227], v[14:17]
	v_mfma_f32_16x16x32_bf16 v[10:13], v[138:141], v[224:227], v[10:13]
	v_mfma_f32_16x16x32_bf16 v[62:65], v[134:137], v[204:207], v[62:65]
	v_mfma_f32_16x16x32_bf16 v[58:61], v[142:145], v[204:207], v[58:61]
	v_mfma_f32_16x16x32_bf16 v[46:49], v[134:137], v[212:215], v[46:49]
	v_mfma_f32_16x16x32_bf16 v[42:45], v[142:145], v[212:215], v[42:45]
	v_mfma_f32_16x16x32_bf16 v[30:33], v[134:137], v[220:223], v[30:33]
	v_mfma_f32_16x16x32_bf16 v[26:29], v[142:145], v[220:223], v[26:29]
	v_mfma_f32_16x16x32_bf16 v[14:17], v[134:137], v[228:231], v[14:17]
	v_mfma_f32_16x16x32_bf16 v[10:13], v[142:145], v[228:231], v[10:13]
	v_mfma_f32_16x16x32_bf16 v[54:57], v[146:149], v[200:203], v[54:57]
	v_mfma_f32_16x16x32_bf16 v[50:53], v[172:175], v[200:203], v[50:53]
	v_mfma_f32_16x16x32_bf16 v[38:41], v[146:149], v[208:211], v[38:41]
	v_mfma_f32_16x16x32_bf16 v[34:37], v[172:175], v[208:211], v[34:37]
	v_mfma_f32_16x16x32_bf16 v[22:25], v[146:149], v[216:219], v[22:25]
	v_mfma_f32_16x16x32_bf16 v[18:21], v[172:175], v[216:219], v[18:21]
	v_mfma_f32_16x16x32_bf16 v[6:9], v[146:149], v[224:227], v[6:9]
	v_mfma_f32_16x16x32_bf16 v[2:5], v[172:175], v[224:227], v[2:5]
	v_mfma_f32_16x16x32_bf16 v[54:57], v[150:153], v[204:207], v[54:57]
	v_mfma_f32_16x16x32_bf16 v[50:53], v[196:199], v[204:207], v[50:53]
	v_mfma_f32_16x16x32_bf16 v[38:41], v[150:153], v[212:215], v[38:41]
	v_mfma_f32_16x16x32_bf16 v[34:37], v[196:199], v[212:215], v[34:37]
	v_mfma_f32_16x16x32_bf16 v[22:25], v[150:153], v[220:223], v[22:25]
	v_mfma_f32_16x16x32_bf16 v[18:21], v[196:199], v[220:223], v[18:21]
	v_mfma_f32_16x16x32_bf16 v[6:9], v[150:153], v[228:231], v[6:9]
	v_mfma_f32_16x16x32_bf16 v[2:5], v[196:199], v[228:231], v[2:5]
	s_setprio 0
	s_barrier
	s_add_i32 s61, s61, 2
	s_add_u32 s59, s59, 0x100
	s_addc_u32 s60, s60, 0
	s_add_u32 s36, s36, 0x100
	s_addc_u32 s37, s37, 0
	s_cmp_gt_u32 s61, 13
	s_cbranch_scc0 .LBB0_1308
	s_and_b64 vcc, exec, s[20:21]
	s_cbranch_vccz .LBB0_1311
	s_barrier

.LBB0_1477:
	ds_read_b128 v[82:85], v180
	ds_read_b128 v[86:89], v180 offset:1024
	ds_read_b128 v[90:93], v180 offset:2048
	ds_read_b128 v[94:97], v180 offset:3072
	ds_read_b128 v[168:171], v181
	ds_read_b128 v[192:195], v181 offset:1024
	ds_read_b128 v[196:199], v181 offset:2048
	ds_read_b128 v[200:203], v181 offset:3072
	s_add_u32 s8, s6, 0xfffc0080
	s_addc_u32 s9, s7, -1
	s_cmp_eq_u32 s61, 12
	s_cselect_b32 s37, s25, s9
	s_cselect_b32 s36, s57, s8
	s_cselect_b32 s9, s23, s60
	s_cselect_b32 s8, s58, s59
	v_lshl_add_u64 v[172:173], s[6:7], 0, v[160:161]
	s_add_i32 m0, s31, 0xc000
	ds_read_b128 v[204:207], v182
	ds_read_b128 v[208:211], v182 offset:1024
	ds_read_b128 v[212:215], v182 offset:2048
	ds_read_b128 v[216:219], v182 offset:3072
	ds_read_b128 v[220:223], v182 offset:4096
	ds_read_b128 v[224:227], v182 offset:5120
	ds_read_b128 v[228:231], v182 offset:6144
	ds_read_b128 v[232:235], v182 offset:7168
	global_load_lds_dwordx4 v[172:173], off
	v_lshl_add_u64 v[172:173], s[6:7], 0, v[158:159]
	s_add_i32 m0, s31, 0xe000
	s_nop 0
	global_load_lds_dwordx4 v[172:173], off
	s_waitcnt vmcnt(8)
	s_waitcnt lgkmcnt(0)
	s_barrier
	s_setprio 1
	s_waitcnt lgkmcnt(0)
	v_mfma_f32_16x16x32_bf16 v[142:145], v[82:85], v[204:207], v[142:145]
	v_mfma_f32_16x16x32_bf16 v[138:141], v[90:93], v[204:207], v[138:141]
	v_mfma_f32_16x16x32_bf16 v[126:129], v[82:85], v[212:215], v[126:129]
	v_mfma_f32_16x16x32_bf16 v[122:125], v[90:93], v[212:215], v[122:125]
	v_mfma_f32_16x16x32_bf16 v[110:113], v[82:85], v[220:223], v[110:113]
	v_mfma_f32_16x16x32_bf16 v[106:109], v[90:93], v[220:223], v[106:109]
	v_mfma_f32_16x16x32_bf16 v[78:81], v[82:85], v[228:231], v[78:81]
	v_mfma_f32_16x16x32_bf16 v[74:77], v[90:93], v[228:231], v[74:77]
	v_mfma_f32_16x16x32_bf16 v[142:145], v[86:89], v[208:211], v[142:145]
	v_mfma_f32_16x16x32_bf16 v[138:141], v[94:97], v[208:211], v[138:141]
	v_mfma_f32_16x16x32_bf16 v[126:129], v[86:89], v[216:219], v[126:129]
	v_mfma_f32_16x16x32_bf16 v[122:125], v[94:97], v[216:219], v[122:125]
	v_mfma_f32_16x16x32_bf16 v[110:113], v[86:89], v[224:227], v[110:113]
	v_mfma_f32_16x16x32_bf16 v[106:109], v[94:97], v[224:227], v[106:109]
	v_mfma_f32_16x16x32_bf16 v[78:81], v[86:89], v[232:235], v[78:81]
	v_mfma_f32_16x16x32_bf16 v[74:77], v[94:97], v[232:235], v[74:77]
	v_mfma_f32_16x16x32_bf16 v[134:137], v[168:171], v[204:207], v[134:137]
	v_mfma_f32_16x16x32_bf16 v[130:133], v[196:199], v[204:207], v[130:133]
	v_mfma_f32_16x16x32_bf16 v[118:121], v[168:171], v[212:215], v[118:121]
	v_mfma_f32_16x16x32_bf16 v[114:117], v[196:199], v[212:215], v[114:117]
	v_mfma_f32_16x16x32_bf16 v[102:105], v[168:171], v[220:223], v[102:105]
	v_mfma_f32_16x16x32_bf16 v[98:101], v[196:199], v[220:223], v[98:101]
	v_mfma_f32_16x16x32_bf16 v[70:73], v[168:171], v[228:231], v[70:73]
	v_mfma_f32_16x16x32_bf16 v[66:69], v[196:199], v[228:231], v[66:69]
	v_mfma_f32_16x16x32_bf16 v[134:137], v[192:195], v[208:211], v[134:137]
	v_mfma_f32_16x16x32_bf16 v[130:133], v[200:203], v[208:211], v[130:133]
	v_mfma_f32_16x16x32_bf16 v[118:121], v[192:195], v[216:219], v[118:121]
	v_mfma_f32_16x16x32_bf16 v[114:117], v[200:203], v[216:219], v[114:117]
	v_mfma_f32_16x16x32_bf16 v[102:105], v[192:195], v[224:227], v[102:105]
	v_mfma_f32_16x16x32_bf16 v[98:101], v[200:203], v[224:227], v[98:101]
	v_mfma_f32_16x16x32_bf16 v[70:73], v[192:195], v[232:235], v[70:73]
	v_mfma_f32_16x16x32_bf16 v[66:69], v[200:203], v[232:235], v[66:69]
	s_setprio 0
	s_barrier
	s_add_i32 s62, s54, s41
	v_lshl_add_u64 v[172:173], s[8:9], 0, v[148:149]
	s_mov_b32 m0, s62
	ds_read_b128 v[204:207], v182 offset:16384
	ds_read_b128 v[208:211], v182 offset:17408
	ds_read_b128 v[212:215], v182 offset:18432
	ds_read_b128 v[216:219], v182 offset:19456
	ds_read_b128 v[220:223], v182 offset:20480
	ds_read_b128 v[224:227], v182 offset:21504
	ds_read_b128 v[228:231], v182 offset:22528
	ds_read_b128 v[232:235], v182 offset:23552
	global_load_lds_dwordx4 v[172:173], off
	s_add_i32 m0, s62, 0x2000
	s_add_u32 s62, s8, 0x40000
	v_lshl_add_u64 v[236:237], s[8:9], 0, v[152:153]
	s_addc_u32 s63, s9, 0
	s_add_i32 s64, s55, s41
	global_load_lds_dwordx4 v[236:237], off
	v_lshl_add_u64 v[238:239], s[62:63], 0, v[148:149]
	s_mov_b32 m0, s64
	v_lshl_add_u64 v[240:241], s[36:37], 0, v[150:151]
	global_load_lds_dwordx4 v[238:239], off
	v_lshl_add_u64 v[238:239], s[62:63], 0, v[152:153]
	s_add_i32 m0, s64, 0x2000
	s_nop 0
	global_load_lds_dwordx4 v[238:239], off
	v_lshl_add_u64 v[238:239], s[36:37], 0, v[146:147]
	s_mov_b32 m0, s31
	s_nop 0
	global_load_lds_dwordx4 v[238:239], off
	s_mov_b32 m0, s35
	s_nop 0
	global_load_lds_dwordx4 v[240:241], off
	s_waitcnt vmcnt(8)
	s_waitcnt lgkmcnt(0)
	s_barrier
	s_setprio 1
	s_waitcnt lgkmcnt(0)
	v_mfma_f32_16x16x32_bf16 v[62:65], v[82:85], v[204:207], v[62:65]
	v_mfma_f32_16x16x32_bf16 v[58:61], v[90:93], v[204:207], v[58:61]
	v_mfma_f32_16x16x32_bf16 v[46:49], v[82:85], v[212:215], v[46:49]
	v_mfma_f32_16x16x32_bf16 v[42:45], v[90:93], v[212:215], v[42:45]
	v_mfma_f32_16x16x32_bf16 v[30:33], v[82:85], v[220:223], v[30:33]
	v_mfma_f32_16x16x32_bf16 v[26:29], v[90:93], v[220:223], v[26:29]
	v_mfma_f32_16x16x32_bf16 v[14:17], v[82:85], v[228:231], v[14:17]
	v_mfma_f32_16x16x32_bf16 v[10:13], v[90:93], v[228:231], v[10:13]
	v_mfma_f32_16x16x32_bf16 v[62:65], v[86:89], v[208:211], v[62:65]
	v_mfma_f32_16x16x32_bf16 v[58:61], v[94:97], v[208:211], v[58:61]
	v_mfma_f32_16x16x32_bf16 v[46:49], v[86:89], v[216:219], v[46:49]
	v_mfma_f32_16x16x32_bf16 v[42:45], v[94:97], v[216:219], v[42:45]
	v_mfma_f32_16x16x32_bf16 v[30:33], v[86:89], v[224:227], v[30:33]
	v_mfma_f32_16x16x32_bf16 v[26:29], v[94:97], v[224:227], v[26:29]
	v_mfma_f32_16x16x32_bf16 v[14:17], v[86:89], v[232:235], v[14:17]
	v_mfma_f32_16x16x32_bf16 v[10:13], v[94:97], v[232:235], v[10:13]
	v_mfma_f32_16x16x32_bf16 v[54:57], v[168:171], v[204:207], v[54:57]
	v_mfma_f32_16x16x32_bf16 v[50:53], v[196:199], v[204:207], v[50:53]
	v_mfma_f32_16x16x32_bf16 v[38:41], v[168:171], v[212:215], v[38:41]
	v_mfma_f32_16x16x32_bf16 v[34:37], v[196:199], v[212:215], v[34:37]
	v_mfma_f32_16x16x32_bf16 v[22:25], v[168:171], v[220:223], v[22:25]
	v_mfma_f32_16x16x32_bf16 v[18:21], v[196:199], v[220:223], v[18:21]
	v_mfma_f32_16x16x32_bf16 v[6:9], v[168:171], v[228:231], v[6:9]
	v_mfma_f32_16x16x32_bf16 v[2:5], v[196:199], v[228:231], v[2:5]
	v_mfma_f32_16x16x32_bf16 v[54:57], v[192:195], v[208:211], v[54:57]
	v_mfma_f32_16x16x32_bf16 v[50:53], v[200:203], v[208:211], v[50:53]
	v_mfma_f32_16x16x32_bf16 v[38:41], v[192:195], v[216:219], v[38:41]
	v_mfma_f32_16x16x32_bf16 v[34:37], v[200:203], v[216:219], v[34:37]
	v_mfma_f32_16x16x32_bf16 v[22:25], v[192:195], v[224:227], v[22:25]
	v_mfma_f32_16x16x32_bf16 v[18:21], v[200:203], v[224:227], v[18:21]
	v_mfma_f32_16x16x32_bf16 v[6:9], v[192:195], v[232:235], v[6:9]
	v_mfma_f32_16x16x32_bf16 v[2:5], v[200:203], v[232:235], v[2:5]
	s_setprio 0
	s_barrier
	s_add_i32 s62, 0, 0x18000
	s_add_i32 s63, 0, 0x1c000
	v_add_u32_e32 v94, s62, v177
	v_add_u32_e32 v166, s63, v177
	ds_read_b128 v[82:85], v94
	ds_read_b128 v[86:89], v94 offset:1024
	ds_read_b128 v[90:93], v94 offset:2048
	ds_read_b128 v[94:97], v94 offset:3072
	ds_read_b128 v[168:171], v166
	ds_read_b128 v[192:195], v166 offset:1024
	ds_read_b128 v[196:199], v166 offset:2048
	ds_read_b128 v[200:203], v166 offset:3072
	s_add_u32 s36, s36, 0x40000
	s_addc_u32 s37, s37, 0
	s_mov_b32 m0, s42
	v_lshl_add_u64 v[242:243], s[36:37], 0, v[146:147]
	ds_read_b128 v[204:207], v182 offset:32768
	ds_read_b128 v[208:211], v182 offset:33792
	ds_read_b128 v[212:215], v182 offset:34816
	ds_read_b128 v[216:219], v182 offset:35840
	ds_read_b128 v[220:223], v182 offset:36864
	ds_read_b128 v[224:227], v182 offset:37888
	ds_read_b128 v[228:231], v182 offset:38912
	ds_read_b128 v[232:235], v182 offset:39936
	global_load_lds_dwordx4 v[242:243], off
	v_lshl_add_u64 v[242:243], s[36:37], 0, v[150:151]
	s_mov_b32 m0, s43
	s_nop 0
	global_load_lds_dwordx4 v[242:243], off
	s_waitcnt vmcnt(8)
	s_waitcnt lgkmcnt(0)
	s_barrier
	s_setprio 1
	s_waitcnt lgkmcnt(0)
	v_mfma_f32_16x16x32_bf16 v[142:145], v[82:85], v[204:207], v[142:145]
	v_mfma_f32_16x16x32_bf16 v[138:141], v[90:93], v[204:207], v[138:141]
	v_mfma_f32_16x16x32_bf16 v[126:129], v[82:85], v[212:215], v[126:129]
	v_mfma_f32_16x16x32_bf16 v[122:125], v[90:93], v[212:215], v[122:125]
	v_mfma_f32_16x16x32_bf16 v[110:113], v[82:85], v[220:223], v[110:113]
	v_mfma_f32_16x16x32_bf16 v[106:109], v[90:93], v[220:223], v[106:109]
	v_mfma_f32_16x16x32_bf16 v[78:81], v[82:85], v[228:231], v[78:81]
	v_mfma_f32_16x16x32_bf16 v[74:77], v[90:93], v[228:231], v[74:77]
	v_mfma_f32_16x16x32_bf16 v[142:145], v[86:89], v[208:211], v[142:145]
	v_mfma_f32_16x16x32_bf16 v[138:141], v[94:97], v[208:211], v[138:141]
	v_mfma_f32_16x16x32_bf16 v[126:129], v[86:89], v[216:219], v[126:129]
	v_mfma_f32_16x16x32_bf16 v[122:125], v[94:97], v[216:219], v[122:125]
	v_mfma_f32_16x16x32_bf16 v[110:113], v[86:89], v[224:227], v[110:113]
	v_mfma_f32_16x16x32_bf16 v[106:109], v[94:97], v[224:227], v[106:109]
	v_mfma_f32_16x16x32_bf16 v[78:81], v[86:89], v[232:235], v[78:81]
	v_mfma_f32_16x16x32_bf16 v[74:77], v[94:97], v[232:235], v[74:77]
	v_mfma_f32_16x16x32_bf16 v[134:137], v[168:171], v[204:207], v[134:137]
	v_mfma_f32_16x16x32_bf16 v[130:133], v[196:199], v[204:207], v[130:133]
	v_mfma_f32_16x16x32_bf16 v[118:121], v[168:171], v[212:215], v[118:121]
	v_mfma_f32_16x16x32_bf16 v[114:117], v[196:199], v[212:215], v[114:117]
	v_mfma_f32_16x16x32_bf16 v[102:105], v[168:171], v[220:223], v[102:105]
	v_mfma_f32_16x16x32_bf16 v[98:101], v[196:199], v[220:223], v[98:101]
	v_mfma_f32_16x16x32_bf16 v[70:73], v[168:171], v[228:231], v[70:73]
	v_mfma_f32_16x16x32_bf16 v[66:69], v[196:199], v[228:231], v[66:69]
	v_mfma_f32_16x16x32_bf16 v[134:137], v[192:195], v[208:211], v[134:137]
	v_mfma_f32_16x16x32_bf16 v[130:133], v[200:203], v[208:211], v[130:133]
	v_mfma_f32_16x16x32_bf16 v[118:121], v[192:195], v[216:219], v[118:121]
	v_mfma_f32_16x16x32_bf16 v[114:117], v[200:203], v[216:219], v[114:117]
	v_mfma_f32_16x16x32_bf16 v[102:105], v[192:195], v[224:227], v[102:105]
	v_mfma_f32_16x16x32_bf16 v[98:101], v[200:203], v[224:227], v[98:101]
	v_mfma_f32_16x16x32_bf16 v[70:73], v[192:195], v[232:235], v[70:73]
	v_mfma_f32_16x16x32_bf16 v[66:69], v[200:203], v[232:235], v[66:69]
	s_setprio 0
	s_barrier
	s_add_i32 s36, s62, s41
	v_lshl_add_u64 v[172:173], v[172:173], 0, s[12:13]
	s_mov_b32 m0, s36
	ds_read_b128 v[204:207], v182 offset:49152
	ds_read_b128 v[208:211], v182 offset:50176
	ds_read_b128 v[212:215], v182 offset:51200
	ds_read_b128 v[216:219], v182 offset:52224
	ds_read_b128 v[220:223], v182 offset:53248
	ds_read_b128 v[224:227], v182 offset:54272
	ds_read_b128 v[228:231], v182 offset:55296
	ds_read_b128 v[232:235], v182 offset:56320
	global_load_lds_dwordx4 v[172:173], off
	s_add_i32 m0, s36, 0x2000
	s_add_u32 s8, s8, 0x40080
	v_lshl_add_u64 v[172:173], v[236:237], 0, s[12:13]
	s_addc_u32 s9, s9, 0
	s_add_i32 s36, s63, s41
	global_load_lds_dwordx4 v[172:173], off
	v_lshl_add_u64 v[172:173], s[8:9], 0, v[148:149]
	s_mov_b32 m0, s36
	s_nop 0
	global_load_lds_dwordx4 v[172:173], off
	v_lshl_add_u64 v[172:173], s[8:9], 0, v[152:153]
	s_add_i32 m0, s36, 0x2000
	s_nop 0
	global_load_lds_dwordx4 v[172:173], off
	v_lshl_add_u64 v[172:173], v[238:239], 0, s[12:13]
	s_mov_b32 m0, s48
	s_nop 0
	global_load_lds_dwordx4 v[172:173], off
	v_lshl_add_u64 v[172:173], v[240:241], 0, s[12:13]
	s_mov_b32 m0, s49
	s_nop 0
	global_load_lds_dwordx4 v[172:173], off
	s_waitcnt vmcnt(8)
	s_waitcnt lgkmcnt(0)
	s_barrier
	s_setprio 1
	s_waitcnt lgkmcnt(0)
	v_mfma_f32_16x16x32_bf16 v[62:65], v[82:85], v[204:207], v[62:65]
	v_mfma_f32_16x16x32_bf16 v[58:61], v[90:93], v[204:207], v[58:61]
	v_mfma_f32_16x16x32_bf16 v[46:49], v[82:85], v[212:215], v[46:49]
	v_mfma_f32_16x16x32_bf16 v[42:45], v[90:93], v[212:215], v[42:45]
	v_mfma_f32_16x16x32_bf16 v[30:33], v[82:85], v[220:223], v[30:33]
	v_mfma_f32_16x16x32_bf16 v[26:29], v[90:93], v[220:223], v[26:29]
	v_mfma_f32_16x16x32_bf16 v[14:17], v[82:85], v[228:231], v[14:17]
	v_mfma_f32_16x16x32_bf16 v[10:13], v[90:93], v[228:231], v[10:13]
	v_mfma_f32_16x16x32_bf16 v[62:65], v[86:89], v[208:211], v[62:65]
	v_mfma_f32_16x16x32_bf16 v[58:61], v[94:97], v[208:211], v[58:61]
	v_mfma_f32_16x16x32_bf16 v[46:49], v[86:89], v[216:219], v[46:49]
	v_mfma_f32_16x16x32_bf16 v[42:45], v[94:97], v[216:219], v[42:45]
	v_mfma_f32_16x16x32_bf16 v[30:33], v[86:89], v[224:227], v[30:33]
	v_mfma_f32_16x16x32_bf16 v[26:29], v[94:97], v[224:227], v[26:29]
	v_mfma_f32_16x16x32_bf16 v[14:17], v[86:89], v[232:235], v[14:17]
	v_mfma_f32_16x16x32_bf16 v[10:13], v[94:97], v[232:235], v[10:13]
	v_mfma_f32_16x16x32_bf16 v[54:57], v[168:171], v[204:207], v[54:57]
	v_mfma_f32_16x16x32_bf16 v[50:53], v[196:199], v[204:207], v[50:53]
	v_mfma_f32_16x16x32_bf16 v[38:41], v[168:171], v[212:215], v[38:41]
	v_mfma_f32_16x16x32_bf16 v[34:37], v[196:199], v[212:215], v[34:37]
	v_mfma_f32_16x16x32_bf16 v[22:25], v[168:171], v[220:223], v[22:25]
	v_mfma_f32_16x16x32_bf16 v[18:21], v[196:199], v[220:223], v[18:21]
	v_mfma_f32_16x16x32_bf16 v[6:9], v[168:171], v[228:231], v[6:9]
	v_mfma_f32_16x16x32_bf16 v[2:5], v[196:199], v[228:231], v[2:5]
	v_mfma_f32_16x16x32_bf16 v[54:57], v[192:195], v[208:211], v[54:57]
	v_mfma_f32_16x16x32_bf16 v[50:53], v[200:203], v[208:211], v[50:53]
	v_mfma_f32_16x16x32_bf16 v[38:41], v[192:195], v[216:219], v[38:41]
	v_mfma_f32_16x16x32_bf16 v[34:37], v[200:203], v[216:219], v[34:37]
	v_mfma_f32_16x16x32_bf16 v[22:25], v[192:195], v[224:227], v[22:25]
	v_mfma_f32_16x16x32_bf16 v[18:21], v[200:203], v[224:227], v[18:21]
	v_mfma_f32_16x16x32_bf16 v[6:9], v[192:195], v[232:235], v[6:9]
	v_mfma_f32_16x16x32_bf16 v[2:5], v[200:203], v[232:235], v[2:5]
	s_setprio 0
	s_barrier
	s_add_i32 s61, s61, 2
	s_add_u32 s59, s59, 0x100
	s_addc_u32 s60, s60, 0
	s_add_u32 s6, s6, 0x100
	s_addc_u32 s7, s7, 0
	s_cmp_gt_u32 s61, 13
	s_cbranch_scc0 .LBB0_1477
	s_andn2_b64 vcc, exec, s[2:3]
	s_cbranch_vccnz .Lrs8h_skip2
	v_lshl_add_u32 v204, s24, 8, v176
	v_ashrrev_i32_e32 v205, 31, v204
	v_lshlrev_b64 v[196:197], 6, v[204:205]
	v_lshl_add_u64 v[212:213], v[156:157], 0, v[196:197]
	v_or_b32_e32 v196, 16, v204
	v_or_b32_e32 v206, 32, v204
	v_or_b32_e32 v204, 48, v204
	v_ashrrev_i32_e32 v197, 31, v196
	v_ashrrev_i32_e32 v207, 31, v206
	v_ashrrev_i32_e32 v205, 31, v204
	v_lshlrev_b64 v[196:197], 6, v[196:197]
	v_lshlrev_b64 v[206:207], 6, v[206:207]
	v_lshlrev_b64 v[204:205], 6, v[204:205]
	v_add_co_u32_e32 v224, vcc, s44, v212
	v_lshl_add_u64 v[200:201], v[156:157], 0, v[196:197]
	v_lshl_add_u64 v[206:207], v[156:157], 0, v[206:207]
	v_lshl_add_u64 v[208:209], v[156:157], 0, v[204:205]
	v_addc_co_u32_e32 v225, vcc, 0, v213, vcc
	flat_load_dwordx4 v[196:199], v[212:213]
	s_nop 0
	flat_load_dwordx4 v[200:203], v[200:201]
	s_nop 0
	flat_load_dwordx4 v[204:207], v[206:207]
	s_nop 0
	flat_load_dwordx4 v[208:211], v[208:209]
	s_nop 0
	flat_load_dwordx4 v[212:215], v[224:225]
	flat_load_dwordx4 v[216:219], v[224:225] offset:1024
	flat_load_dwordx4 v[220:223], v[224:225] offset:2048
	s_nop 0
	flat_load_dwordx4 v[224:227], v[224:225] offset:3072

.LBB0_1817:
	v_add_u32_e32 v154, s64, v156
	ds_read_b128 v[130:133], v154
	ds_read_b128 v[150:153], v154 offset:1024
	ds_read_b128 v[160:163], v154 offset:2048
	ds_read_b128 v[164:167], v154 offset:3072
	v_add_u32_e32 v154, s65, v156
	ds_read_b128 v[168:171], v154
	ds_read_b128 v[172:175], v154 offset:1024
	ds_read_b128 v[180:183], v154 offset:2048
	ds_read_b128 v[184:187], v154 offset:3072
	s_add_u32 s44, s42, 0xfffc0080
	s_addc_u32 s45, s43, -1
	s_cmp_eq_u32 s70, 12
	s_cselect_b32 s47, s35, s45
	s_cselect_b32 s46, s41, s44
	s_cselect_b32 s45, s31, s69
	s_cselect_b32 s44, s67, s68
	v_lshl_add_u64 v[154:155], s[42:43], 0, v[144:145]
	s_add_i32 m0, s53, 0xc000
	ds_read_b128 v[188:191], v158
	ds_read_b128 v[192:195], v158 offset:1024
	ds_read_b128 v[196:199], v158 offset:2048
	ds_read_b128 v[200:203], v158 offset:3072
	ds_read_b128 v[204:207], v158 offset:4096
	ds_read_b128 v[208:211], v158 offset:5120
	ds_read_b128 v[212:215], v158 offset:6144
	ds_read_b128 v[216:219], v158 offset:7168
	global_load_lds_dwordx4 v[154:155], off
	v_lshl_add_u64 v[154:155], s[42:43], 0, v[142:143]
	s_add_i32 m0, s53, 0xe000
	s_nop 0
	global_load_lds_dwordx4 v[154:155], off
	s_waitcnt vmcnt(8)
	s_waitcnt lgkmcnt(0)
	s_barrier
	s_setprio 1
	s_waitcnt lgkmcnt(0)
	v_mfma_f32_16x16x32_bf16 v[114:117], v[130:133], v[188:191], v[114:117]
	v_mfma_f32_16x16x32_bf16 v[118:121], v[160:163], v[188:191], v[118:121]
	v_mfma_f32_16x16x32_bf16 v[98:101], v[130:133], v[196:199], v[98:101]
	v_mfma_f32_16x16x32_bf16 v[102:105], v[160:163], v[196:199], v[102:105]
	v_mfma_f32_16x16x32_bf16 v[82:85], v[130:133], v[204:207], v[82:85]
	v_mfma_f32_16x16x32_bf16 v[86:89], v[160:163], v[204:207], v[86:89]
	v_mfma_f32_16x16x32_bf16 v[66:69], v[130:133], v[212:215], v[66:69]
	v_mfma_f32_16x16x32_bf16 v[70:73], v[160:163], v[212:215], v[70:73]
	v_mfma_f32_16x16x32_bf16 v[114:117], v[150:153], v[192:195], v[114:117]
	v_mfma_f32_16x16x32_bf16 v[118:121], v[164:167], v[192:195], v[118:121]
	v_mfma_f32_16x16x32_bf16 v[98:101], v[150:153], v[200:203], v[98:101]
	v_mfma_f32_16x16x32_bf16 v[102:105], v[164:167], v[200:203], v[102:105]
	v_mfma_f32_16x16x32_bf16 v[82:85], v[150:153], v[208:211], v[82:85]
	v_mfma_f32_16x16x32_bf16 v[86:89], v[164:167], v[208:211], v[86:89]
	v_mfma_f32_16x16x32_bf16 v[66:69], v[150:153], v[216:219], v[66:69]
	v_mfma_f32_16x16x32_bf16 v[70:73], v[164:167], v[216:219], v[70:73]
	v_mfma_f32_16x16x32_bf16 v[122:125], v[168:171], v[188:191], v[122:125]
	v_mfma_f32_16x16x32_bf16 v[126:129], v[180:183], v[188:191], v[126:129]
	v_mfma_f32_16x16x32_bf16 v[106:109], v[168:171], v[196:199], v[106:109]
	v_mfma_f32_16x16x32_bf16 v[110:113], v[180:183], v[196:199], v[110:113]
	v_mfma_f32_16x16x32_bf16 v[90:93], v[168:171], v[204:207], v[90:93]
	v_mfma_f32_16x16x32_bf16 v[94:97], v[180:183], v[204:207], v[94:97]
	v_mfma_f32_16x16x32_bf16 v[74:77], v[168:171], v[212:215], v[74:77]
	v_mfma_f32_16x16x32_bf16 v[78:81], v[180:183], v[212:215], v[78:81]
	v_mfma_f32_16x16x32_bf16 v[122:125], v[172:175], v[192:195], v[122:125]
	v_mfma_f32_16x16x32_bf16 v[126:129], v[184:187], v[192:195], v[126:129]
	v_mfma_f32_16x16x32_bf16 v[106:109], v[172:175], v[200:203], v[106:109]
	v_mfma_f32_16x16x32_bf16 v[110:113], v[184:187], v[200:203], v[110:113]
	v_mfma_f32_16x16x32_bf16 v[90:93], v[172:175], v[208:211], v[90:93]
	v_mfma_f32_16x16x32_bf16 v[94:97], v[184:187], v[208:211], v[94:97]
	v_mfma_f32_16x16x32_bf16 v[74:77], v[172:175], v[216:219], v[74:77]
	v_mfma_f32_16x16x32_bf16 v[78:81], v[184:187], v[216:219], v[78:81]
	s_setprio 0
	s_barrier
	s_add_i32 s71, s64, s52
	v_lshl_add_u64 v[154:155], s[44:45], 0, v[136:137]
	s_mov_b32 m0, s71
	ds_read_b128 v[188:191], v158 offset:16384
	ds_read_b128 v[192:195], v158 offset:17408
	ds_read_b128 v[196:199], v158 offset:18432
	ds_read_b128 v[200:203], v158 offset:19456
	ds_read_b128 v[204:207], v158 offset:20480
	ds_read_b128 v[208:211], v158 offset:21504
	ds_read_b128 v[212:215], v158 offset:22528
	ds_read_b128 v[216:219], v158 offset:23552
	global_load_lds_dwordx4 v[154:155], off
	s_add_i32 m0, s71, 0x2000
	s_add_u32 s72, s44, 0x40000
	v_lshl_add_u64 v[176:177], s[44:45], 0, v[140:141]
	s_addc_u32 s73, s45, 0
	s_add_i32 s71, s65, s52
	global_load_lds_dwordx4 v[176:177], off
	v_lshl_add_u64 v[220:221], s[72:73], 0, v[136:137]
	s_mov_b32 m0, s71
	v_lshl_add_u64 v[222:223], s[46:47], 0, v[138:139]
	global_load_lds_dwordx4 v[220:221], off
	v_lshl_add_u64 v[220:221], s[72:73], 0, v[140:141]
	s_add_i32 m0, s71, 0x2000
	s_nop 0
	global_load_lds_dwordx4 v[220:221], off
	v_lshl_add_u64 v[220:221], s[46:47], 0, v[134:135]
	s_mov_b32 m0, s53
	s_nop 0
	global_load_lds_dwordx4 v[220:221], off
	s_mov_b32 m0, s54
	s_nop 0
	global_load_lds_dwordx4 v[222:223], off
	s_waitcnt vmcnt(8)
	s_waitcnt lgkmcnt(0)
	s_barrier
	s_setprio 1
	s_waitcnt lgkmcnt(0)
	v_mfma_f32_16x16x32_bf16 v[50:53], v[130:133], v[188:191], v[50:53]
	v_mfma_f32_16x16x32_bf16 v[54:57], v[160:163], v[188:191], v[54:57]
	v_mfma_f32_16x16x32_bf16 v[26:29], v[130:133], v[196:199], v[26:29]
	v_mfma_f32_16x16x32_bf16 v[30:33], v[160:163], v[196:199], v[30:33]
	v_mfma_f32_16x16x32_bf16 v[18:21], v[130:133], v[204:207], v[18:21]
	v_mfma_f32_16x16x32_bf16 v[22:25], v[160:163], v[204:207], v[22:25]
	v_mfma_f32_16x16x32_bf16 v[2:5], v[130:133], v[212:215], v[2:5]
	v_mfma_f32_16x16x32_bf16 v[6:9], v[160:163], v[212:215], v[6:9]
	v_mfma_f32_16x16x32_bf16 v[50:53], v[150:153], v[192:195], v[50:53]
	v_mfma_f32_16x16x32_bf16 v[54:57], v[164:167], v[192:195], v[54:57]
	v_mfma_f32_16x16x32_bf16 v[26:29], v[150:153], v[200:203], v[26:29]
	v_mfma_f32_16x16x32_bf16 v[30:33], v[164:167], v[200:203], v[30:33]
	v_mfma_f32_16x16x32_bf16 v[18:21], v[150:153], v[208:211], v[18:21]
	v_mfma_f32_16x16x32_bf16 v[22:25], v[164:167], v[208:211], v[22:25]
	v_mfma_f32_16x16x32_bf16 v[2:5], v[150:153], v[216:219], v[2:5]
	v_mfma_f32_16x16x32_bf16 v[6:9], v[164:167], v[216:219], v[6:9]
	v_mfma_f32_16x16x32_bf16 v[58:61], v[168:171], v[188:191], v[58:61]
	v_mfma_f32_16x16x32_bf16 v[62:65], v[180:183], v[188:191], v[62:65]
	v_mfma_f32_16x16x32_bf16 v[42:45], v[168:171], v[196:199], v[42:45]
	v_mfma_f32_16x16x32_bf16 v[46:49], v[180:183], v[196:199], v[46:49]
	v_mfma_f32_16x16x32_bf16 v[34:37], v[168:171], v[204:207], v[34:37]
	v_mfma_f32_16x16x32_bf16 v[38:41], v[180:183], v[204:207], v[38:41]
	v_mfma_f32_16x16x32_bf16 v[10:13], v[168:171], v[212:215], v[10:13]
	v_mfma_f32_16x16x32_bf16 v[14:17], v[180:183], v[212:215], v[14:17]
	v_mfma_f32_16x16x32_bf16 v[58:61], v[172:175], v[192:195], v[58:61]
	v_mfma_f32_16x16x32_bf16 v[62:65], v[184:187], v[192:195], v[62:65]
	v_mfma_f32_16x16x32_bf16 v[42:45], v[172:175], v[200:203], v[42:45]
	v_mfma_f32_16x16x32_bf16 v[46:49], v[184:187], v[200:203], v[46:49]
	v_mfma_f32_16x16x32_bf16 v[34:37], v[172:175], v[208:211], v[34:37]
	v_mfma_f32_16x16x32_bf16 v[38:41], v[184:187], v[208:211], v[38:41]
	v_mfma_f32_16x16x32_bf16 v[10:13], v[172:175], v[216:219], v[10:13]
	v_mfma_f32_16x16x32_bf16 v[14:17], v[184:187], v[216:219], v[14:17]
	s_setprio 0
	s_barrier
	s_add_i32 s71, 0, 0x18000
	s_add_i32 s72, 0, 0x1c000
	v_add_u32_e32 v164, s71, v156
	v_add_u32_e32 v179, s72, v156
	ds_read_b128 v[130:133], v164
	ds_read_b128 v[150:153], v164 offset:1024
	ds_read_b128 v[160:163], v164 offset:2048
	ds_read_b128 v[164:167], v164 offset:3072
	ds_read_b128 v[168:171], v179
	ds_read_b128 v[172:175], v179 offset:1024
	ds_read_b128 v[180:183], v179 offset:2048
	ds_read_b128 v[184:187], v179 offset:3072
	s_add_u32 s46, s46, 0x40000
	s_addc_u32 s47, s47, 0
	s_mov_b32 m0, s55
	v_lshl_add_u64 v[224:225], s[46:47], 0, v[134:135]
	ds_read_b128 v[188:191], v158 offset:32768
	ds_read_b128 v[192:195], v158 offset:33792
	ds_read_b128 v[196:199], v158 offset:34816
	ds_read_b128 v[200:203], v158 offset:35840
	ds_read_b128 v[204:207], v158 offset:36864
	ds_read_b128 v[208:211], v158 offset:37888
	ds_read_b128 v[212:215], v158 offset:38912
	ds_read_b128 v[216:219], v158 offset:39936
	global_load_lds_dwordx4 v[224:225], off
	v_lshl_add_u64 v[224:225], s[46:47], 0, v[138:139]
	s_mov_b32 m0, s56
	s_nop 0
	global_load_lds_dwordx4 v[224:225], off
	s_waitcnt vmcnt(8)
	s_waitcnt lgkmcnt(0)
	s_barrier
	s_setprio 1
	s_waitcnt lgkmcnt(0)
	v_mfma_f32_16x16x32_bf16 v[114:117], v[130:133], v[188:191], v[114:117]
	v_mfma_f32_16x16x32_bf16 v[118:121], v[160:163], v[188:191], v[118:121]
	v_mfma_f32_16x16x32_bf16 v[98:101], v[130:133], v[196:199], v[98:101]
	v_mfma_f32_16x16x32_bf16 v[102:105], v[160:163], v[196:199], v[102:105]
	v_mfma_f32_16x16x32_bf16 v[82:85], v[130:133], v[204:207], v[82:85]
	v_mfma_f32_16x16x32_bf16 v[86:89], v[160:163], v[204:207], v[86:89]
	v_mfma_f32_16x16x32_bf16 v[66:69], v[130:133], v[212:215], v[66:69]
	v_mfma_f32_16x16x32_bf16 v[70:73], v[160:163], v[212:215], v[70:73]
	v_mfma_f32_16x16x32_bf16 v[114:117], v[150:153], v[192:195], v[114:117]
	v_mfma_f32_16x16x32_bf16 v[118:121], v[164:167], v[192:195], v[118:121]
	v_mfma_f32_16x16x32_bf16 v[98:101], v[150:153], v[200:203], v[98:101]
	v_mfma_f32_16x16x32_bf16 v[102:105], v[164:167], v[200:203], v[102:105]
	v_mfma_f32_16x16x32_bf16 v[82:85], v[150:153], v[208:211], v[82:85]
	v_mfma_f32_16x16x32_bf16 v[86:89], v[164:167], v[208:211], v[86:89]
	v_mfma_f32_16x16x32_bf16 v[66:69], v[150:153], v[216:219], v[66:69]
	v_mfma_f32_16x16x32_bf16 v[70:73], v[164:167], v[216:219], v[70:73]
	v_mfma_f32_16x16x32_bf16 v[122:125], v[168:171], v[188:191], v[122:125]
	v_mfma_f32_16x16x32_bf16 v[126:129], v[180:183], v[188:191], v[126:129]
	v_mfma_f32_16x16x32_bf16 v[106:109], v[168:171], v[196:199], v[106:109]
	v_mfma_f32_16x16x32_bf16 v[110:113], v[180:183], v[196:199], v[110:113]
	v_mfma_f32_16x16x32_bf16 v[90:93], v[168:171], v[204:207], v[90:93]
	v_mfma_f32_16x16x32_bf16 v[94:97], v[180:183], v[204:207], v[94:97]
	v_mfma_f32_16x16x32_bf16 v[74:77], v[168:171], v[212:215], v[74:77]
	v_mfma_f32_16x16x32_bf16 v[78:81], v[180:183], v[212:215], v[78:81]
	v_mfma_f32_16x16x32_bf16 v[122:125], v[172:175], v[192:195], v[122:125]
	v_mfma_f32_16x16x32_bf16 v[126:129], v[184:187], v[192:195], v[126:129]
	v_mfma_f32_16x16x32_bf16 v[106:109], v[172:175], v[200:203], v[106:109]
	v_mfma_f32_16x16x32_bf16 v[110:113], v[184:187], v[200:203], v[110:113]
	v_mfma_f32_16x16x32_bf16 v[90:93], v[172:175], v[208:211], v[90:93]
	v_mfma_f32_16x16x32_bf16 v[94:97], v[184:187], v[208:211], v[94:97]
	v_mfma_f32_16x16x32_bf16 v[74:77], v[172:175], v[216:219], v[74:77]
	v_mfma_f32_16x16x32_bf16 v[78:81], v[184:187], v[216:219], v[78:81]
	s_setprio 0
	s_barrier
	s_add_i32 s46, s71, s52
	v_lshl_add_u64 v[154:155], v[154:155], 0, s[24:25]
	s_mov_b32 m0, s46
	ds_read_b128 v[188:191], v158 offset:49152
	ds_read_b128 v[192:195], v158 offset:50176
	ds_read_b128 v[196:199], v158 offset:51200
	ds_read_b128 v[200:203], v158 offset:52224
	ds_read_b128 v[204:207], v158 offset:53248
	ds_read_b128 v[208:211], v158 offset:54272
	ds_read_b128 v[212:215], v158 offset:55296
	ds_read_b128 v[216:219], v158 offset:56320
	global_load_lds_dwordx4 v[154:155], off
	s_add_i32 m0, s46, 0x2000
	s_add_u32 s44, s44, 0x40080
	v_lshl_add_u64 v[154:155], v[176:177], 0, s[24:25]
	s_addc_u32 s45, s45, 0
	s_add_i32 s46, s72, s52
	global_load_lds_dwordx4 v[154:155], off
	v_lshl_add_u64 v[154:155], s[44:45], 0, v[136:137]
	s_mov_b32 m0, s46
	s_nop 0
	global_load_lds_dwordx4 v[154:155], off
	v_lshl_add_u64 v[154:155], s[44:45], 0, v[140:141]
	s_add_i32 m0, s46, 0x2000
	s_nop 0
	global_load_lds_dwordx4 v[154:155], off
	v_lshl_add_u64 v[154:155], v[220:221], 0, s[24:25]
	s_mov_b32 m0, s59
	s_nop 0
	global_load_lds_dwordx4 v[154:155], off
	v_lshl_add_u64 v[154:155], v[222:223], 0, s[24:25]
	s_mov_b32 m0, s60
	s_nop 0
	global_load_lds_dwordx4 v[154:155], off
	s_waitcnt vmcnt(8)
	s_waitcnt lgkmcnt(0)
	s_barrier
	s_setprio 1
	s_waitcnt lgkmcnt(0)
	v_mfma_f32_16x16x32_bf16 v[50:53], v[130:133], v[188:191], v[50:53]
	v_mfma_f32_16x16x32_bf16 v[54:57], v[160:163], v[188:191], v[54:57]
	v_mfma_f32_16x16x32_bf16 v[26:29], v[130:133], v[196:199], v[26:29]
	v_mfma_f32_16x16x32_bf16 v[30:33], v[160:163], v[196:199], v[30:33]
	v_mfma_f32_16x16x32_bf16 v[18:21], v[130:133], v[204:207], v[18:21]
	v_mfma_f32_16x16x32_bf16 v[22:25], v[160:163], v[204:207], v[22:25]
	v_mfma_f32_16x16x32_bf16 v[2:5], v[130:133], v[212:215], v[2:5]
	v_mfma_f32_16x16x32_bf16 v[6:9], v[160:163], v[212:215], v[6:9]
	v_mfma_f32_16x16x32_bf16 v[50:53], v[150:153], v[192:195], v[50:53]
	v_mfma_f32_16x16x32_bf16 v[54:57], v[164:167], v[192:195], v[54:57]
	v_mfma_f32_16x16x32_bf16 v[26:29], v[150:153], v[200:203], v[26:29]
	v_mfma_f32_16x16x32_bf16 v[30:33], v[164:167], v[200:203], v[30:33]
	v_mfma_f32_16x16x32_bf16 v[18:21], v[150:153], v[208:211], v[18:21]
	v_mfma_f32_16x16x32_bf16 v[22:25], v[164:167], v[208:211], v[22:25]
	v_mfma_f32_16x16x32_bf16 v[2:5], v[150:153], v[216:219], v[2:5]
	v_mfma_f32_16x16x32_bf16 v[6:9], v[164:167], v[216:219], v[6:9]
	v_mfma_f32_16x16x32_bf16 v[58:61], v[168:171], v[188:191], v[58:61]
	v_mfma_f32_16x16x32_bf16 v[62:65], v[180:183], v[188:191], v[62:65]
	v_mfma_f32_16x16x32_bf16 v[42:45], v[168:171], v[196:199], v[42:45]
	v_mfma_f32_16x16x32_bf16 v[46:49], v[180:183], v[196:199], v[46:49]
	v_mfma_f32_16x16x32_bf16 v[34:37], v[168:171], v[204:207], v[34:37]
	v_mfma_f32_16x16x32_bf16 v[38:41], v[180:183], v[204:207], v[38:41]
	v_mfma_f32_16x16x32_bf16 v[10:13], v[168:171], v[212:215], v[10:13]
	v_mfma_f32_16x16x32_bf16 v[14:17], v[180:183], v[212:215], v[14:17]
	v_mfma_f32_16x16x32_bf16 v[58:61], v[172:175], v[192:195], v[58:61]
	v_mfma_f32_16x16x32_bf16 v[62:65], v[184:187], v[192:195], v[62:65]
	v_mfma_f32_16x16x32_bf16 v[42:45], v[172:175], v[200:203], v[42:45]
	v_mfma_f32_16x16x32_bf16 v[46:49], v[184:187], v[200:203], v[46:49]
	v_mfma_f32_16x16x32_bf16 v[34:37], v[172:175], v[208:211], v[34:37]
	v_mfma_f32_16x16x32_bf16 v[38:41], v[184:187], v[208:211], v[38:41]
	v_mfma_f32_16x16x32_bf16 v[10:13], v[172:175], v[216:219], v[10:13]
	v_mfma_f32_16x16x32_bf16 v[14:17], v[184:187], v[216:219], v[14:17]
	s_setprio 0
	s_barrier
	s_add_i32 s70, s70, 2
	s_add_u32 s68, s68, 0x100
	s_addc_u32 s69, s69, 0
	s_add_u32 s42, s42, 0x100
	s_addc_u32 s43, s43, 0
	s_cmp_gt_u32 s70, 13
	s_cbranch_scc0 .LBB0_1817
	s_and_b64 vcc, exec, s[26:27]
	s_cbranch_vccz .LBB0_1820
	s_barrier

.LBB0_2352:
	s_add_u32 s45, s38, s44
	s_addc_u32 s50, s39, 0
	s_add_u32 s48, s45, 0x100
	s_addc_u32 s49, s50, 0
	s_and_b64 s[46:47], s[42:43], exec
	s_cselect_b32 s47, s25, s49
	s_cselect_b32 s46, s31, s48
	s_add_u32 s44, s36, s44
	s_addc_u32 s48, s37, 0
	s_add_u32 s44, s44, 0x100
	s_addc_u32 s48, s48, 0
	s_and_b64 s[42:43], s[42:43], exec
	s_cselect_b32 s49, s23, s48
	s_cselect_b32 s48, s68, s44
	s_add_u32 s52, s45, 0x10080
	ds_read_b128 v[140:143], v147
	ds_read_b128 v[150:153], v147 offset:1024
	ds_read_b128 v[154:157], v147 offset:2048
	ds_read_b128 v[158:161], v147 offset:3072
	ds_read_b128 v[162:165], v148
	ds_read_b128 v[166:169], v148 offset:1024
	ds_read_b128 v[170:173], v148 offset:2048
	ds_read_b128 v[174:177], v148 offset:3072
	s_addc_u32 s53, s50, 0
	s_add_i32 s76, s66, s57
	s_add_i32 m0, s35, 0xc000
	s_add_i32 s79, s35, 0xe000
	s_add_i32 s73, s76, 0x2000
	s_add_u32 s50, s48, 0x10000
	s_addc_u32 s51, s49, 0
	s_add_i32 s75, s67, s57
	s_add_i32 s74, s75, 0x2000
	s_add_i32 s72, 0, 0x18000
	s_add_i32 s71, 0, 0x1c000
	s_add_u32 s44, s46, 0x10000
	s_addc_u32 s45, s47, 0
	s_add_i32 s70, s72, s57
	s_add_i32 s69, s70, 0x2000
	s_add_u32 s42, s48, 0x10080
	s_addc_u32 s43, s49, 0
	s_add_i32 s78, s71, s57
	s_add_i32 s77, s78, 0x2000
	v_lshl_add_u64 v[212:213], s[52:53], 0, v[128:129]
	ds_read_b128 v[180:183], v149
	ds_read_b128 v[184:187], v149 offset:1024
	ds_read_b128 v[188:191], v149 offset:2048
	ds_read_b128 v[192:195], v149 offset:3072
	ds_read_b128 v[196:199], v149 offset:4096
	ds_read_b128 v[200:203], v149 offset:5120
	ds_read_b128 v[204:207], v149 offset:6144
	ds_read_b128 v[208:211], v149 offset:7168
	global_load_lds_dwordx4 v[212:213], off
	v_lshl_add_u64 v[212:213], s[52:53], 0, v[132:133]
	s_mov_b32 m0, s79
	s_nop 0
	global_load_lds_dwordx4 v[212:213], off
	s_waitcnt vmcnt(8)
	s_waitcnt lgkmcnt(0)
	s_barrier
	s_setprio 1
	s_waitcnt lgkmcnt(0)
	v_mfma_f32_16x16x32_bf16 v[124:127], v[140:143], v[180:183], v[124:127]
	v_mfma_f32_16x16x32_bf16 v[120:123], v[154:157], v[180:183], v[120:123]
	v_mfma_f32_16x16x32_bf16 v[108:111], v[140:143], v[188:191], v[108:111]
	v_mfma_f32_16x16x32_bf16 v[104:107], v[154:157], v[188:191], v[104:107]
	v_mfma_f32_16x16x32_bf16 v[92:95], v[140:143], v[196:199], v[92:95]
	v_mfma_f32_16x16x32_bf16 v[88:91], v[154:157], v[196:199], v[88:91]
	v_mfma_f32_16x16x32_bf16 v[76:79], v[140:143], v[204:207], v[76:79]
	v_mfma_f32_16x16x32_bf16 v[72:75], v[154:157], v[204:207], v[72:75]
	v_mfma_f32_16x16x32_bf16 v[124:127], v[150:153], v[184:187], v[124:127]
	v_mfma_f32_16x16x32_bf16 v[120:123], v[158:161], v[184:187], v[120:123]
	v_mfma_f32_16x16x32_bf16 v[108:111], v[150:153], v[192:195], v[108:111]
	v_mfma_f32_16x16x32_bf16 v[104:107], v[158:161], v[192:195], v[104:107]
	v_mfma_f32_16x16x32_bf16 v[92:95], v[150:153], v[200:203], v[92:95]
	v_mfma_f32_16x16x32_bf16 v[88:91], v[158:161], v[200:203], v[88:91]
	v_mfma_f32_16x16x32_bf16 v[76:79], v[150:153], v[208:211], v[76:79]
	v_mfma_f32_16x16x32_bf16 v[72:75], v[158:161], v[208:211], v[72:75]
	v_mfma_f32_16x16x32_bf16 v[116:119], v[162:165], v[180:183], v[116:119]
	v_mfma_f32_16x16x32_bf16 v[112:115], v[170:173], v[180:183], v[112:115]
	v_mfma_f32_16x16x32_bf16 v[100:103], v[162:165], v[188:191], v[100:103]
	v_mfma_f32_16x16x32_bf16 v[96:99], v[170:173], v[188:191], v[96:99]
	v_mfma_f32_16x16x32_bf16 v[84:87], v[162:165], v[196:199], v[84:87]
	v_mfma_f32_16x16x32_bf16 v[80:83], v[170:173], v[196:199], v[80:83]
	v_mfma_f32_16x16x32_bf16 v[68:71], v[162:165], v[204:207], v[68:71]
	v_mfma_f32_16x16x32_bf16 v[64:67], v[170:173], v[204:207], v[64:67]
	v_mfma_f32_16x16x32_bf16 v[116:119], v[166:169], v[184:187], v[116:119]
	v_mfma_f32_16x16x32_bf16 v[112:115], v[174:177], v[184:187], v[112:115]
	v_mfma_f32_16x16x32_bf16 v[100:103], v[166:169], v[192:195], v[100:103]
	v_mfma_f32_16x16x32_bf16 v[96:99], v[174:177], v[192:195], v[96:99]
	v_mfma_f32_16x16x32_bf16 v[84:87], v[166:169], v[200:203], v[84:87]
	v_mfma_f32_16x16x32_bf16 v[80:83], v[174:177], v[200:203], v[80:83]
	v_mfma_f32_16x16x32_bf16 v[68:71], v[166:169], v[208:211], v[68:71]
	v_mfma_f32_16x16x32_bf16 v[64:67], v[174:177], v[208:211], v[64:67]
	s_setprio 0
	s_barrier
	s_mov_b32 m0, s76
	v_lshl_add_u64 v[212:213], s[48:49], 0, v[130:131]
	ds_read_b128 v[180:183], v149 offset:16384
	ds_read_b128 v[184:187], v149 offset:17408
	ds_read_b128 v[188:191], v149 offset:18432
	ds_read_b128 v[192:195], v149 offset:19456
	ds_read_b128 v[196:199], v149 offset:20480
	ds_read_b128 v[200:203], v149 offset:21504
	ds_read_b128 v[204:207], v149 offset:22528
	ds_read_b128 v[208:211], v149 offset:23552
	global_load_lds_dwordx4 v[212:213], off
	v_lshl_add_u64 v[214:215], s[48:49], 0, v[134:135]
	s_mov_b32 m0, s73
	v_lshl_add_u64 v[216:217], s[50:51], 0, v[130:131]
	global_load_lds_dwordx4 v[214:215], off
	s_mov_b32 m0, s75
	v_lshl_add_u64 v[218:219], s[46:47], 0, v[132:133]
	global_load_lds_dwordx4 v[216:217], off
	v_lshl_add_u64 v[216:217], s[50:51], 0, v[134:135]
	s_mov_b32 m0, s74
	s_nop 0
	global_load_lds_dwordx4 v[216:217], off
	v_lshl_add_u64 v[216:217], s[46:47], 0, v[128:129]
	s_mov_b32 m0, s35
	s_nop 0
	global_load_lds_dwordx4 v[216:217], off
	s_mov_b32 m0, s58
	s_nop 0
	global_load_lds_dwordx4 v[218:219], off
	s_waitcnt vmcnt(8)
	s_waitcnt lgkmcnt(0)
	s_barrier
	s_setprio 1
	s_waitcnt lgkmcnt(0)
	v_mfma_f32_16x16x32_bf16 v[60:63], v[140:143], v[180:183], v[60:63]
	v_mfma_f32_16x16x32_bf16 v[56:59], v[154:157], v[180:183], v[56:59]
	v_mfma_f32_16x16x32_bf16 v[44:47], v[140:143], v[188:191], v[44:47]
	v_mfma_f32_16x16x32_bf16 v[40:43], v[154:157], v[188:191], v[40:43]
	v_mfma_f32_16x16x32_bf16 v[28:31], v[140:143], v[196:199], v[28:31]
	v_mfma_f32_16x16x32_bf16 v[24:27], v[154:157], v[196:199], v[24:27]
	v_mfma_f32_16x16x32_bf16 v[12:15], v[140:143], v[204:207], v[12:15]
	v_mfma_f32_16x16x32_bf16 v[8:11], v[154:157], v[204:207], v[8:11]
	v_mfma_f32_16x16x32_bf16 v[60:63], v[150:153], v[184:187], v[60:63]
	v_mfma_f32_16x16x32_bf16 v[56:59], v[158:161], v[184:187], v[56:59]
	v_mfma_f32_16x16x32_bf16 v[44:47], v[150:153], v[192:195], v[44:47]
	v_mfma_f32_16x16x32_bf16 v[40:43], v[158:161], v[192:195], v[40:43]
	v_mfma_f32_16x16x32_bf16 v[28:31], v[150:153], v[200:203], v[28:31]
	v_mfma_f32_16x16x32_bf16 v[24:27], v[158:161], v[200:203], v[24:27]
	v_mfma_f32_16x16x32_bf16 v[12:15], v[150:153], v[208:211], v[12:15]
	v_mfma_f32_16x16x32_bf16 v[8:11], v[158:161], v[208:211], v[8:11]
	v_mfma_f32_16x16x32_bf16 v[52:55], v[162:165], v[180:183], v[52:55]
	v_mfma_f32_16x16x32_bf16 v[48:51], v[170:173], v[180:183], v[48:51]
	v_mfma_f32_16x16x32_bf16 v[36:39], v[162:165], v[188:191], v[36:39]
	v_mfma_f32_16x16x32_bf16 v[32:35], v[170:173], v[188:191], v[32:35]
	v_mfma_f32_16x16x32_bf16 v[20:23], v[162:165], v[196:199], v[20:23]
	v_mfma_f32_16x16x32_bf16 v[16:19], v[170:173], v[196:199], v[16:19]
	v_mfma_f32_16x16x32_bf16 v[4:7], v[162:165], v[204:207], v[4:7]
	v_mfma_f32_16x16x32_bf16 v[0:3], v[170:173], v[204:207], v[0:3]
	v_mfma_f32_16x16x32_bf16 v[52:55], v[166:169], v[184:187], v[52:55]
	v_mfma_f32_16x16x32_bf16 v[48:51], v[174:177], v[184:187], v[48:51]
	v_mfma_f32_16x16x32_bf16 v[36:39], v[166:169], v[192:195], v[36:39]
	v_mfma_f32_16x16x32_bf16 v[32:35], v[174:177], v[192:195], v[32:35]
	v_mfma_f32_16x16x32_bf16 v[20:23], v[166:169], v[200:203], v[20:23]
	v_mfma_f32_16x16x32_bf16 v[16:19], v[174:177], v[200:203], v[16:19]
	v_mfma_f32_16x16x32_bf16 v[4:7], v[166:169], v[208:211], v[4:7]
	v_mfma_f32_16x16x32_bf16 v[0:3], v[174:177], v[208:211], v[0:3]
	s_setprio 0
	s_barrier
	v_add_u32_e32 v158, s72, v145
	v_add_u32_e32 v174, s71, v145
	ds_read_b128 v[140:143], v158
	ds_read_b128 v[150:153], v158 offset:1024
	ds_read_b128 v[154:157], v158 offset:2048
	ds_read_b128 v[158:161], v158 offset:3072
	ds_read_b128 v[162:165], v174
	ds_read_b128 v[166:169], v174 offset:1024
	ds_read_b128 v[170:173], v174 offset:2048
	ds_read_b128 v[174:177], v174 offset:3072
	s_mov_b32 m0, s59
	v_lshl_add_u64 v[220:221], s[44:45], 0, v[128:129]
	ds_read_b128 v[180:183], v149 offset:32768
	ds_read_b128 v[184:187], v149 offset:33792
	ds_read_b128 v[188:191], v149 offset:34816
	ds_read_b128 v[192:195], v149 offset:35840
	ds_read_b128 v[196:199], v149 offset:36864
	ds_read_b128 v[200:203], v149 offset:37888
	ds_read_b128 v[204:207], v149 offset:38912
	ds_read_b128 v[208:211], v149 offset:39936
	global_load_lds_dwordx4 v[220:221], off
	v_lshl_add_u64 v[220:221], s[44:45], 0, v[132:133]
	s_mov_b32 m0, s60
	s_nop 0
	global_load_lds_dwordx4 v[220:221], off
	s_waitcnt vmcnt(8)
	s_waitcnt lgkmcnt(0)
	s_barrier
	s_setprio 1
	s_waitcnt lgkmcnt(0)
	v_mfma_f32_16x16x32_bf16 v[124:127], v[140:143], v[180:183], v[124:127]
	v_mfma_f32_16x16x32_bf16 v[120:123], v[154:157], v[180:183], v[120:123]
	v_mfma_f32_16x16x32_bf16 v[108:111], v[140:143], v[188:191], v[108:111]
	v_mfma_f32_16x16x32_bf16 v[104:107], v[154:157], v[188:191], v[104:107]
	v_mfma_f32_16x16x32_bf16 v[92:95], v[140:143], v[196:199], v[92:95]
	v_mfma_f32_16x16x32_bf16 v[88:91], v[154:157], v[196:199], v[88:91]
	v_mfma_f32_16x16x32_bf16 v[76:79], v[140:143], v[204:207], v[76:79]
	v_mfma_f32_16x16x32_bf16 v[72:75], v[154:157], v[204:207], v[72:75]
	v_mfma_f32_16x16x32_bf16 v[124:127], v[150:153], v[184:187], v[124:127]
	v_mfma_f32_16x16x32_bf16 v[120:123], v[158:161], v[184:187], v[120:123]
	v_mfma_f32_16x16x32_bf16 v[108:111], v[150:153], v[192:195], v[108:111]
	v_mfma_f32_16x16x32_bf16 v[104:107], v[158:161], v[192:195], v[104:107]
	v_mfma_f32_16x16x32_bf16 v[92:95], v[150:153], v[200:203], v[92:95]
	v_mfma_f32_16x16x32_bf16 v[88:91], v[158:161], v[200:203], v[88:91]
	v_mfma_f32_16x16x32_bf16 v[76:79], v[150:153], v[208:211], v[76:79]
	v_mfma_f32_16x16x32_bf16 v[72:75], v[158:161], v[208:211], v[72:75]
	v_mfma_f32_16x16x32_bf16 v[116:119], v[162:165], v[180:183], v[116:119]
	v_mfma_f32_16x16x32_bf16 v[112:115], v[170:173], v[180:183], v[112:115]
	v_mfma_f32_16x16x32_bf16 v[100:103], v[162:165], v[188:191], v[100:103]
	v_mfma_f32_16x16x32_bf16 v[96:99], v[170:173], v[188:191], v[96:99]
	v_mfma_f32_16x16x32_bf16 v[84:87], v[162:165], v[196:199], v[84:87]
	v_mfma_f32_16x16x32_bf16 v[80:83], v[170:173], v[196:199], v[80:83]
	v_mfma_f32_16x16x32_bf16 v[68:71], v[162:165], v[204:207], v[68:71]
	v_mfma_f32_16x16x32_bf16 v[64:67], v[170:173], v[204:207], v[64:67]
	v_mfma_f32_16x16x32_bf16 v[116:119], v[166:169], v[184:187], v[116:119]
	v_mfma_f32_16x16x32_bf16 v[112:115], v[174:177], v[184:187], v[112:115]
	v_mfma_f32_16x16x32_bf16 v[100:103], v[166:169], v[192:195], v[100:103]
	v_mfma_f32_16x16x32_bf16 v[96:99], v[174:177], v[192:195], v[96:99]
	v_mfma_f32_16x16x32_bf16 v[84:87], v[166:169], v[200:203], v[84:87]
	v_mfma_f32_16x16x32_bf16 v[80:83], v[174:177], v[200:203], v[80:83]
	v_mfma_f32_16x16x32_bf16 v[68:71], v[166:169], v[208:211], v[68:71]
	v_mfma_f32_16x16x32_bf16 v[64:67], v[174:177], v[208:211], v[64:67]
	s_setprio 0
	s_barrier
	s_mov_b32 m0, s70
	v_lshl_add_u64 v[212:213], v[212:213], 0, s[8:9]
	ds_read_b128 v[180:183], v149 offset:49152
	ds_read_b128 v[184:187], v149 offset:50176
	ds_read_b128 v[188:191], v149 offset:51200
	ds_read_b128 v[192:195], v149 offset:52224
	ds_read_b128 v[196:199], v149 offset:53248
	ds_read_b128 v[200:203], v149 offset:54272
	ds_read_b128 v[204:207], v149 offset:55296
	ds_read_b128 v[208:211], v149 offset:56320
	global_load_lds_dwordx4 v[212:213], off
	v_lshl_add_u64 v[212:213], v[214:215], 0, s[8:9]
	s_mov_b32 m0, s69
	s_nop 0
	global_load_lds_dwordx4 v[212:213], off
	v_lshl_add_u64 v[212:213], s[42:43], 0, v[130:131]
	s_mov_b32 m0, s78
	s_nop 0
	global_load_lds_dwordx4 v[212:213], off
	v_lshl_add_u64 v[212:213], s[42:43], 0, v[134:135]
	s_mov_b32 m0, s77
	s_nop 0
	global_load_lds_dwordx4 v[212:213], off
	v_lshl_add_u64 v[212:213], v[216:217], 0, s[8:9]
	s_mov_b32 m0, s62
	s_nop 0
	global_load_lds_dwordx4 v[212:213], off
	v_lshl_add_u64 v[212:213], v[218:219], 0, s[8:9]
	s_mov_b32 m0, s63
	s_nop 0
	global_load_lds_dwordx4 v[212:213], off
	s_waitcnt vmcnt(8)
	s_waitcnt lgkmcnt(0)
	s_barrier
	s_setprio 1
	s_waitcnt lgkmcnt(0)
	v_mfma_f32_16x16x32_bf16 v[60:63], v[140:143], v[180:183], v[60:63]
	v_mfma_f32_16x16x32_bf16 v[56:59], v[154:157], v[180:183], v[56:59]
	v_mfma_f32_16x16x32_bf16 v[44:47], v[140:143], v[188:191], v[44:47]
	v_mfma_f32_16x16x32_bf16 v[40:43], v[154:157], v[188:191], v[40:43]
	v_mfma_f32_16x16x32_bf16 v[28:31], v[140:143], v[196:199], v[28:31]
	v_mfma_f32_16x16x32_bf16 v[24:27], v[154:157], v[196:199], v[24:27]
	v_mfma_f32_16x16x32_bf16 v[12:15], v[140:143], v[204:207], v[12:15]
	v_mfma_f32_16x16x32_bf16 v[8:11], v[154:157], v[204:207], v[8:11]
	v_mfma_f32_16x16x32_bf16 v[60:63], v[150:153], v[184:187], v[60:63]
	v_mfma_f32_16x16x32_bf16 v[56:59], v[158:161], v[184:187], v[56:59]
	v_mfma_f32_16x16x32_bf16 v[44:47], v[150:153], v[192:195], v[44:47]
	v_mfma_f32_16x16x32_bf16 v[40:43], v[158:161], v[192:195], v[40:43]
	v_mfma_f32_16x16x32_bf16 v[28:31], v[150:153], v[200:203], v[28:31]
	v_mfma_f32_16x16x32_bf16 v[24:27], v[158:161], v[200:203], v[24:27]
	v_mfma_f32_16x16x32_bf16 v[12:15], v[150:153], v[208:211], v[12:15]
	v_mfma_f32_16x16x32_bf16 v[8:11], v[158:161], v[208:211], v[8:11]
	v_mfma_f32_16x16x32_bf16 v[52:55], v[162:165], v[180:183], v[52:55]
	v_mfma_f32_16x16x32_bf16 v[48:51], v[170:173], v[180:183], v[48:51]
	v_mfma_f32_16x16x32_bf16 v[36:39], v[162:165], v[188:191], v[36:39]
	v_mfma_f32_16x16x32_bf16 v[32:35], v[170:173], v[188:191], v[32:35]
	v_mfma_f32_16x16x32_bf16 v[20:23], v[162:165], v[196:199], v[20:23]
	v_mfma_f32_16x16x32_bf16 v[16:19], v[170:173], v[196:199], v[16:19]
	v_mfma_f32_16x16x32_bf16 v[4:7], v[162:165], v[204:207], v[4:7]
	v_mfma_f32_16x16x32_bf16 v[0:3], v[170:173], v[204:207], v[0:3]
	v_mfma_f32_16x16x32_bf16 v[52:55], v[166:169], v[184:187], v[52:55]
	v_mfma_f32_16x16x32_bf16 v[48:51], v[174:177], v[184:187], v[48:51]
	v_mfma_f32_16x16x32_bf16 v[36:39], v[166:169], v[192:195], v[36:39]
	v_mfma_f32_16x16x32_bf16 v[32:35], v[174:177], v[192:195], v[32:35]
	v_mfma_f32_16x16x32_bf16 v[20:23], v[166:169], v[200:203], v[20:23]
	v_mfma_f32_16x16x32_bf16 v[16:19], v[174:177], v[200:203], v[16:19]
	v_mfma_f32_16x16x32_bf16 v[4:7], v[166:169], v[208:211], v[4:7]
	v_mfma_f32_16x16x32_bf16 v[0:3], v[174:177], v[208:211], v[0:3]
	s_setprio 0
	s_barrier
	s_movk_i32 s44, 0x100
	s_andn2_b64 vcc, exec, s[40:41]
	s_mov_b64 s[42:43], -1
	s_mov_b64 s[40:41], 0
	s_cbranch_vccz .LBB0_2352
	s_and_b64 vcc, exec, s[10:11]
	s_cbranch_vccz .LBB0_2355
	s_barrier

.LBB0_2442:
	ds_read_b128 v[130:133], v178
	ds_read_b128 v[134:137], v178 offset:1024
	ds_read_b128 v[138:141], v178 offset:2048
	ds_read_b128 v[162:165], v178 offset:3072
	ds_read_b128 v[166:169], v179
	ds_read_b128 v[188:191], v179 offset:1024
	ds_read_b128 v[192:195], v179 offset:2048
	ds_read_b128 v[196:199], v179 offset:3072
	s_add_u32 s34, s30, 0xfffc0080
	s_addc_u32 s35, s31, -1
	s_cmp_eq_u32 s59, 12
	s_cselect_b32 s37, s23, s35
	s_cselect_b32 s36, s55, s34
	s_cselect_b32 s35, s21, s58
	s_cselect_b32 s34, s56, s57
	v_lshl_add_u64 v[142:143], s[30:31], 0, v[156:157]
	s_add_i32 m0, s29, 0xc000
	ds_read_b128 v[200:203], v180
	ds_read_b128 v[204:207], v180 offset:1024
	ds_read_b128 v[208:211], v180 offset:2048
	ds_read_b128 v[212:215], v180 offset:3072
	ds_read_b128 v[216:219], v180 offset:4096
	ds_read_b128 v[220:223], v180 offset:5120
	ds_read_b128 v[224:227], v180 offset:6144
	ds_read_b128 v[228:231], v180 offset:7168
	global_load_lds_dwordx4 v[142:143], off
	v_lshl_add_u64 v[142:143], s[30:31], 0, v[154:155]
	s_add_i32 m0, s29, 0xe000
	s_nop 0
	global_load_lds_dwordx4 v[142:143], off
	s_waitcnt vmcnt(8)
	s_waitcnt lgkmcnt(0)
	s_barrier
	s_setprio 1
	s_waitcnt lgkmcnt(0)
	v_mfma_f32_16x16x32_bf16 v[124:127], v[130:133], v[200:203], v[124:127]
	v_mfma_f32_16x16x32_bf16 v[120:123], v[138:141], v[200:203], v[120:123]
	v_mfma_f32_16x16x32_bf16 v[108:111], v[130:133], v[208:211], v[108:111]
	v_mfma_f32_16x16x32_bf16 v[104:107], v[138:141], v[208:211], v[104:107]
	v_mfma_f32_16x16x32_bf16 v[92:95], v[130:133], v[216:219], v[92:95]
	v_mfma_f32_16x16x32_bf16 v[88:91], v[138:141], v[216:219], v[88:91]
	v_mfma_f32_16x16x32_bf16 v[76:79], v[130:133], v[224:227], v[76:79]
	v_mfma_f32_16x16x32_bf16 v[72:75], v[138:141], v[224:227], v[72:75]
	v_mfma_f32_16x16x32_bf16 v[124:127], v[134:137], v[204:207], v[124:127]
	v_mfma_f32_16x16x32_bf16 v[120:123], v[162:165], v[204:207], v[120:123]
	v_mfma_f32_16x16x32_bf16 v[108:111], v[134:137], v[212:215], v[108:111]
	v_mfma_f32_16x16x32_bf16 v[104:107], v[162:165], v[212:215], v[104:107]
	v_mfma_f32_16x16x32_bf16 v[92:95], v[134:137], v[220:223], v[92:95]
	v_mfma_f32_16x16x32_bf16 v[88:91], v[162:165], v[220:223], v[88:91]
	v_mfma_f32_16x16x32_bf16 v[76:79], v[134:137], v[228:231], v[76:79]
	v_mfma_f32_16x16x32_bf16 v[72:75], v[162:165], v[228:231], v[72:75]
	v_mfma_f32_16x16x32_bf16 v[116:119], v[166:169], v[200:203], v[116:119]
	v_mfma_f32_16x16x32_bf16 v[112:115], v[192:195], v[200:203], v[112:115]
	v_mfma_f32_16x16x32_bf16 v[100:103], v[166:169], v[208:211], v[100:103]
	v_mfma_f32_16x16x32_bf16 v[96:99], v[192:195], v[208:211], v[96:99]
	v_mfma_f32_16x16x32_bf16 v[84:87], v[166:169], v[216:219], v[84:87]
	v_mfma_f32_16x16x32_bf16 v[80:83], v[192:195], v[216:219], v[80:83]
	v_mfma_f32_16x16x32_bf16 v[68:71], v[166:169], v[224:227], v[68:71]
	v_mfma_f32_16x16x32_bf16 v[64:67], v[192:195], v[224:227], v[64:67]
	v_mfma_f32_16x16x32_bf16 v[116:119], v[188:191], v[204:207], v[116:119]
	v_mfma_f32_16x16x32_bf16 v[112:115], v[196:199], v[204:207], v[112:115]
	v_mfma_f32_16x16x32_bf16 v[100:103], v[188:191], v[212:215], v[100:103]
	v_mfma_f32_16x16x32_bf16 v[96:99], v[196:199], v[212:215], v[96:99]
	v_mfma_f32_16x16x32_bf16 v[84:87], v[188:191], v[220:223], v[84:87]
	v_mfma_f32_16x16x32_bf16 v[80:83], v[196:199], v[220:223], v[80:83]
	v_mfma_f32_16x16x32_bf16 v[68:71], v[188:191], v[228:231], v[68:71]
	v_mfma_f32_16x16x32_bf16 v[64:67], v[196:199], v[228:231], v[64:67]
	s_setprio 0
	s_barrier
	s_add_i32 s60, s49, s40
	v_lshl_add_u64 v[142:143], s[34:35], 0, v[146:147]
	s_mov_b32 m0, s60
	ds_read_b128 v[200:203], v180 offset:16384
	ds_read_b128 v[204:207], v180 offset:17408
	ds_read_b128 v[208:211], v180 offset:18432
	ds_read_b128 v[212:215], v180 offset:19456
	ds_read_b128 v[216:219], v180 offset:20480
	ds_read_b128 v[220:223], v180 offset:21504
	ds_read_b128 v[224:227], v180 offset:22528
	ds_read_b128 v[228:231], v180 offset:23552
	global_load_lds_dwordx4 v[142:143], off
	s_add_i32 m0, s60, 0x2000
	s_add_u32 s60, s34, 0x40000
	v_lshl_add_u64 v[170:171], s[34:35], 0, v[150:151]
	s_addc_u32 s61, s35, 0
	s_add_i32 s62, s50, s40
	global_load_lds_dwordx4 v[170:171], off
	v_lshl_add_u64 v[232:233], s[60:61], 0, v[146:147]
	s_mov_b32 m0, s62
	v_lshl_add_u64 v[234:235], s[36:37], 0, v[148:149]
	global_load_lds_dwordx4 v[232:233], off
	v_lshl_add_u64 v[232:233], s[60:61], 0, v[150:151]
	s_add_i32 m0, s62, 0x2000
	s_nop 0
	global_load_lds_dwordx4 v[232:233], off
	v_lshl_add_u64 v[232:233], s[36:37], 0, v[144:145]
	s_mov_b32 m0, s29
	s_nop 0
	global_load_lds_dwordx4 v[232:233], off
	s_mov_b32 m0, s41
	s_nop 0
	global_load_lds_dwordx4 v[234:235], off
	s_waitcnt vmcnt(8)
	s_waitcnt lgkmcnt(0)
	s_barrier
	s_setprio 1
	s_waitcnt lgkmcnt(0)
	v_mfma_f32_16x16x32_bf16 v[60:63], v[130:133], v[200:203], v[60:63]
	v_mfma_f32_16x16x32_bf16 v[56:59], v[138:141], v[200:203], v[56:59]
	v_mfma_f32_16x16x32_bf16 v[44:47], v[130:133], v[208:211], v[44:47]
	v_mfma_f32_16x16x32_bf16 v[40:43], v[138:141], v[208:211], v[40:43]
	v_mfma_f32_16x16x32_bf16 v[28:31], v[130:133], v[216:219], v[28:31]
	v_mfma_f32_16x16x32_bf16 v[24:27], v[138:141], v[216:219], v[24:27]
	v_mfma_f32_16x16x32_bf16 v[12:15], v[130:133], v[224:227], v[12:15]
	v_mfma_f32_16x16x32_bf16 v[8:11], v[138:141], v[224:227], v[8:11]
	v_mfma_f32_16x16x32_bf16 v[60:63], v[134:137], v[204:207], v[60:63]
	v_mfma_f32_16x16x32_bf16 v[56:59], v[162:165], v[204:207], v[56:59]
	v_mfma_f32_16x16x32_bf16 v[44:47], v[134:137], v[212:215], v[44:47]
	v_mfma_f32_16x16x32_bf16 v[40:43], v[162:165], v[212:215], v[40:43]
	v_mfma_f32_16x16x32_bf16 v[28:31], v[134:137], v[220:223], v[28:31]
	v_mfma_f32_16x16x32_bf16 v[24:27], v[162:165], v[220:223], v[24:27]
	v_mfma_f32_16x16x32_bf16 v[12:15], v[134:137], v[228:231], v[12:15]
	v_mfma_f32_16x16x32_bf16 v[8:11], v[162:165], v[228:231], v[8:11]
	v_mfma_f32_16x16x32_bf16 v[52:55], v[166:169], v[200:203], v[52:55]
	v_mfma_f32_16x16x32_bf16 v[48:51], v[192:195], v[200:203], v[48:51]
	v_mfma_f32_16x16x32_bf16 v[36:39], v[166:169], v[208:211], v[36:39]
	v_mfma_f32_16x16x32_bf16 v[32:35], v[192:195], v[208:211], v[32:35]
	v_mfma_f32_16x16x32_bf16 v[20:23], v[166:169], v[216:219], v[20:23]
	v_mfma_f32_16x16x32_bf16 v[16:19], v[192:195], v[216:219], v[16:19]
	v_mfma_f32_16x16x32_bf16 v[4:7], v[166:169], v[224:227], v[4:7]
	v_mfma_f32_16x16x32_bf16 v[0:3], v[192:195], v[224:227], v[0:3]
	v_mfma_f32_16x16x32_bf16 v[52:55], v[188:191], v[204:207], v[52:55]
	v_mfma_f32_16x16x32_bf16 v[48:51], v[196:199], v[204:207], v[48:51]
	v_mfma_f32_16x16x32_bf16 v[36:39], v[188:191], v[212:215], v[36:39]
	v_mfma_f32_16x16x32_bf16 v[32:35], v[196:199], v[212:215], v[32:35]
	v_mfma_f32_16x16x32_bf16 v[20:23], v[188:191], v[220:223], v[20:23]
	v_mfma_f32_16x16x32_bf16 v[16:19], v[196:199], v[220:223], v[16:19]
	v_mfma_f32_16x16x32_bf16 v[4:7], v[188:191], v[228:231], v[4:7]
	v_mfma_f32_16x16x32_bf16 v[0:3], v[196:199], v[228:231], v[0:3]
	s_setprio 0
	s_barrier
	s_add_i32 s60, 0, 0x18000
	v_add_u32_e32 v129, s60, v176
	s_add_i32 s61, 0, 0x1c000
	ds_read_b128 v[130:133], v129
	ds_read_b128 v[134:137], v129 offset:1024
	ds_read_b128 v[138:141], v129 offset:2048
	ds_read_b128 v[162:165], v129 offset:3072
	v_add_u32_e32 v129, s61, v176
	ds_read_b128 v[166:169], v129
	ds_read_b128 v[188:191], v129 offset:1024
	ds_read_b128 v[192:195], v129 offset:2048
	ds_read_b128 v[196:199], v129 offset:3072
	s_add_u32 s36, s36, 0x40000
	s_addc_u32 s37, s37, 0
	s_mov_b32 m0, s42
	v_lshl_add_u64 v[236:237], s[36:37], 0, v[144:145]
	ds_read_b128 v[200:203], v180 offset:32768
	ds_read_b128 v[204:207], v180 offset:33792
	ds_read_b128 v[208:211], v180 offset:34816
	ds_read_b128 v[212:215], v180 offset:35840
	ds_read_b128 v[216:219], v180 offset:36864
	ds_read_b128 v[220:223], v180 offset:37888
	ds_read_b128 v[224:227], v180 offset:38912
	ds_read_b128 v[228:231], v180 offset:39936
	global_load_lds_dwordx4 v[236:237], off
	v_lshl_add_u64 v[236:237], s[36:37], 0, v[148:149]
	s_mov_b32 m0, s43
	s_nop 0
	global_load_lds_dwordx4 v[236:237], off
	s_waitcnt vmcnt(8)
	s_waitcnt lgkmcnt(0)
	s_barrier
	s_setprio 1
	s_waitcnt lgkmcnt(0)
	v_mfma_f32_16x16x32_bf16 v[124:127], v[130:133], v[200:203], v[124:127]
	v_mfma_f32_16x16x32_bf16 v[120:123], v[138:141], v[200:203], v[120:123]
	v_mfma_f32_16x16x32_bf16 v[108:111], v[130:133], v[208:211], v[108:111]
	v_mfma_f32_16x16x32_bf16 v[104:107], v[138:141], v[208:211], v[104:107]
	v_mfma_f32_16x16x32_bf16 v[92:95], v[130:133], v[216:219], v[92:95]
	v_mfma_f32_16x16x32_bf16 v[88:91], v[138:141], v[216:219], v[88:91]
	v_mfma_f32_16x16x32_bf16 v[76:79], v[130:133], v[224:227], v[76:79]
	v_mfma_f32_16x16x32_bf16 v[72:75], v[138:141], v[224:227], v[72:75]
	v_mfma_f32_16x16x32_bf16 v[124:127], v[134:137], v[204:207], v[124:127]
	v_mfma_f32_16x16x32_bf16 v[120:123], v[162:165], v[204:207], v[120:123]
	v_mfma_f32_16x16x32_bf16 v[108:111], v[134:137], v[212:215], v[108:111]
	v_mfma_f32_16x16x32_bf16 v[104:107], v[162:165], v[212:215], v[104:107]
	v_mfma_f32_16x16x32_bf16 v[92:95], v[134:137], v[220:223], v[92:95]
	v_mfma_f32_16x16x32_bf16 v[88:91], v[162:165], v[220:223], v[88:91]
	v_mfma_f32_16x16x32_bf16 v[76:79], v[134:137], v[228:231], v[76:79]
	v_mfma_f32_16x16x32_bf16 v[72:75], v[162:165], v[228:231], v[72:75]
	v_mfma_f32_16x16x32_bf16 v[116:119], v[166:169], v[200:203], v[116:119]
	v_mfma_f32_16x16x32_bf16 v[112:115], v[192:195], v[200:203], v[112:115]
	v_mfma_f32_16x16x32_bf16 v[100:103], v[166:169], v[208:211], v[100:103]
	v_mfma_f32_16x16x32_bf16 v[96:99], v[192:195], v[208:211], v[96:99]
	v_mfma_f32_16x16x32_bf16 v[84:87], v[166:169], v[216:219], v[84:87]
	v_mfma_f32_16x16x32_bf16 v[80:83], v[192:195], v[216:219], v[80:83]
	v_mfma_f32_16x16x32_bf16 v[68:71], v[166:169], v[224:227], v[68:71]
	v_mfma_f32_16x16x32_bf16 v[64:67], v[192:195], v[224:227], v[64:67]
	v_mfma_f32_16x16x32_bf16 v[116:119], v[188:191], v[204:207], v[116:119]
	v_mfma_f32_16x16x32_bf16 v[112:115], v[196:199], v[204:207], v[112:115]
	v_mfma_f32_16x16x32_bf16 v[100:103], v[188:191], v[212:215], v[100:103]
	v_mfma_f32_16x16x32_bf16 v[96:99], v[196:199], v[212:215], v[96:99]
	v_mfma_f32_16x16x32_bf16 v[84:87], v[188:191], v[220:223], v[84:87]
	v_mfma_f32_16x16x32_bf16 v[80:83], v[196:199], v[220:223], v[80:83]
	v_mfma_f32_16x16x32_bf16 v[68:71], v[188:191], v[228:231], v[68:71]
	v_mfma_f32_16x16x32_bf16 v[64:67], v[196:199], v[228:231], v[64:67]
	s_setprio 0
	s_barrier
	s_add_i32 s36, s60, s40
	v_lshl_add_u64 v[142:143], v[142:143], 0, s[8:9]
	s_mov_b32 m0, s36
	ds_read_b128 v[200:203], v180 offset:49152
	ds_read_b128 v[204:207], v180 offset:50176
	ds_read_b128 v[208:211], v180 offset:51200
	ds_read_b128 v[212:215], v180 offset:52224
	ds_read_b128 v[216:219], v180 offset:53248
	ds_read_b128 v[220:223], v180 offset:54272
	ds_read_b128 v[224:227], v180 offset:55296
	ds_read_b128 v[228:231], v180 offset:56320
	global_load_lds_dwordx4 v[142:143], off
	s_add_i32 m0, s36, 0x2000
	s_add_u32 s34, s34, 0x40080
	v_lshl_add_u64 v[142:143], v[170:171], 0, s[8:9]
	s_addc_u32 s35, s35, 0
	s_add_i32 s36, s61, s40
	global_load_lds_dwordx4 v[142:143], off
	v_lshl_add_u64 v[142:143], s[34:35], 0, v[146:147]
	s_mov_b32 m0, s36
	s_nop 0
	global_load_lds_dwordx4 v[142:143], off
	v_lshl_add_u64 v[142:143], s[34:35], 0, v[150:151]
	s_add_i32 m0, s36, 0x2000
	s_nop 0
	global_load_lds_dwordx4 v[142:143], off
	v_lshl_add_u64 v[142:143], v[232:233], 0, s[8:9]
	s_mov_b32 m0, s46
	s_nop 0
	global_load_lds_dwordx4 v[142:143], off
	v_lshl_add_u64 v[142:143], v[234:235], 0, s[8:9]
	s_mov_b32 m0, s47
	s_nop 0
	global_load_lds_dwordx4 v[142:143], off
	s_waitcnt vmcnt(8)
	s_waitcnt lgkmcnt(0)
	s_barrier
	s_setprio 1
	s_waitcnt lgkmcnt(0)
	v_mfma_f32_16x16x32_bf16 v[60:63], v[130:133], v[200:203], v[60:63]
	v_mfma_f32_16x16x32_bf16 v[56:59], v[138:141], v[200:203], v[56:59]
	v_mfma_f32_16x16x32_bf16 v[44:47], v[130:133], v[208:211], v[44:47]
	v_mfma_f32_16x16x32_bf16 v[40:43], v[138:141], v[208:211], v[40:43]
	v_mfma_f32_16x16x32_bf16 v[28:31], v[130:133], v[216:219], v[28:31]
	v_mfma_f32_16x16x32_bf16 v[24:27], v[138:141], v[216:219], v[24:27]
	v_mfma_f32_16x16x32_bf16 v[12:15], v[130:133], v[224:227], v[12:15]
	v_mfma_f32_16x16x32_bf16 v[8:11], v[138:141], v[224:227], v[8:11]
	v_mfma_f32_16x16x32_bf16 v[60:63], v[134:137], v[204:207], v[60:63]
	v_mfma_f32_16x16x32_bf16 v[56:59], v[162:165], v[204:207], v[56:59]
	v_mfma_f32_16x16x32_bf16 v[44:47], v[134:137], v[212:215], v[44:47]
	v_mfma_f32_16x16x32_bf16 v[40:43], v[162:165], v[212:215], v[40:43]
	v_mfma_f32_16x16x32_bf16 v[28:31], v[134:137], v[220:223], v[28:31]
	v_mfma_f32_16x16x32_bf16 v[24:27], v[162:165], v[220:223], v[24:27]
	v_mfma_f32_16x16x32_bf16 v[12:15], v[134:137], v[228:231], v[12:15]
	v_mfma_f32_16x16x32_bf16 v[8:11], v[162:165], v[228:231], v[8:11]
	v_mfma_f32_16x16x32_bf16 v[52:55], v[166:169], v[200:203], v[52:55]
	v_mfma_f32_16x16x32_bf16 v[48:51], v[192:195], v[200:203], v[48:51]
	v_mfma_f32_16x16x32_bf16 v[36:39], v[166:169], v[208:211], v[36:39]
	v_mfma_f32_16x16x32_bf16 v[32:35], v[192:195], v[208:211], v[32:35]
	v_mfma_f32_16x16x32_bf16 v[20:23], v[166:169], v[216:219], v[20:23]
	v_mfma_f32_16x16x32_bf16 v[16:19], v[192:195], v[216:219], v[16:19]
	v_mfma_f32_16x16x32_bf16 v[4:7], v[166:169], v[224:227], v[4:7]
	v_mfma_f32_16x16x32_bf16 v[0:3], v[192:195], v[224:227], v[0:3]
	v_mfma_f32_16x16x32_bf16 v[52:55], v[188:191], v[204:207], v[52:55]
	v_mfma_f32_16x16x32_bf16 v[48:51], v[196:199], v[204:207], v[48:51]
	v_mfma_f32_16x16x32_bf16 v[36:39], v[188:191], v[212:215], v[36:39]
	v_mfma_f32_16x16x32_bf16 v[32:35], v[196:199], v[212:215], v[32:35]
	v_mfma_f32_16x16x32_bf16 v[20:23], v[188:191], v[220:223], v[20:23]
	v_mfma_f32_16x16x32_bf16 v[16:19], v[196:199], v[220:223], v[16:19]
	v_mfma_f32_16x16x32_bf16 v[4:7], v[188:191], v[228:231], v[4:7]
	v_mfma_f32_16x16x32_bf16 v[0:3], v[196:199], v[228:231], v[0:3]
	s_setprio 0
	s_barrier
	s_add_i32 s59, s59, 2
	s_add_u32 s57, s57, 0x100
	s_addc_u32 s58, s58, 0
	s_add_u32 s30, s30, 0x100
	s_addc_u32 s31, s31, 0
	s_cmp_gt_u32 s59, 13
	s_cbranch_scc0 .LBB0_2442
	s_and_b64 vcc, exec, s[10:11]
	s_cbranch_vccz .LBB0_2445
	s_barrier
